# v36 + nt on read-once/write-once streams: FFN-down y1 epilogue loads, LN2 output stores, out-proj x epilogue loads
# baseline (speedup 1.0000x reference)
;     __device__ __forceinline__ size_t a_koff(int t) const { return (size_t)t * 128; }
;     __device__ __forceinline__ size_t a_koff(int t) const { return (size_t)t * 32768; }
; #define PG8_STAGE(bufoff, gbase, voff) do { _Pragma("unroll") for (int _i = 0; _i < 2; ++_i) \
;         __builtin_amdgcn_global_load_lds((const unsigned*)((const char*)(gbase) + (size_t)_i * p##voff + (voff)), (LAS unsigned*)(lds + (bufoff) + ldsw + _i * 8192), 16, 0, 0); } while (0)
; #define PG8_LDA(dst, b, h) do { _Pragma("unroll") for (int m = 0; m < 4; ++m) _Pragma("unroll") for (int k = 0; k < 2; ++k) dst[m][k] = *(const LAS bf16x8*)(lds + PG8_SA(b, h) + aoff + m * 2048 + k * 1024); } while (0)
; #define PG8_LDB(dst, b, h) do { _Pragma("unroll") for (int n = 0; n < 2; ++n) _Pragma("unroll") for (int k = 0; k < 2; ++k) dst[n][k] = *(const LAS bf16x8*)(lds + PG8_SB(b, h) + boff + n * 2048 + k * 1024); } while (0)
; #define PG8_WAIT_V(n) asm volatile("s_waitcnt vmcnt(" #n ")" ::: "memory")
; #define PG8_WAIT_L(n) asm volatile("s_waitcnt lgkmcnt(" #n ")" ::: "memory")
; #define PG8_BAR __builtin_amdgcn_s_barrier()
; #define PG8_SCHED __builtin_amdgcn_sched_barrier(0)
;     __device__ __forceinline__ size_t a_koff(int t) const { return ((size_t)(t >> 1) * 3072 + (size_t)(t & 1) * 64) * 2; }
;     ...
;             const char* a1 = cA + g.a_koff(t + 1);
;             const char* a2 = last ? nA : cA + g.a_koff(t + 2); const char* b2 = last ? nB : cB + (size_t)(t + 2) * kstep;
;             const char* a3 = last ? nA + g.a_koff(1) : cA + g.a_koff(t + 3); const char* b3 = b2 + kstep;
;             PG8_LDB(B0, 0, 0); PG8_LDB(B1, 0, 1); PG8_SCHED; PG8_LDA(At, 0, 0); PG8_STAGE(PG8_SA(1, 1), a1 + hstepA, voffA);
;             PG8_WAIT_V(8); PG8_WAIT_L(0); PG8_BAR; PG8_MMA(0, 0, At, B0); PG8_MMA(0, 1, At, B1); PG8_BAR; PG8_SCHED;
;             PG8_LDA(At, 0, 1); PG8_STAGE(PG8_SB(0, 0), b2, voffB); PG8_STAGE(PG8_SB(0, 1), b2 + hstepB, voffB); PG8_STAGE(PG8_SA(0, 0), a2, voffA);
;             PG8_WAIT_V(8); PG8_WAIT_L(0); PG8_BAR; PG8_MMA(1, 0, At, B0); PG8_MMA(1, 1, At, B1); PG8_BAR; PG8_SCHED;
;             PG8_LDB(B0, 1, 0); PG8_LDB(B1, 1, 1); PG8_SCHED; PG8_LDA(At, 1, 0); PG8_STAGE(PG8_SA(0, 1), a2 + hstepA, voffA);
;             PG8_WAIT_V(8); PG8_WAIT_L(0); PG8_BAR; PG8_MMA(0, 0, At, B0); PG8_MMA(0, 1, At, B1); PG8_BAR; PG8_SCHED;
.LBB0_1041:
	ds_read_b128 v[26:29], v187
	ds_read_b128 v[30:33], v187 offset:1024
	ds_read_b128 v[18:21], v187 offset:2048
	ds_read_b128 v[22:25], v187 offset:3072
	ds_read_b128 v[10:13], v212
	ds_read_b128 v[14:17], v212 offset:1024
	ds_read_b128 v[2:5], v212 offset:2048
	ds_read_b128 v[6:9], v212 offset:3072
	s_add_u32 s48, s42, s46
	s_addc_u32 s49, s43, s47
	s_add_u32 s50, s48, 0x10000
	s_addc_u32 s51, s49, 0
	s_add_u32 s48, s48, 0x18000
	s_addc_u32 s49, s49, 0
	s_cmp_eq_u32 s46, 0xf0000
	s_cselect_b32 s49, s72, s49
	s_cselect_b32 s48, s71, s48
	s_cselect_b32 s53, s29, s74
	s_cselect_b32 s52, s45, s73
	s_cselect_b32 s51, s35, s51
	s_cselect_b32 s50, s41, s50
	v_lshl_add_u64 v[180:181], v[162:163], 0, s[46:47]
	s_mov_b64 s[76:77], 0xc000
	v_lshl_add_u64 v[182:183], v[180:181], 0, s[76:77]
	s_add_i32 m0, s57, 0xc000
	s_mov_b64 s[76:77], 0xe000
	ds_read_b128 v[164:167], v213
	ds_read_b128 v[168:171], v213 offset:1024
	ds_read_b128 v[172:175], v213 offset:2048
	ds_read_b128 v[176:179], v213 offset:3072
	ds_read_b128 v[200:203], v213 offset:4096
	ds_read_b128 v[204:207], v213 offset:5120
	ds_read_b128 v[218:221], v213 offset:6144
	ds_read_b128 v[222:225], v213 offset:7168
	global_load_lds_dwordx4 v[182:183], off
	v_lshl_add_u64 v[180:181], v[180:181], 0, s[76:77]
	s_add_i32 m0, s57, 0xe000
	s_nop 0
	global_load_lds_dwordx4 v[180:181], off
	s_waitcnt vmcnt(8)
	s_waitcnt lgkmcnt(0)
	s_barrier
	s_setprio 1
	s_waitcnt lgkmcnt(0)
	v_mfma_scale_f32_16x16x128_f8f6f4 v[158:161], v[26:33], v[164:171], v[158:161], v214, v215 op_sel_hi:[0,0,0]
	v_mfma_scale_f32_16x16x128_f8f6f4 v[154:157], v[18:25], v[164:171], v[154:157], v214, v215 op_sel_hi:[0,0,0]
	v_mfma_scale_f32_16x16x128_f8f6f4 v[146:149], v[26:33], v[172:179], v[146:149], v214, v215 op_sel_hi:[0,0,0]
	v_mfma_scale_f32_16x16x128_f8f6f4 v[138:141], v[18:25], v[172:179], v[138:141], v214, v215 op_sel_hi:[0,0,0]
	v_mfma_scale_f32_16x16x128_f8f6f4 v[126:129], v[26:33], v[200:207], v[126:129], v214, v215 op_sel_hi:[0,0,0]
	v_mfma_scale_f32_16x16x128_f8f6f4 v[122:125], v[18:25], v[200:207], v[122:125], v214, v215 op_sel_hi:[0,0,0]
	v_mfma_scale_f32_16x16x128_f8f6f4 v[114:117], v[26:33], v[218:225], v[114:117], v214, v215 op_sel_hi:[0,0,0]
	v_mfma_scale_f32_16x16x128_f8f6f4 v[106:109], v[18:25], v[218:225], v[106:109], v214, v215 op_sel_hi:[0,0,0]
	s_setprio 0
	s_setprio 1
	v_mfma_scale_f32_16x16x128_f8f6f4 v[150:153], v[10:17], v[164:171], v[150:153], v214, v215 op_sel_hi:[0,0,0]
	v_mfma_scale_f32_16x16x128_f8f6f4 v[142:145], v[2:9], v[164:171], v[142:145], v214, v215 op_sel_hi:[0,0,0]
	v_mfma_scale_f32_16x16x128_f8f6f4 v[134:137], v[10:17], v[172:179], v[134:137], v214, v215 op_sel_hi:[0,0,0]
	v_mfma_scale_f32_16x16x128_f8f6f4 v[130:133], v[2:9], v[172:179], v[130:133], v214, v215 op_sel_hi:[0,0,0]
	v_mfma_scale_f32_16x16x128_f8f6f4 v[118:121], v[10:17], v[200:207], v[118:121], v214, v215 op_sel_hi:[0,0,0]
	v_mfma_scale_f32_16x16x128_f8f6f4 v[110:113], v[2:9], v[200:207], v[110:113], v214, v215 op_sel_hi:[0,0,0]
	v_mfma_scale_f32_16x16x128_f8f6f4 v[102:105], v[10:17], v[218:225], v[102:105], v214, v215 op_sel_hi:[0,0,0]
	v_mfma_scale_f32_16x16x128_f8f6f4 v[98:101], v[2:9], v[218:225], v[98:101], v214, v215 op_sel_hi:[0,0,0]
	s_setprio 0
	s_barrier
	v_lshl_add_u64 v[164:165], s[52:53], 0, v[190:191]
	s_add_i32 s52, s69, s55
	s_mov_b32 m0, s52
	ds_read_b128 v[166:169], v213 offset:16384
	ds_read_b128 v[170:173], v213 offset:17408
	ds_read_b128 v[174:177], v213 offset:18432
	ds_read_b128 v[178:181], v213 offset:19456
	ds_read_b128 v[200:203], v213 offset:20480
	ds_read_b128 v[204:207], v213 offset:21504
	ds_read_b128 v[218:221], v213 offset:22528
	ds_read_b128 v[222:225], v213 offset:23552
	global_load_lds_dwordx4 v[164:165], off
	v_lshl_add_u64 v[182:183], v[164:165], 0, s[4:5]
	s_add_i32 m0, s52, 0x2000
	s_add_i32 s52, s70, s55
	global_load_lds_dwordx4 v[182:183], off
	v_lshl_add_u64 v[182:183], v[164:165], 0, s[6:7]
	s_mov_b32 m0, s52
	s_nop 0
	global_load_lds_dwordx4 v[182:183], off
	v_lshl_add_u64 v[182:183], v[164:165], 0, s[8:9]
	s_add_i32 m0, s52, 0x2000
	s_nop 0
	global_load_lds_dwordx4 v[182:183], off
	v_lshl_add_u64 v[182:183], s[50:51], 0, v[188:189]
	s_mov_b32 m0, s57
	v_lshl_add_u64 v[184:185], v[182:183], 0, s[10:11]
	global_load_lds_dwordx4 v[182:183], off
	s_mov_b32 m0, s58
	s_nop 0
	global_load_lds_dwordx4 v[184:185], off
	s_waitcnt vmcnt(8)
	s_waitcnt lgkmcnt(0)
	s_barrier
	s_setprio 1
	s_waitcnt lgkmcnt(0)
	v_mfma_scale_f32_16x16x128_f8f6f4 v[94:97], v[26:33], v[166:173], v[94:97], v214, v215 op_sel_hi:[0,0,0]
	v_mfma_scale_f32_16x16x128_f8f6f4 v[90:93], v[18:25], v[166:173], v[90:93], v214, v215 op_sel_hi:[0,0,0]
	v_mfma_scale_f32_16x16x128_f8f6f4 v[82:85], v[26:33], v[174:181], v[82:85], v214, v215 op_sel_hi:[0,0,0]
	v_mfma_scale_f32_16x16x128_f8f6f4 v[74:77], v[18:25], v[174:181], v[74:77], v214, v215 op_sel_hi:[0,0,0]
	v_mfma_scale_f32_16x16x128_f8f6f4 v[66:69], v[26:33], v[200:207], v[66:69], v214, v215 op_sel_hi:[0,0,0]
	v_mfma_scale_f32_16x16x128_f8f6f4 v[58:61], v[18:25], v[200:207], v[58:61], v214, v215 op_sel_hi:[0,0,0]
	v_mfma_scale_f32_16x16x128_f8f6f4 v[50:53], v[26:33], v[218:225], v[50:53], v214, v215 op_sel_hi:[0,0,0]
	v_mfma_scale_f32_16x16x128_f8f6f4 v[42:45], v[18:25], v[218:225], v[42:45], v214, v215 op_sel_hi:[0,0,0]
	s_setprio 0
	s_setprio 1
	v_mfma_scale_f32_16x16x128_f8f6f4 v[86:89], v[10:17], v[166:173], v[86:89], v214, v215 op_sel_hi:[0,0,0]
	v_mfma_scale_f32_16x16x128_f8f6f4 v[78:81], v[2:9], v[166:173], v[78:81], v214, v215 op_sel_hi:[0,0,0]
	v_mfma_scale_f32_16x16x128_f8f6f4 v[70:73], v[10:17], v[174:181], v[70:73], v214, v215 op_sel_hi:[0,0,0]
	v_mfma_scale_f32_16x16x128_f8f6f4 v[62:65], v[2:9], v[174:181], v[62:65], v214, v215 op_sel_hi:[0,0,0]
	v_mfma_scale_f32_16x16x128_f8f6f4 v[54:57], v[10:17], v[200:207], v[54:57], v214, v215 op_sel_hi:[0,0,0]
	v_mfma_scale_f32_16x16x128_f8f6f4 v[46:49], v[2:9], v[200:207], v[46:49], v214, v215 op_sel_hi:[0,0,0]
	v_mfma_scale_f32_16x16x128_f8f6f4 v[38:41], v[10:17], v[218:225], v[38:41], v214, v215 op_sel_hi:[0,0,0]
	v_mfma_scale_f32_16x16x128_f8f6f4 v[34:37], v[2:9], v[218:225], v[34:37], v214, v215 op_sel_hi:[0,0,0]
	s_setprio 0
	s_barrier
; #define PG8_STAGE(bufoff, gbase, voff) do { _Pragma("unroll") for (int _i = 0; _i < 2; ++_i) \
;         __builtin_amdgcn_global_load_lds((const unsigned*)((const char*)(gbase) + (size_t)_i * p##voff + (voff)), (LAS unsigned*)(lds + (bufoff) + ldsw + _i * 8192), 16, 0, 0); } while (0)
; #define PG8_LDA(dst, b, h) do { _Pragma("unroll") for (int m = 0; m < 4; ++m) _Pragma("unroll") for (int k = 0; k < 2; ++k) dst[m][k] = *(const LAS bf16x8*)(lds + PG8_SA(b, h) + aoff + m * 2048 + k * 1024); } while (0)
; #define PG8_LDB(dst, b, h) do { _Pragma("unroll") for (int n = 0; n < 2; ++n) _Pragma("unroll") for (int k = 0; k < 2; ++k) dst[n][k] = *(const LAS bf16x8*)(lds + PG8_SB(b, h) + boff + n * 2048 + k * 1024); } while (0)
; #define PG8_WAIT_V(n) asm volatile("s_waitcnt vmcnt(" #n ")" ::: "memory")
; #define PG8_WAIT_L(n) asm volatile("s_waitcnt lgkmcnt(" #n ")" ::: "memory")
; #define PG8_BAR __builtin_amdgcn_s_barrier()
; #define PG8_SCHED __builtin_amdgcn_sched_barrier(0)
;     ...
;             PG8_WAIT_V(8); PG8_WAIT_L(0); PG8_BAR; PG8_MMA(1, 0, At, B0); PG8_MMA(1, 1, At, B1); PG8_BAR; PG8_SCHED;
;             PG8_LDB(B0, 1, 0); PG8_LDB(B1, 1, 1); PG8_SCHED; PG8_LDA(At, 1, 0); PG8_STAGE(PG8_SA(0, 1), a2 + hstepA, voffA);
;             PG8_WAIT_V(8); PG8_WAIT_L(0); PG8_BAR; PG8_MMA(0, 0, At, B0); PG8_MMA(0, 1, At, B1); PG8_BAR; PG8_SCHED;
;             PG8_LDA(At, 1, 1); PG8_STAGE(PG8_SB(1, 0), b3, voffB); PG8_STAGE(PG8_SB(1, 1), b3 + hstepB, voffB); PG8_STAGE(PG8_SA(1, 0), a3, voffA);
;             PG8_WAIT_V(8); PG8_WAIT_L(0); PG8_BAR; PG8_MMA(1, 0, At, B0); PG8_MMA(1, 1, At, B1); PG8_BAR; PG8_SCHED;
	s_add_i32 s50, 0, 0x18000
	s_add_i32 s51, 0, 0x1c000
	v_add_u32_e32 v14, s50, v1
	v_add_u32_e32 v30, s51, v1
	ds_read_b128 v[2:5], v14
	ds_read_b128 v[6:9], v14 offset:1024
	ds_read_b128 v[10:13], v14 offset:2048
	ds_read_b128 v[14:17], v14 offset:3072
	ds_read_b128 v[18:21], v30
	ds_read_b128 v[22:25], v30 offset:1024
	ds_read_b128 v[26:29], v30 offset:2048
	ds_read_b128 v[30:33], v30 offset:3072
	s_mov_b32 m0, s59
	v_lshl_add_u64 v[184:185], v[182:183], 0, s[12:13]
	ds_read_b128 v[166:169], v213 offset:32768
	ds_read_b128 v[170:173], v213 offset:33792
	ds_read_b128 v[174:177], v213 offset:34816
	ds_read_b128 v[178:181], v213 offset:35840
	ds_read_b128 v[200:203], v213 offset:36864
	ds_read_b128 v[204:207], v213 offset:37888
	ds_read_b128 v[218:221], v213 offset:38912
	ds_read_b128 v[222:225], v213 offset:39936
	global_load_lds_dwordx4 v[184:185], off
	v_lshl_add_u64 v[182:183], v[182:183], 0, s[14:15]
	s_mov_b32 m0, s60
	s_nop 0
	global_load_lds_dwordx4 v[182:183], off
	s_waitcnt vmcnt(8)
	s_waitcnt lgkmcnt(0)
	s_barrier
	s_setprio 1
	s_waitcnt lgkmcnt(0)
	v_mfma_scale_f32_16x16x128_f8f6f4 v[158:161], v[2:9], v[166:173], v[158:161], v214, v215 op_sel_hi:[0,0,0]
	v_mfma_scale_f32_16x16x128_f8f6f4 v[154:157], v[10:17], v[166:173], v[154:157], v214, v215 op_sel_hi:[0,0,0]
	v_mfma_scale_f32_16x16x128_f8f6f4 v[146:149], v[2:9], v[174:181], v[146:149], v214, v215 op_sel_hi:[0,0,0]
	v_mfma_scale_f32_16x16x128_f8f6f4 v[138:141], v[10:17], v[174:181], v[138:141], v214, v215 op_sel_hi:[0,0,0]
	v_mfma_scale_f32_16x16x128_f8f6f4 v[126:129], v[2:9], v[200:207], v[126:129], v214, v215 op_sel_hi:[0,0,0]
	v_mfma_scale_f32_16x16x128_f8f6f4 v[122:125], v[10:17], v[200:207], v[122:125], v214, v215 op_sel_hi:[0,0,0]
	v_mfma_scale_f32_16x16x128_f8f6f4 v[114:117], v[2:9], v[218:225], v[114:117], v214, v215 op_sel_hi:[0,0,0]
	v_mfma_scale_f32_16x16x128_f8f6f4 v[106:109], v[10:17], v[218:225], v[106:109], v214, v215 op_sel_hi:[0,0,0]
	s_setprio 0
	s_setprio 1
	v_mfma_scale_f32_16x16x128_f8f6f4 v[150:153], v[18:25], v[166:173], v[150:153], v214, v215 op_sel_hi:[0,0,0]
	v_mfma_scale_f32_16x16x128_f8f6f4 v[142:145], v[26:33], v[166:173], v[142:145], v214, v215 op_sel_hi:[0,0,0]
	v_mfma_scale_f32_16x16x128_f8f6f4 v[134:137], v[18:25], v[174:181], v[134:137], v214, v215 op_sel_hi:[0,0,0]
	v_mfma_scale_f32_16x16x128_f8f6f4 v[130:133], v[26:33], v[174:181], v[130:133], v214, v215 op_sel_hi:[0,0,0]
	v_mfma_scale_f32_16x16x128_f8f6f4 v[118:121], v[18:25], v[200:207], v[118:121], v214, v215 op_sel_hi:[0,0,0]
	v_mfma_scale_f32_16x16x128_f8f6f4 v[110:113], v[26:33], v[200:207], v[110:113], v214, v215 op_sel_hi:[0,0,0]
	v_mfma_scale_f32_16x16x128_f8f6f4 v[102:105], v[18:25], v[218:225], v[102:105], v214, v215 op_sel_hi:[0,0,0]
	v_mfma_scale_f32_16x16x128_f8f6f4 v[98:101], v[26:33], v[218:225], v[98:101], v214, v215 op_sel_hi:[0,0,0]
	s_setprio 0
	s_barrier
	s_add_i32 s50, s50, s55
	v_lshl_add_u64 v[182:183], v[164:165], 0, s[16:17]
	s_mov_b32 m0, s50
	ds_read_b128 v[166:169], v213 offset:49152
	ds_read_b128 v[170:173], v213 offset:50176
	ds_read_b128 v[174:177], v213 offset:51200
	ds_read_b128 v[178:181], v213 offset:52224
	ds_read_b128 v[200:203], v213 offset:53248
	ds_read_b128 v[204:207], v213 offset:54272
	ds_read_b128 v[218:221], v213 offset:55296
	ds_read_b128 v[222:225], v213 offset:56320
	global_load_lds_dwordx4 v[182:183], off
	v_lshl_add_u64 v[182:183], v[164:165], 0, s[18:19]
	s_add_i32 m0, s50, 0x2000
	s_add_i32 s50, s51, s55
	global_load_lds_dwordx4 v[182:183], off
	v_lshl_add_u64 v[182:183], v[164:165], 0, s[20:21]
	s_mov_b32 m0, s50
	v_lshl_add_u64 v[164:165], v[164:165], 0, s[22:23]
	global_load_lds_dwordx4 v[182:183], off
	s_add_i32 m0, s50, 0x2000
	s_nop 0
	global_load_lds_dwordx4 v[164:165], off
	v_lshl_add_u64 v[164:165], s[48:49], 0, v[188:189]
	s_mov_b32 m0, s64
	s_nop 0
	global_load_lds_dwordx4 v[164:165], off
	v_lshl_add_u64 v[164:165], v[164:165], 0, s[10:11]
	s_mov_b32 m0, s65
	s_nop 0
	global_load_lds_dwordx4 v[164:165], off
	s_waitcnt vmcnt(8)
	s_waitcnt lgkmcnt(0)
	s_barrier
	s_setprio 1
	s_waitcnt lgkmcnt(0)
	v_mfma_scale_f32_16x16x128_f8f6f4 v[94:97], v[2:9], v[166:173], v[94:97], v214, v215 op_sel_hi:[0,0,0]
	v_mfma_scale_f32_16x16x128_f8f6f4 v[90:93], v[10:17], v[166:173], v[90:93], v214, v215 op_sel_hi:[0,0,0]
	v_mfma_scale_f32_16x16x128_f8f6f4 v[82:85], v[2:9], v[174:181], v[82:85], v214, v215 op_sel_hi:[0,0,0]
	v_mfma_scale_f32_16x16x128_f8f6f4 v[74:77], v[10:17], v[174:181], v[74:77], v214, v215 op_sel_hi:[0,0,0]
	v_mfma_scale_f32_16x16x128_f8f6f4 v[66:69], v[2:9], v[200:207], v[66:69], v214, v215 op_sel_hi:[0,0,0]
	v_mfma_scale_f32_16x16x128_f8f6f4 v[58:61], v[10:17], v[200:207], v[58:61], v214, v215 op_sel_hi:[0,0,0]
	v_mfma_scale_f32_16x16x128_f8f6f4 v[50:53], v[2:9], v[218:225], v[50:53], v214, v215 op_sel_hi:[0,0,0]
	v_mfma_scale_f32_16x16x128_f8f6f4 v[42:45], v[10:17], v[218:225], v[42:45], v214, v215 op_sel_hi:[0,0,0]
	s_setprio 0
	s_setprio 1
	v_mfma_scale_f32_16x16x128_f8f6f4 v[86:89], v[18:25], v[166:173], v[86:89], v214, v215 op_sel_hi:[0,0,0]
	v_mfma_scale_f32_16x16x128_f8f6f4 v[78:81], v[26:33], v[166:173], v[78:81], v214, v215 op_sel_hi:[0,0,0]
	v_mfma_scale_f32_16x16x128_f8f6f4 v[70:73], v[18:25], v[174:181], v[70:73], v214, v215 op_sel_hi:[0,0,0]
	v_mfma_scale_f32_16x16x128_f8f6f4 v[62:65], v[26:33], v[174:181], v[62:65], v214, v215 op_sel_hi:[0,0,0]
	v_mfma_scale_f32_16x16x128_f8f6f4 v[54:57], v[18:25], v[200:207], v[54:57], v214, v215 op_sel_hi:[0,0,0]
	v_mfma_scale_f32_16x16x128_f8f6f4 v[46:49], v[26:33], v[200:207], v[46:49], v214, v215 op_sel_hi:[0,0,0]
	v_mfma_scale_f32_16x16x128_f8f6f4 v[38:41], v[18:25], v[218:225], v[38:41], v214, v215 op_sel_hi:[0,0,0]
	v_mfma_scale_f32_16x16x128_f8f6f4 v[34:37], v[26:33], v[218:225], v[34:37], v214, v215 op_sel_hi:[0,0,0]
	s_setprio 0
	s_barrier
; #define Y1_LOAD(dst, am) do { _Pragma("unroll") for (int mm = 0; mm < 2; ++mm) { const int m_ = ((am) & 1) * 2 + mm; const size_t off_ = (size_t)(rowb + ((am) >> 1) * 128 + m_ * 16) * D + col0; \
;             _Pragma("unroll") for (int bj = 0; bj < 2; ++bj) _Pragma("unroll") for (int n = 0; n < 2; ++n) dst[mm][bj][n] = *(const f32x4*)(x + off_ + bj * 128 + n * 4); } } while (0)
;     __device__ __forceinline__ void operator()(const Acc& acc, const Unit& u, int wr, int wc, int fr, int fq) const {
;     ...
;         const int rowb = u.pm * 256 + wr * 64 + fr, col0 = u.pn * 256 + wc * 32 + 8 * fq; const int b = (u.pm * 256) / S;
;         const size_t yb = (((size_t)u.pm * 16 + u.pn) * 256 + (wr * 64 + fr)) * 256 + wc * 32 + 8 * fq;
;         f32x4 gv[2][2];
; #pragma unroll
;         for (int bj = 0; bj < 2; ++bj)
; #pragma unroll
;             for (int n = 0; n < 2; ++n) gv[bj][n] = *(const f32x4*)(gate + (size_t)b * NADA + col0 + bj * 128 + n * 4) + 1.0f;
;         f32x4 bsA[2][2][2], bsB[2][2][2];
;     ...
;         Y1_LOAD(bsA, 0);
;         Y1_LOAD(bsB, 1); asm volatile("" ::: "memory");
;         Y1_STORE(bsA, 0); asm volatile("" ::: "memory");
	s_add_i32 s75, s75, 2
	s_add_u32 s73, s73, 0x100
	s_addc_u32 s74, s74, 0
	s_add_u32 s46, s46, 0x10000
	s_addc_u32 s47, s47, 0
	s_cmp_gt_u32 s75, 29
	s_cbranch_scc0 .LBB0_1041
	s_lshl_b32 s35, s44, 8
	v_lshrrev_b32_e32 v2, 1, v216
	s_or_b32 s35, s35, s68
	v_and_b32_e32 v30, 56, v2
	s_ashr_i32 s41, s40, 31
	v_add_u32_e32 v2, s35, v30
	s_lshr_b32 s35, s41, 28
	s_lshl_b32 s29, s40, 8
	s_add_i32 s35, s40, s35
	s_ashr_i32 s45, s44, 31
	s_add_i32 s29, s29, s67
	s_ashr_i32 s35, s35, 4
	s_lshl_b64 s[40:41], s[40:41], 12
	s_lshl_b64 s[42:43], s[44:45], 8
	v_and_b32_e32 v14, 15, v216
	s_add_u32 s40, s40, s42
	s_addc_u32 s41, s41, s43
	s_mul_hi_i32 s43, s35, 0x18000
	v_ashrrev_i32_e32 v3, 31, v2
	v_or_b32_e32 v6, s29, v14
	v_readlane_b32 s72, v245, 29
	s_mul_i32 s35, s35, 0x18000
	v_lshlrev_b64 v[2:3], 2, v[2:3]
	v_readlane_b32 s73, v245, 30
	v_ashrrev_i32_e32 v7, 31, v6
	s_add_u32 s42, s62, s35
	v_lshl_add_u64 v[8:9], s[72:73], 0, v[2:3]
	v_lshlrev_b64 v[4:5], 14, v[6:7]
	s_addc_u32 s43, s63, s43
	s_nop 15
	s_nop 15
	v_lshl_add_u64 v[200:201], v[8:9], 0, v[4:5]
	v_lshl_add_u64 v[2:3], s[42:43], 0, v[2:3]
	global_load_dwordx4 v[204:207], v[200:201], off offset:16
	global_load_dwordx4 v[208:211], v[200:201], off
	global_load_dwordx4 v[218:221], v[200:201], off offset:512
	global_load_dwordx4 v[222:225], v[2:3], off nt
	global_load_dwordx4 v[226:229], v[2:3], off offset:16 nt
	global_load_dwordx4 v[182:185], v[2:3], off offset:512 nt
	global_load_dwordx4 v[174:177], v[2:3], off offset:528 nt
	global_load_dwordx4 v[18:21], v[200:201], off offset:528
	v_or_b32_e32 v2, 16, v6
	v_ashrrev_i32_e32 v3, 31, v2
	v_lshlrev_b64 v[2:3], 14, v[2:3]
	v_lshl_add_u64 v[2:3], v[8:9], 0, v[2:3]
	global_load_dwordx4 v[26:29], v[2:3], off nt
	global_load_dwordx4 v[22:25], v[2:3], off offset:16 nt
	global_load_dwordx4 v[10:13], v[2:3], off offset:512 nt
	s_nop 0
	global_load_dwordx4 v[2:5], v[2:3], off offset:528 nt
	v_or_b32_e32 v192, s67, v14
	v_or_b32_e32 v14, 32, v6
	v_or_b32_e32 v6, 48, v6
	v_ashrrev_i32_e32 v15, 31, v14
	v_ashrrev_i32_e32 v7, 31, v6
	v_lshlrev_b64 v[14:15], 14, v[14:15]
	v_lshlrev_b64 v[6:7], 14, v[6:7]
	v_lshl_add_u64 v[14:15], v[8:9], 0, v[14:15]
	v_lshl_add_u64 v[16:17], v[8:9], 0, v[6:7]
	v_lshl_add_u64 v[202:203], s[40:41], 0, v[192:193]
	v_lshlrev_b32_e32 v192, 1, v30
	global_load_dwordx4 v[178:181], v[14:15], off offset:16 nt
	global_load_dwordx4 v[230:233], v[14:15], off nt
	global_load_dwordx4 v[166:169], v[14:15], off offset:528 nt
	global_load_dwordx4 v[170:173], v[14:15], off offset:512 nt
	global_load_dwordx4 v[30:33], v[16:17], off offset:16 nt
	global_load_dwordx4 v[162:165], v[16:17], off nt
	global_load_dwordx4 v[6:9], v[16:17], off offset:528 nt
	s_nop 0
	global_load_dwordx4 v[14:17], v[16:17], off offset:512 nt
	v_lshl_add_u64 v[234:235], s[24:25], 0, v[192:193]
	v_lshlrev_b64 v[202:203], 9, v[202:203]
	v_lshl_add_u64 v[202:203], v[234:235], 0, v[202:203]
	s_movk_i32 s29, 0x2000
	s_mov_b64 s[40:41], 0x200000
	s_mov_b32 s44, s28
	s_mov_b64 s[46:47], s[38:39]
	s_mov_b64 s[42:43], s[36:37]
	v_readlane_b32 s74, v245, 31
	v_readlane_b32 s75, v245, 32
	v_readlane_b32 s76, v245, 33
	v_readlane_b32 s77, v245, 34
	v_readlane_b32 s78, v245, 35
	v_readlane_b32 s79, v245, 36
	v_readlane_b32 s80, v245, 37
	v_readlane_b32 s81, v245, 38
	v_readlane_b32 s82, v245, 39
	v_readlane_b32 s83, v245, 40
	v_readlane_b32 s84, v245, 41
	v_readlane_b32 s85, v245, 42
	v_readlane_b32 s86, v245, 43
	v_readlane_b32 s87, v245, 44
	s_waitcnt vmcnt(0)
	v_pk_mul_f32 v[238:239], v[206:207], s[26:27] op_sel_hi:[1,0]
	v_pk_add_f32 v[184:185], v[184:185], 1.0 op_sel_hi:[1,0]
	v_pk_mul_f32 v[220:221], v[220:221], s[26:27] op_sel_hi:[1,0]
	v_pk_mul_f32 v[218:219], v[218:219], s[26:27] op_sel_hi:[1,0]
	v_pk_add_f32 v[182:183], v[182:183], 1.0 op_sel_hi:[1,0]
	v_pk_add_f32 v[176:177], v[176:177], 1.0 op_sel_hi:[1,0]
	v_pk_add_f32 v[174:175], v[174:175], 1.0 op_sel_hi:[1,0]
	v_pk_mul_f32 v[20:21], v[20:21], s[26:27] op_sel_hi:[1,0]
	v_pk_mul_f32 v[18:19], v[18:19], s[26:27] op_sel_hi:[1,0]
	v_pk_fma_f32 v[220:221], v[152:153], v[184:185], v[220:221]
	v_pk_fma_f32 v[150:151], v[150:151], v[182:183], v[218:219]
	v_pk_fma_f32 v[144:145], v[144:145], v[176:177], v[20:21]
	v_pk_fma_f32 v[20:21], v[142:143], v[174:175], v[18:19]
	v_cvt_pk_bf16_f32 v18, v150, v151
	v_cvt_pk_bf16_f32 v19, v220, v221
	v_cvt_pk_bf16_f32 v20, v20, v21
	v_cvt_pk_bf16_f32 v21, v144, v145
	v_pk_mul_f32 v[234:235], v[210:211], s[26:27] op_sel_hi:[1,0]
	v_pk_mul_f32 v[236:237], v[208:209], s[26:27] op_sel_hi:[1,0]
	v_pk_add_f32 v[208:209], v[224:225], 1.0 op_sel_hi:[1,0]
	v_pk_add_f32 v[210:211], v[222:223], 1.0 op_sel_hi:[1,0]
	global_store_dwordx4 v[202:203], v[18:21], off offset:256
	v_pk_mul_f32 v[240:241], v[204:205], s[26:27] op_sel_hi:[1,0]
	v_pk_add_f32 v[204:205], v[228:229], 1.0 op_sel_hi:[1,0]
	v_pk_mul_f32 v[18:19], v[28:29], s[26:27] op_sel_hi:[1,0]
	v_pk_mul_f32 v[20:21], v[26:27], s[26:27] op_sel_hi:[1,0]
	v_pk_add_f32 v[206:207], v[226:227], 1.0 op_sel_hi:[1,0]
	v_pk_fma_f32 v[26:27], v[148:149], v[208:209], v[18:19]
	v_pk_fma_f32 v[18:19], v[146:147], v[210:211], v[20:21]
	v_pk_mul_f32 v[20:21], v[24:25], s[26:27] op_sel_hi:[1,0]
	v_pk_mul_f32 v[22:23], v[22:23], s[26:27] op_sel_hi:[1,0]
	v_pk_fma_f32 v[24:25], v[140:141], v[204:205], v[20:21]
	v_pk_fma_f32 v[20:21], v[138:139], v[206:207], v[22:23]
	v_add_co_u32_e32 v22, vcc, s29, v202
	v_cvt_pk_bf16_f32 v18, v18, v19
	v_cvt_pk_bf16_f32 v19, v26, v27
	v_cvt_pk_bf16_f32 v20, v20, v21
	v_cvt_pk_bf16_f32 v21, v24, v25
	v_addc_co_u32_e32 v23, vcc, 0, v203, vcc
	v_pk_mul_f32 v[12:13], v[12:13], s[26:27] op_sel_hi:[1,0]
; #define Y1_LOAD(dst, am) do { _Pragma("unroll") for (int mm = 0; mm < 2; ++mm) { const int m_ = ((am) & 1) * 2 + mm; const size_t off_ = (size_t)(rowb + ((am) >> 1) * 128 + m_ * 16) * D + col0; \
;             _Pragma("unroll") for (int bj = 0; bj < 2; ++bj) _Pragma("unroll") for (int n = 0; n < 2; ++n) dst[mm][bj][n] = *(const f32x4*)(x + off_ + bj * 128 + n * 4); } } while (0)
;     __device__ __forceinline__ void operator()(const Acc& acc, const Unit& u, int wr, int wc, int fr, int fq) const {
;     ...
;         Y1_LOAD(bsA, 0);
;         Y1_LOAD(bsB, 1); asm volatile("" ::: "memory");
;         Y1_STORE(bsA, 0); asm volatile("" ::: "memory");
;         Y1_LOAD(bsA, 2); asm volatile("" ::: "memory");
;         Y1_STORE(bsB, 1); asm volatile("" ::: "memory");
;         Y1_LOAD(bsB, 3); asm volatile("" ::: "memory");
	v_pk_mul_f32 v[10:11], v[10:11], s[26:27] op_sel_hi:[1,0]
	v_pk_mul_f32 v[4:5], v[4:5], s[26:27] op_sel_hi:[1,0]
	v_pk_mul_f32 v[2:3], v[2:3], s[26:27] op_sel_hi:[1,0]
	v_pk_fma_f32 v[160:161], v[160:161], v[208:209], v[234:235]
	v_pk_fma_f32 v[158:159], v[158:159], v[210:211], v[236:237]
	v_pk_fma_f32 v[156:157], v[156:157], v[204:205], v[238:239]
	v_pk_fma_f32 v[154:155], v[154:155], v[206:207], v[240:241]
	global_store_dwordx4 v[22:23], v[18:21], off
	v_pk_fma_f32 v[12:13], v[136:137], v[184:185], v[12:13]
	v_pk_fma_f32 v[10:11], v[134:135], v[182:183], v[10:11]
	v_pk_fma_f32 v[18:19], v[132:133], v[176:177], v[4:5]
	v_pk_fma_f32 v[4:5], v[130:131], v[174:175], v[2:3]
	v_cvt_pk_bf16_f32 v152, v158, v159
	v_cvt_pk_bf16_f32 v153, v160, v161
	v_cvt_pk_bf16_f32 v154, v154, v155
	v_cvt_pk_bf16_f32 v155, v156, v157
	v_cvt_pk_bf16_f32 v2, v10, v11
	v_cvt_pk_bf16_f32 v3, v12, v13
	v_cvt_pk_bf16_f32 v4, v4, v5
	v_cvt_pk_bf16_f32 v5, v18, v19
	s_mov_b32 s29, 0x200000
	global_store_dwordx4 v[202:203], v[152:155], off
	global_store_dwordx4 v[22:23], v[2:5], off offset:256
	v_lshl_add_u64 v[22:23], v[200:201], 0, s[40:41]
	v_pk_mul_f32 v[142:143], v[232:233], s[26:27] op_sel_hi:[1,0]
	v_add_co_u32_e32 v2, vcc, s29, v200
	s_mov_b32 s29, 0x240000
	s_nop 0
	v_addc_co_u32_e32 v3, vcc, 0, v201, vcc
	global_load_dwordx4 v[2:5], v[2:3], off nt
	s_nop 0
	global_load_dwordx4 v[10:13], v[22:23], off offset:528 nt
	global_load_dwordx4 v[18:21], v[22:23], off offset:16 nt
	s_nop 0
	global_load_dwordx4 v[22:25], v[22:23], off offset:512 nt
	v_add_co_u32_e32 v26, vcc, s29, v200
	v_pk_mul_f32 v[144:145], v[230:231], s[26:27] op_sel_hi:[1,0]
	s_nop 0
	v_addc_co_u32_e32 v27, vcc, 0, v201, vcc
	v_pk_fma_f32 v[128:129], v[128:129], v[208:209], v[142:143]
	v_pk_fma_f32 v[126:127], v[126:127], v[210:211], v[144:145]
	v_pk_mul_f32 v[142:143], v[180:181], s[26:27] op_sel_hi:[1,0]
	v_pk_mul_f32 v[144:145], v[178:179], s[26:27] op_sel_hi:[1,0]
	s_movk_i32 s29, 0x4000
	s_mov_b64 s[40:41], 0x240000
	v_pk_fma_f32 v[142:143], v[124:125], v[204:205], v[142:143]
	v_pk_fma_f32 v[124:125], v[122:123], v[206:207], v[144:145]
	v_cvt_pk_bf16_f32 v122, v126, v127
	v_add_co_u32_e32 v126, vcc, s29, v202
	v_lshl_add_u64 v[138:139], v[200:201], 0, s[40:41]
	v_cvt_pk_bf16_f32 v123, v128, v129
	v_cvt_pk_bf16_f32 v124, v124, v125
	v_cvt_pk_bf16_f32 v125, v142, v143
	v_addc_co_u32_e32 v127, vcc, 0, v203, vcc
	global_load_dwordx4 v[26:29], v[26:27], off nt
	s_nop 0
	global_load_dwordx4 v[130:133], v[138:139], off offset:528 nt
	global_load_dwordx4 v[134:137], v[138:139], off offset:16 nt
	s_nop 0
	global_load_dwordx4 v[138:141], v[138:139], off offset:512 nt
	global_store_dwordx4 v[126:127], v[122:125], off
	v_pk_mul_f32 v[32:33], v[32:33], s[26:27] op_sel_hi:[1,0]
	v_pk_mul_f32 v[30:31], v[30:31], s[26:27] op_sel_hi:[1,0]
	v_pk_mul_f32 v[122:123], v[172:173], s[26:27] op_sel_hi:[1,0]
	v_pk_mul_f32 v[124:125], v[170:171], s[26:27] op_sel_hi:[1,0]
	v_pk_fma_f32 v[120:121], v[120:121], v[184:185], v[122:123]
	v_pk_fma_f32 v[118:119], v[118:119], v[182:183], v[124:125]
	v_pk_mul_f32 v[122:123], v[168:169], s[26:27] op_sel_hi:[1,0]
	v_pk_mul_f32 v[124:125], v[166:167], s[26:27] op_sel_hi:[1,0]
	v_pk_fma_f32 v[122:123], v[112:113], v[176:177], v[122:123]
	v_pk_fma_f32 v[112:113], v[110:111], v[174:175], v[124:125]
	v_cvt_pk_bf16_f32 v110, v118, v119
	v_cvt_pk_bf16_f32 v111, v120, v121
	v_cvt_pk_bf16_f32 v112, v112, v113
	v_cvt_pk_bf16_f32 v113, v122, v123
	global_store_dwordx4 v[126:127], v[110:113], off offset:256
	s_movk_i32 s29, 0x6000
	v_pk_fma_f32 v[108:109], v[108:109], v[204:205], v[32:33]
	v_pk_mul_f32 v[110:111], v[164:165], s[26:27] op_sel_hi:[1,0]
	v_pk_mul_f32 v[112:113], v[162:163], s[26:27] op_sel_hi:[1,0]
	v_pk_fma_f32 v[110:111], v[116:117], v[208:209], v[110:111]
	v_pk_fma_f32 v[112:113], v[114:115], v[210:211], v[112:113]
	v_pk_fma_f32 v[32:33], v[106:107], v[206:207], v[30:31]
	v_add_co_u32_e32 v106, vcc, s29, v202
	v_cvt_pk_bf16_f32 v30, v112, v113
	v_cvt_pk_bf16_f32 v31, v110, v111
	v_cvt_pk_bf16_f32 v32, v32, v33
	v_cvt_pk_bf16_f32 v33, v108, v109
	v_addc_co_u32_e32 v107, vcc, 0, v203, vcc
	v_pk_mul_f32 v[16:17], v[16:17], s[26:27] op_sel_hi:[1,0]
	v_pk_mul_f32 v[14:15], v[14:15], s[26:27] op_sel_hi:[1,0]
	v_pk_mul_f32 v[8:9], v[8:9], s[26:27] op_sel_hi:[1,0]
	v_pk_mul_f32 v[6:7], v[6:7], s[26:27] op_sel_hi:[1,0]
	global_store_dwordx4 v[106:107], v[30:33], off
	v_pk_fma_f32 v[16:17], v[104:105], v[184:185], v[16:17]
	v_pk_fma_f32 v[14:15], v[102:103], v[182:183], v[14:15]
	v_pk_fma_f32 v[30:31], v[100:101], v[176:177], v[8:9]
	v_pk_fma_f32 v[8:9], v[98:99], v[174:175], v[6:7]
	v_cvt_pk_bf16_f32 v6, v14, v15
	v_cvt_pk_bf16_f32 v7, v16, v17
	v_cvt_pk_bf16_f32 v8, v8, v9
	v_cvt_pk_bf16_f32 v9, v30, v31
	s_mov_b32 s29, 0x280000
	global_store_dwordx4 v[106:107], v[6:9], off offset:256
	s_mov_b64 s[40:41], 0x280000
	v_lshl_add_u64 v[98:99], v[200:201], 0, s[40:41]
	v_add_co_u32_e32 v6, vcc, s29, v200
	s_mov_b32 s29, 0x2c0000
	s_nop 0
	v_addc_co_u32_e32 v7, vcc, 0, v201, vcc
	global_load_dwordx4 v[6:9], v[6:7], off nt
	s_nop 0
	global_load_dwordx4 v[14:17], v[98:99], off offset:528 nt
	global_load_dwordx4 v[30:33], v[98:99], off offset:16 nt
	s_nop 0
	global_load_dwordx4 v[98:101], v[98:99], off offset:512 nt
	s_mov_b64 s[40:41], 0x2c0000
	v_add_co_u32_e32 v102, vcc, s29, v200
	v_lshl_add_u64 v[114:115], v[200:201], 0, s[40:41]
	s_nop 0
	v_addc_co_u32_e32 v103, vcc, 0, v201, vcc
	global_load_dwordx4 v[102:105], v[102:103], off nt
	s_nop 0
	global_load_dwordx4 v[106:109], v[114:115], off offset:528 nt
	global_load_dwordx4 v[110:113], v[114:115], off offset:16 nt
	s_nop 0
	global_load_dwordx4 v[114:117], v[114:115], off offset:512 nt
	s_waitcnt vmcnt(19)
; #define Y1_LOAD(dst, am) do { _Pragma("unroll") for (int mm = 0; mm < 2; ++mm) { const int m_ = ((am) & 1) * 2 + mm; const size_t off_ = (size_t)(rowb + ((am) >> 1) * 128 + m_ * 16) * D + col0; \
;             _Pragma("unroll") for (int bj = 0; bj < 2; ++bj) _Pragma("unroll") for (int n = 0; n < 2; ++n) dst[mm][bj][n] = *(const f32x4*)(x + off_ + bj * 128 + n * 4); } } while (0)
;     __device__ __forceinline__ void operator()(const Acc& acc, const Unit& u, int wr, int wc, int fr, int fq) const {
;     ...
;         Y1_LOAD(bsA, 0);
;         Y1_LOAD(bsB, 1); asm volatile("" ::: "memory");
;         Y1_STORE(bsA, 0); asm volatile("" ::: "memory");
;         Y1_LOAD(bsA, 2); asm volatile("" ::: "memory");
;         Y1_STORE(bsB, 1); asm volatile("" ::: "memory");
;         Y1_LOAD(bsB, 3); asm volatile("" ::: "memory");
;         Y1_STORE(bsA, 2); asm volatile("" ::: "memory");
;         Y1_STORE(bsB, 3);
	v_pk_mul_f32 v[4:5], v[4:5], s[26:27] op_sel_hi:[1,0]
	v_pk_mul_f32 v[2:3], v[2:3], s[26:27] op_sel_hi:[1,0]
	s_waitcnt vmcnt(17)
	v_pk_mul_f32 v[18:19], v[18:19], s[26:27] op_sel_hi:[1,0]
	v_pk_fma_f32 v[4:5], v[96:97], v[208:209], v[4:5]
	v_pk_fma_f32 v[2:3], v[94:95], v[210:211], v[2:3]
	v_pk_mul_f32 v[20:21], v[20:21], s[26:27] op_sel_hi:[1,0]
	v_pk_fma_f32 v[18:19], v[90:91], v[206:207], v[18:19]
	s_mov_b32 s29, 0x10000
	v_pk_fma_f32 v[20:21], v[92:93], v[204:205], v[20:21]
	v_cvt_pk_bf16_f32 v2, v2, v3
	v_cvt_pk_bf16_f32 v3, v4, v5
	v_cvt_pk_bf16_f32 v4, v18, v19
	v_add_co_u32_e32 v18, vcc, s29, v202
	v_cvt_pk_bf16_f32 v5, v20, v21
	s_nop 0
	v_addc_co_u32_e32 v19, vcc, 0, v203, vcc
	global_store_dwordx4 v[18:19], v[2:5], off
	v_pk_mul_f32 v[10:11], v[10:11], s[26:27] op_sel_hi:[1,0]
	s_mov_b32 s29, 0x12000
	s_waitcnt vmcnt(17)
	v_pk_mul_f32 v[2:3], v[24:25], s[26:27] op_sel_hi:[1,0]
	v_pk_mul_f32 v[4:5], v[22:23], s[26:27] op_sel_hi:[1,0]
	v_pk_fma_f32 v[20:21], v[88:89], v[184:185], v[2:3]
	v_pk_fma_f32 v[2:3], v[86:87], v[182:183], v[4:5]
	v_pk_mul_f32 v[4:5], v[12:13], s[26:27] op_sel_hi:[1,0]
	v_cvt_pk_bf16_f32 v2, v2, v3
	v_pk_fma_f32 v[12:13], v[80:81], v[176:177], v[4:5]
	v_pk_fma_f32 v[4:5], v[78:79], v[174:175], v[10:11]
	v_cvt_pk_bf16_f32 v3, v20, v21
	v_cvt_pk_bf16_f32 v4, v4, v5
	v_cvt_pk_bf16_f32 v5, v12, v13
	global_store_dwordx4 v[18:19], v[2:5], off offset:256
	s_waitcnt vmcnt(15)
	v_pk_mul_f32 v[12:13], v[134:135], s[26:27] op_sel_hi:[1,0]
	s_mov_b32 s40, s34
	v_pk_mul_f32 v[2:3], v[28:29], s[26:27] op_sel_hi:[1,0]
	v_pk_mul_f32 v[4:5], v[26:27], s[26:27] op_sel_hi:[1,0]
	v_pk_fma_f32 v[10:11], v[84:85], v[208:209], v[2:3]
	v_pk_fma_f32 v[2:3], v[82:83], v[210:211], v[4:5]
	v_pk_mul_f32 v[4:5], v[136:137], s[26:27] op_sel_hi:[1,0]
	v_cvt_pk_bf16_f32 v2, v2, v3
	v_pk_fma_f32 v[18:19], v[76:77], v[204:205], v[4:5]
	v_pk_fma_f32 v[4:5], v[74:75], v[206:207], v[12:13]
	v_cvt_pk_bf16_f32 v3, v10, v11
	v_add_co_u32_e32 v10, vcc, s29, v202
	v_cvt_pk_bf16_f32 v4, v4, v5
	v_cvt_pk_bf16_f32 v5, v18, v19
	v_addc_co_u32_e32 v11, vcc, 0, v203, vcc
	global_store_dwordx4 v[10:11], v[2:5], off
	v_pk_mul_f32 v[18:19], v[130:131], s[26:27] op_sel_hi:[1,0]
	s_mov_b32 s29, 0x14000
	s_waitcnt vmcnt(15)
	v_pk_mul_f32 v[2:3], v[140:141], s[26:27] op_sel_hi:[1,0]
	v_pk_mul_f32 v[4:5], v[138:139], s[26:27] op_sel_hi:[1,0]
	v_pk_fma_f32 v[12:13], v[72:73], v[184:185], v[2:3]
	v_pk_fma_f32 v[2:3], v[70:71], v[182:183], v[4:5]
	v_pk_mul_f32 v[4:5], v[132:133], s[26:27] op_sel_hi:[1,0]
	v_cvt_pk_bf16_f32 v2, v2, v3
	v_pk_fma_f32 v[20:21], v[64:65], v[176:177], v[4:5]
	v_pk_fma_f32 v[4:5], v[62:63], v[174:175], v[18:19]
	v_cvt_pk_bf16_f32 v3, v12, v13
	v_cvt_pk_bf16_f32 v4, v4, v5
	v_cvt_pk_bf16_f32 v5, v20, v21
	global_store_dwordx4 v[10:11], v[2:5], off offset:256
	s_waitcnt vmcnt(11)
	s_nop 0
	v_pk_mul_f32 v[2:3], v[8:9], s[26:27] op_sel_hi:[1,0]
	v_pk_mul_f32 v[4:5], v[6:7], s[26:27] op_sel_hi:[1,0]
	v_pk_fma_f32 v[6:7], v[68:69], v[208:209], v[2:3]
	v_pk_fma_f32 v[2:3], v[66:67], v[210:211], v[4:5]
	s_waitcnt vmcnt(9)
	v_pk_mul_f32 v[4:5], v[32:33], s[26:27] op_sel_hi:[1,0]
	v_pk_mul_f32 v[8:9], v[30:31], s[26:27] op_sel_hi:[1,0]
	v_pk_fma_f32 v[10:11], v[60:61], v[204:205], v[4:5]
	v_pk_fma_f32 v[4:5], v[58:59], v[206:207], v[8:9]
	v_cvt_pk_bf16_f32 v2, v2, v3
	v_cvt_pk_bf16_f32 v3, v6, v7
	v_add_co_u32_e32 v6, vcc, s29, v202
	v_cvt_pk_bf16_f32 v4, v4, v5
	v_cvt_pk_bf16_f32 v5, v10, v11
	v_addc_co_u32_e32 v7, vcc, 0, v203, vcc
	global_store_dwordx4 v[6:7], v[2:5], off
	v_pk_mul_f32 v[10:11], v[14:15], s[26:27] op_sel_hi:[1,0]
	s_mov_b32 s29, 0x16000
	s_waitcnt vmcnt(9)
	v_pk_mul_f32 v[2:3], v[100:101], s[26:27] op_sel_hi:[1,0]
	v_pk_mul_f32 v[4:5], v[98:99], s[26:27] op_sel_hi:[1,0]
	v_pk_fma_f32 v[8:9], v[56:57], v[184:185], v[2:3]
	v_pk_fma_f32 v[2:3], v[54:55], v[182:183], v[4:5]
	v_pk_mul_f32 v[4:5], v[16:17], s[26:27] op_sel_hi:[1,0]
	v_cvt_pk_bf16_f32 v2, v2, v3
	v_pk_fma_f32 v[12:13], v[48:49], v[176:177], v[4:5]
	v_pk_fma_f32 v[4:5], v[46:47], v[174:175], v[10:11]
	v_cvt_pk_bf16_f32 v3, v8, v9
	v_cvt_pk_bf16_f32 v4, v4, v5
	v_cvt_pk_bf16_f32 v5, v12, v13
	global_store_dwordx4 v[6:7], v[2:5], off offset:256
	s_waitcnt vmcnt(7)
	v_pk_mul_f32 v[8:9], v[110:111], s[26:27] op_sel_hi:[1,0]
	v_pk_mul_f32 v[2:3], v[104:105], s[26:27] op_sel_hi:[1,0]
	v_pk_mul_f32 v[4:5], v[102:103], s[26:27] op_sel_hi:[1,0]
	v_pk_fma_f32 v[6:7], v[52:53], v[208:209], v[2:3]
	v_pk_fma_f32 v[2:3], v[50:51], v[210:211], v[4:5]
	v_pk_mul_f32 v[4:5], v[112:113], s[26:27] op_sel_hi:[1,0]
	v_cvt_pk_bf16_f32 v2, v2, v3
	v_pk_fma_f32 v[10:11], v[44:45], v[204:205], v[4:5]
	v_pk_fma_f32 v[4:5], v[42:43], v[206:207], v[8:9]
	v_cvt_pk_bf16_f32 v3, v6, v7
	v_add_co_u32_e32 v6, vcc, s29, v202
	v_cvt_pk_bf16_f32 v4, v4, v5
	v_cvt_pk_bf16_f32 v5, v10, v11
	v_addc_co_u32_e32 v7, vcc, 0, v203, vcc
	global_store_dwordx4 v[6:7], v[2:5], off
	v_pk_mul_f32 v[10:11], v[106:107], s[26:27] op_sel_hi:[1,0]
	s_and_b64 vcc, exec, s[2:3]
	s_waitcnt vmcnt(7)
	v_pk_mul_f32 v[2:3], v[116:117], s[26:27] op_sel_hi:[1,0]
	v_pk_mul_f32 v[4:5], v[114:115], s[26:27] op_sel_hi:[1,0]
	v_pk_fma_f32 v[8:9], v[40:41], v[184:185], v[2:3]
	v_pk_fma_f32 v[2:3], v[38:39], v[182:183], v[4:5]
	v_pk_mul_f32 v[4:5], v[108:109], s[26:27] op_sel_hi:[1,0]
	v_cvt_pk_bf16_f32 v2, v2, v3
	v_pk_fma_f32 v[12:13], v[36:37], v[176:177], v[4:5]
	v_pk_fma_f32 v[4:5], v[34:35], v[174:175], v[10:11]
	v_cvt_pk_bf16_f32 v3, v8, v9
	v_cvt_pk_bf16_f32 v4, v4, v5
	v_cvt_pk_bf16_f32 v5, v12, v13
	global_store_dwordx4 v[6:7], v[2:5], off offset:256
	s_cbranch_vccz .LBB0_1034
	s_waitcnt vmcnt(0)
	s_cmpk_gt_u32 s27, 0xff
	s_cbranch_scc1 .LBB0_1045
	s_barrier

; #define PG8_STAGE(bufoff, gbase, voff) do { _Pragma("unroll") for (int _i = 0; _i < 2; ++_i) \
;         __builtin_amdgcn_global_load_lds((const unsigned*)((const char*)(gbase) + (size_t)_i * p##voff + (voff)), (LAS unsigned*)(lds + (bufoff) + ldsw + _i * 8192), 16, 0, 0); } while (0)
; #define PG8_LDA(dst, b, h) do { _Pragma("unroll") for (int m = 0; m < 4; ++m) _Pragma("unroll") for (int k = 0; k < 2; ++k) dst[m][k] = *(const LAS bf16x8*)(lds + PG8_SA(b, h) + aoff + m * 2048 + k * 1024); } while (0)
; #define PG8_LDB(dst, b, h) do { _Pragma("unroll") for (int n = 0; n < 2; ++n) _Pragma("unroll") for (int k = 0; k < 2; ++k) dst[n][k] = *(const LAS bf16x8*)(lds + PG8_SB(b, h) + boff + n * 2048 + k * 1024); } while (0)
; #define PG8_WAIT_V(n) asm volatile("s_waitcnt vmcnt(" #n ")" ::: "memory")
; #define PG8_WAIT_L(n) asm volatile("s_waitcnt lgkmcnt(" #n ")" ::: "memory")
; #define PG8_BAR __builtin_amdgcn_s_barrier()
; #define PG8_SCHED __builtin_amdgcn_sched_barrier(0)
;     ...
;             PG8_LDB(B0, 0, 0); PG8_LDB(B1, 0, 1); PG8_SCHED; PG8_LDA(At, 0, 0); PG8_STAGE(PG8_SA(1, 1), a1 + hstepA, voffA);
;             PG8_WAIT_V(8); PG8_WAIT_L(0); PG8_BAR; PG8_MMA(0, 0, At, B0); PG8_MMA(0, 1, At, B1); PG8_BAR; PG8_SCHED;
;             PG8_LDA(At, 0, 1); PG8_STAGE(PG8_SB(0, 0), b2, voffB); PG8_STAGE(PG8_SB(0, 1), b2 + hstepB, voffB); PG8_STAGE(PG8_SA(0, 0), a2, voffA);
;             PG8_WAIT_V(8); PG8_WAIT_L(0); PG8_BAR; PG8_MMA(1, 0, At, B0); PG8_MMA(1, 1, At, B1); PG8_BAR; PG8_SCHED;
.LBB0_1281:
	ds_read_b128 v[142:145], v188
	ds_read_b128 v[146:149], v188 offset:1024
	ds_read_b128 v[150:153], v188 offset:2048
	ds_read_b128 v[154:157], v188 offset:3072
	ds_read_b128 v[158:161], v189
	ds_read_b128 v[162:165], v189 offset:1024
	ds_read_b128 v[166:169], v189 offset:2048
	ds_read_b128 v[170:173], v189 offset:3072
	s_add_u32 s50, s44, s48
	s_addc_u32 s51, s45, s49
	s_add_u32 s83, s50, 0x10000
	s_addc_u32 s86, s51, 0
	s_add_u32 s50, s50, 0x18000
	s_addc_u32 s51, s51, 0
	s_cmp_eq_u32 s48, 0x7f0000
	s_cselect_b32 s51, s79, s51
	s_cselect_b32 s50, s78, s50
	s_cselect_b32 s85, s35, s81
	s_cselect_b32 s84, s47, s80
	s_cselect_b32 s87, s37, s86
	s_cselect_b32 s86, s43, s83
	v_lshl_add_u64 v[212:213], v[140:141], 0, s[48:49]
	s_mov_b64 s[88:89], 0xc000
	v_lshl_add_u64 v[214:215], v[212:213], 0, s[88:89]
	s_add_i32 m0, s57, 0xc000
	s_mov_b64 s[88:89], 0xe000
	ds_read_b128 v[174:177], v190
	ds_read_b128 v[178:181], v190 offset:1024
	ds_read_b128 v[182:185], v190 offset:2048
	ds_read_b128 v[192:195], v190 offset:3072
	ds_read_b128 v[196:199], v190 offset:4096
	ds_read_b128 v[200:203], v190 offset:5120
	ds_read_b128 v[204:207], v190 offset:6144
	ds_read_b128 v[208:211], v190 offset:7168
	global_load_lds_dwordx4 v[214:215], off
	v_lshl_add_u64 v[212:213], v[212:213], 0, s[88:89]
	s_add_i32 m0, s57, 0xe000
	s_nop 0
	global_load_lds_dwordx4 v[212:213], off
	s_waitcnt vmcnt(8)
	s_waitcnt lgkmcnt(0)
	s_barrier
	s_setprio 1
	s_waitcnt lgkmcnt(0)
	v_mfma_f32_16x16x32_bf16 v[124:127], v[142:145], v[174:177], v[124:127]
	v_mfma_f32_16x16x32_bf16 v[124:127], v[146:149], v[178:181], v[124:127]
	v_mfma_f32_16x16x32_bf16 v[120:123], v[150:153], v[174:177], v[120:123]
	v_mfma_f32_16x16x32_bf16 v[120:123], v[154:157], v[178:181], v[120:123]
	v_mfma_f32_16x16x32_bf16 v[116:119], v[142:145], v[182:185], v[116:119]
	v_mfma_f32_16x16x32_bf16 v[116:119], v[146:149], v[192:195], v[116:119]
	v_mfma_f32_16x16x32_bf16 v[112:115], v[150:153], v[182:185], v[112:115]
	v_mfma_f32_16x16x32_bf16 v[112:115], v[154:157], v[192:195], v[112:115]
	v_mfma_f32_16x16x32_bf16 v[108:111], v[142:145], v[196:199], v[108:111]
	v_mfma_f32_16x16x32_bf16 v[108:111], v[146:149], v[200:203], v[108:111]
	v_mfma_f32_16x16x32_bf16 v[104:107], v[150:153], v[196:199], v[104:107]
	v_mfma_f32_16x16x32_bf16 v[104:107], v[154:157], v[200:203], v[104:107]
	v_mfma_f32_16x16x32_bf16 v[100:103], v[142:145], v[204:207], v[100:103]
	v_mfma_f32_16x16x32_bf16 v[100:103], v[146:149], v[208:211], v[100:103]
	v_mfma_f32_16x16x32_bf16 v[96:99], v[150:153], v[204:207], v[96:99]
	v_mfma_f32_16x16x32_bf16 v[96:99], v[154:157], v[208:211], v[96:99]
	s_setprio 0
	s_setprio 1
	v_mfma_f32_16x16x32_bf16 v[60:63], v[158:161], v[174:177], v[60:63]
	v_mfma_f32_16x16x32_bf16 v[60:63], v[162:165], v[178:181], v[60:63]
	v_mfma_f32_16x16x32_bf16 v[56:59], v[166:169], v[174:177], v[56:59]
	v_mfma_f32_16x16x32_bf16 v[56:59], v[170:173], v[178:181], v[56:59]
	v_mfma_f32_16x16x32_bf16 v[52:55], v[158:161], v[182:185], v[52:55]
	v_mfma_f32_16x16x32_bf16 v[52:55], v[162:165], v[192:195], v[52:55]
	v_mfma_f32_16x16x32_bf16 v[48:51], v[166:169], v[182:185], v[48:51]
	v_mfma_f32_16x16x32_bf16 v[48:51], v[170:173], v[192:195], v[48:51]
	v_mfma_f32_16x16x32_bf16 v[44:47], v[158:161], v[196:199], v[44:47]
	v_mfma_f32_16x16x32_bf16 v[44:47], v[162:165], v[200:203], v[44:47]
	v_mfma_f32_16x16x32_bf16 v[40:43], v[166:169], v[196:199], v[40:43]
	v_mfma_f32_16x16x32_bf16 v[40:43], v[170:173], v[200:203], v[40:43]
	v_mfma_f32_16x16x32_bf16 v[36:39], v[158:161], v[204:207], v[36:39]
	v_mfma_f32_16x16x32_bf16 v[36:39], v[162:165], v[208:211], v[36:39]
	v_mfma_f32_16x16x32_bf16 v[32:35], v[166:169], v[204:207], v[32:35]
	v_mfma_f32_16x16x32_bf16 v[32:35], v[170:173], v[208:211], v[32:35]
	s_setprio 0
	s_barrier
	s_add_i32 s83, s94, s56
	v_lshl_add_u64 v[212:213], s[84:85], 0, v[130:131]
	s_mov_b32 m0, s83
	ds_read_b128 v[174:177], v190 offset:16384
	ds_read_b128 v[178:181], v190 offset:17408
	ds_read_b128 v[182:185], v190 offset:18432
	ds_read_b128 v[192:195], v190 offset:19456
	ds_read_b128 v[196:199], v190 offset:20480
	ds_read_b128 v[200:203], v190 offset:21504
	ds_read_b128 v[204:207], v190 offset:22528
	ds_read_b128 v[208:211], v190 offset:23552
	global_load_lds_dwordx4 v[212:213], off
	v_lshl_add_u64 v[214:215], v[212:213], 0, s[4:5]
	s_add_i32 m0, s83, 0x2000
	s_add_i32 s83, s95, s56
	global_load_lds_dwordx4 v[214:215], off
	v_lshl_add_u64 v[214:215], v[212:213], 0, s[6:7]
	s_mov_b32 m0, s83
	s_nop 0
	global_load_lds_dwordx4 v[214:215], off
	v_lshl_add_u64 v[214:215], v[212:213], 0, s[8:9]
	s_add_i32 m0, s83, 0x2000
	s_nop 0
	global_load_lds_dwordx4 v[214:215], off
	v_lshl_add_u64 v[214:215], s[86:87], 0, v[128:129]
	s_mov_b32 m0, s57
	v_lshl_add_u64 v[216:217], v[214:215], 0, s[10:11]
	global_load_lds_dwordx4 v[214:215], off
	s_mov_b32 m0, s58
	s_nop 0
	global_load_lds_dwordx4 v[216:217], off
	s_waitcnt vmcnt(8)
	s_waitcnt lgkmcnt(0)
	s_barrier
; #define PG8_STAGE(bufoff, gbase, voff) do { _Pragma("unroll") for (int _i = 0; _i < 2; ++_i) \
;         __builtin_amdgcn_global_load_lds((const unsigned*)((const char*)(gbase) + (size_t)_i * p##voff + (voff)), (LAS unsigned*)(lds + (bufoff) + ldsw + _i * 8192), 16, 0, 0); } while (0)
; #define PG8_LDA(dst, b, h) do { _Pragma("unroll") for (int m = 0; m < 4; ++m) _Pragma("unroll") for (int k = 0; k < 2; ++k) dst[m][k] = *(const LAS bf16x8*)(lds + PG8_SA(b, h) + aoff + m * 2048 + k * 1024); } while (0)
; #define PG8_LDB(dst, b, h) do { _Pragma("unroll") for (int n = 0; n < 2; ++n) _Pragma("unroll") for (int k = 0; k < 2; ++k) dst[n][k] = *(const LAS bf16x8*)(lds + PG8_SB(b, h) + boff + n * 2048 + k * 1024); } while (0)
; #define PG8_WAIT_V(n) asm volatile("s_waitcnt vmcnt(" #n ")" ::: "memory")
; #define PG8_WAIT_L(n) asm volatile("s_waitcnt lgkmcnt(" #n ")" ::: "memory")
; #define PG8_BAR __builtin_amdgcn_s_barrier()
; #define PG8_SCHED __builtin_amdgcn_sched_barrier(0)
;     ...
;             PG8_WAIT_V(8); PG8_WAIT_L(0); PG8_BAR; PG8_MMA(1, 0, At, B0); PG8_MMA(1, 1, At, B1); PG8_BAR; PG8_SCHED;
;             PG8_LDB(B0, 1, 0); PG8_LDB(B1, 1, 1); PG8_SCHED; PG8_LDA(At, 1, 0); PG8_STAGE(PG8_SA(0, 1), a2 + hstepA, voffA);
;             PG8_WAIT_V(8); PG8_WAIT_L(0); PG8_BAR; PG8_MMA(0, 0, At, B0); PG8_MMA(0, 1, At, B1); PG8_BAR; PG8_SCHED;
;             PG8_LDA(At, 1, 1); PG8_STAGE(PG8_SB(1, 0), b3, voffB); PG8_STAGE(PG8_SB(1, 1), b3 + hstepB, voffB); PG8_STAGE(PG8_SA(1, 0), a3, voffA);
	s_setprio 1
	s_waitcnt lgkmcnt(0)
	v_mfma_f32_16x16x32_bf16 v[92:95], v[142:145], v[174:177], v[92:95]
	v_mfma_f32_16x16x32_bf16 v[92:95], v[146:149], v[178:181], v[92:95]
	v_mfma_f32_16x16x32_bf16 v[88:91], v[150:153], v[174:177], v[88:91]
	v_mfma_f32_16x16x32_bf16 v[88:91], v[154:157], v[178:181], v[88:91]
	v_mfma_f32_16x16x32_bf16 v[84:87], v[142:145], v[182:185], v[84:87]
	v_mfma_f32_16x16x32_bf16 v[84:87], v[146:149], v[192:195], v[84:87]
	v_mfma_f32_16x16x32_bf16 v[80:83], v[150:153], v[182:185], v[80:83]
	v_mfma_f32_16x16x32_bf16 v[80:83], v[154:157], v[192:195], v[80:83]
	v_mfma_f32_16x16x32_bf16 v[76:79], v[142:145], v[196:199], v[76:79]
	v_mfma_f32_16x16x32_bf16 v[76:79], v[146:149], v[200:203], v[76:79]
	v_mfma_f32_16x16x32_bf16 v[72:75], v[150:153], v[196:199], v[72:75]
	v_mfma_f32_16x16x32_bf16 v[72:75], v[154:157], v[200:203], v[72:75]
	v_mfma_f32_16x16x32_bf16 v[68:71], v[142:145], v[204:207], v[68:71]
	v_mfma_f32_16x16x32_bf16 v[68:71], v[146:149], v[208:211], v[68:71]
	v_mfma_f32_16x16x32_bf16 v[64:67], v[150:153], v[204:207], v[64:67]
	v_mfma_f32_16x16x32_bf16 v[64:67], v[154:157], v[208:211], v[64:67]
	s_setprio 0
	s_setprio 1
	v_mfma_f32_16x16x32_bf16 v[28:31], v[158:161], v[174:177], v[28:31]
	v_mfma_f32_16x16x32_bf16 v[28:31], v[162:165], v[178:181], v[28:31]
	v_mfma_f32_16x16x32_bf16 v[24:27], v[166:169], v[174:177], v[24:27]
	v_mfma_f32_16x16x32_bf16 v[24:27], v[170:173], v[178:181], v[24:27]
	v_mfma_f32_16x16x32_bf16 v[20:23], v[158:161], v[182:185], v[20:23]
	v_mfma_f32_16x16x32_bf16 v[20:23], v[162:165], v[192:195], v[20:23]
	v_mfma_f32_16x16x32_bf16 v[16:19], v[166:169], v[182:185], v[16:19]
	v_mfma_f32_16x16x32_bf16 v[16:19], v[170:173], v[192:195], v[16:19]
	v_mfma_f32_16x16x32_bf16 v[12:15], v[158:161], v[196:199], v[12:15]
	v_mfma_f32_16x16x32_bf16 v[12:15], v[162:165], v[200:203], v[12:15]
	v_mfma_f32_16x16x32_bf16 v[8:11], v[166:169], v[196:199], v[8:11]
	v_mfma_f32_16x16x32_bf16 v[8:11], v[170:173], v[200:203], v[8:11]
	v_mfma_f32_16x16x32_bf16 v[4:7], v[158:161], v[204:207], v[4:7]
	v_mfma_f32_16x16x32_bf16 v[4:7], v[162:165], v[208:211], v[4:7]
	v_mfma_f32_16x16x32_bf16 v[0:3], v[166:169], v[204:207], v[0:3]
	v_mfma_f32_16x16x32_bf16 v[0:3], v[170:173], v[208:211], v[0:3]
	s_setprio 0
	s_barrier
	s_add_i32 s83, 0, 0x18000
	v_add_u32_e32 v132, s83, v187
	s_add_i32 s84, 0, 0x1c000
	ds_read_b128 v[142:145], v132
	ds_read_b128 v[146:149], v132 offset:1024
	ds_read_b128 v[150:153], v132 offset:2048
	ds_read_b128 v[154:157], v132 offset:3072
	v_add_u32_e32 v132, s84, v187
	ds_read_b128 v[158:161], v132
	ds_read_b128 v[162:165], v132 offset:1024
	ds_read_b128 v[166:169], v132 offset:2048
	ds_read_b128 v[170:173], v132 offset:3072
	s_mov_b32 m0, s59
	v_lshl_add_u64 v[216:217], v[214:215], 0, s[12:13]
	ds_read_b128 v[174:177], v190 offset:32768
	ds_read_b128 v[178:181], v190 offset:33792
	ds_read_b128 v[182:185], v190 offset:34816
	ds_read_b128 v[192:195], v190 offset:35840
	ds_read_b128 v[196:199], v190 offset:36864
	ds_read_b128 v[200:203], v190 offset:37888
	ds_read_b128 v[204:207], v190 offset:38912
	ds_read_b128 v[208:211], v190 offset:39936
	global_load_lds_dwordx4 v[216:217], off
	v_lshl_add_u64 v[214:215], v[214:215], 0, s[14:15]
	s_mov_b32 m0, s60
	s_nop 0
	global_load_lds_dwordx4 v[214:215], off
	s_waitcnt vmcnt(8)
	s_waitcnt lgkmcnt(0)
	s_barrier
	s_setprio 1
	s_waitcnt lgkmcnt(0)
	v_mfma_f32_16x16x32_bf16 v[124:127], v[142:145], v[174:177], v[124:127]
	v_mfma_f32_16x16x32_bf16 v[124:127], v[146:149], v[178:181], v[124:127]
	v_mfma_f32_16x16x32_bf16 v[120:123], v[150:153], v[174:177], v[120:123]
	v_mfma_f32_16x16x32_bf16 v[120:123], v[154:157], v[178:181], v[120:123]
	v_mfma_f32_16x16x32_bf16 v[116:119], v[142:145], v[182:185], v[116:119]
	v_mfma_f32_16x16x32_bf16 v[116:119], v[146:149], v[192:195], v[116:119]
	v_mfma_f32_16x16x32_bf16 v[112:115], v[150:153], v[182:185], v[112:115]
	v_mfma_f32_16x16x32_bf16 v[112:115], v[154:157], v[192:195], v[112:115]
	v_mfma_f32_16x16x32_bf16 v[108:111], v[142:145], v[196:199], v[108:111]
	v_mfma_f32_16x16x32_bf16 v[108:111], v[146:149], v[200:203], v[108:111]
	v_mfma_f32_16x16x32_bf16 v[104:107], v[150:153], v[196:199], v[104:107]
	v_mfma_f32_16x16x32_bf16 v[104:107], v[154:157], v[200:203], v[104:107]
	v_mfma_f32_16x16x32_bf16 v[100:103], v[142:145], v[204:207], v[100:103]
	v_mfma_f32_16x16x32_bf16 v[100:103], v[146:149], v[208:211], v[100:103]
	v_mfma_f32_16x16x32_bf16 v[96:99], v[150:153], v[204:207], v[96:99]
	v_mfma_f32_16x16x32_bf16 v[96:99], v[154:157], v[208:211], v[96:99]
	s_setprio 0
	s_setprio 1
	v_mfma_f32_16x16x32_bf16 v[60:63], v[158:161], v[174:177], v[60:63]
	v_mfma_f32_16x16x32_bf16 v[60:63], v[162:165], v[178:181], v[60:63]
	v_mfma_f32_16x16x32_bf16 v[56:59], v[166:169], v[174:177], v[56:59]
	v_mfma_f32_16x16x32_bf16 v[56:59], v[170:173], v[178:181], v[56:59]
	v_mfma_f32_16x16x32_bf16 v[52:55], v[158:161], v[182:185], v[52:55]
	v_mfma_f32_16x16x32_bf16 v[52:55], v[162:165], v[192:195], v[52:55]
	v_mfma_f32_16x16x32_bf16 v[48:51], v[166:169], v[182:185], v[48:51]
	v_mfma_f32_16x16x32_bf16 v[48:51], v[170:173], v[192:195], v[48:51]
	v_mfma_f32_16x16x32_bf16 v[44:47], v[158:161], v[196:199], v[44:47]
	v_mfma_f32_16x16x32_bf16 v[44:47], v[162:165], v[200:203], v[44:47]
	v_mfma_f32_16x16x32_bf16 v[40:43], v[166:169], v[196:199], v[40:43]
	v_mfma_f32_16x16x32_bf16 v[40:43], v[170:173], v[200:203], v[40:43]
	v_mfma_f32_16x16x32_bf16 v[36:39], v[158:161], v[204:207], v[36:39]
	v_mfma_f32_16x16x32_bf16 v[36:39], v[162:165], v[208:211], v[36:39]
	v_mfma_f32_16x16x32_bf16 v[32:35], v[166:169], v[204:207], v[32:35]
	v_mfma_f32_16x16x32_bf16 v[32:35], v[170:173], v[208:211], v[32:35]
	s_setprio 0
	s_barrier
; #define PG8_STAGE(bufoff, gbase, voff) do { _Pragma("unroll") for (int _i = 0; _i < 2; ++_i) \
;         __builtin_amdgcn_global_load_lds((const unsigned*)((const char*)(gbase) + (size_t)_i * p##voff + (voff)), (LAS unsigned*)(lds + (bufoff) + ldsw + _i * 8192), 16, 0, 0); } while (0)
; #define PG8_LDA(dst, b, h) do { _Pragma("unroll") for (int m = 0; m < 4; ++m) _Pragma("unroll") for (int k = 0; k < 2; ++k) dst[m][k] = *(const LAS bf16x8*)(lds + PG8_SA(b, h) + aoff + m * 2048 + k * 1024); } while (0)
; #define PG8_WAIT_V(n) asm volatile("s_waitcnt vmcnt(" #n ")" ::: "memory")
; #define PG8_WAIT_L(n) asm volatile("s_waitcnt lgkmcnt(" #n ")" ::: "memory")
; #define PG8_BAR __builtin_amdgcn_s_barrier()
; #define PG8_SCHED __builtin_amdgcn_sched_barrier(0)
;     ...
;             PG8_LDA(At, 1, 1); PG8_STAGE(PG8_SB(1, 0), b3, voffB); PG8_STAGE(PG8_SB(1, 1), b3 + hstepB, voffB); PG8_STAGE(PG8_SA(1, 0), a3, voffA);
;             PG8_WAIT_V(8); PG8_WAIT_L(0); PG8_BAR; PG8_MMA(1, 0, At, B0); PG8_MMA(1, 1, At, B1); PG8_BAR; PG8_SCHED;
;         }
;         if constexpr (ALIGN) { if (wr == 0) PG8_BAR; }
;         if constexpr (F8) asm volatile("s_nop 15\n\ts_nop 15" ::: "memory");
;         E(acc, cur, wr, wc, fr, fq);
;     __device__ __forceinline__ void operator()(const Acc& acc, const Unit& u, int wr, int wc, int fr, int fq) const {
;     ...
;         const int rowb = u.pm * 256 + wr * 64 + fr, col0 = u.pn * 256 + wc * 32 + 8 * fq; const int b = (u.pm * 256) / S;
;         const size_t yb = (((size_t)u.pm * 16 + u.pn) * 256 + (wr * 64 + fr)) * 256 + wc * 32 + 8 * fq;
; #pragma unroll
;         for (int bj = 0; bj < 2; ++bj) {
;             f32x4 gm[2], G[2], Bc[2];
; #pragma unroll
;             for (int n = 0; n < 2; ++n) { const int c = col0 + bj * 128 + n * 4; gm[n] = *(const f32x4*)(gate + (size_t)b * NADA + c) + 1.0f; G[n] = *(const f32x4*)(lg + c) * ALPHA; Bc[n] = *(const f32x4*)(lb + c) * ALPHA; }
; #pragma unroll
;             for (int hf = 0; hf < 2; ++hf) {
;                 u32x4 yv[4]; f32x2 st[4];
; #pragma unroll
;                 for (int m = 0; m < 4; ++m) { const int row = rowb + hf * 128 + m * 16; yv[m] = *(const u32x4*)(y1 + yb + (size_t)(hf * 128 + m * 16) * 256 + bj * 128); st[m] = *(const f32x2*)(stats + (size_t)row * 2); }
	s_add_i32 s83, s83, s56
	v_lshl_add_u64 v[214:215], v[212:213], 0, s[20:21]
	s_mov_b32 m0, s83
	ds_read_b128 v[174:177], v190 offset:49152
	ds_read_b128 v[178:181], v190 offset:50176
	ds_read_b128 v[182:185], v190 offset:51200
	ds_read_b128 v[192:195], v190 offset:52224
	ds_read_b128 v[196:199], v190 offset:53248
	ds_read_b128 v[200:203], v190 offset:54272
	ds_read_b128 v[204:207], v190 offset:55296
	ds_read_b128 v[208:211], v190 offset:56320
	global_load_lds_dwordx4 v[214:215], off
	v_lshl_add_u64 v[214:215], v[212:213], 0, s[22:23]
	s_add_i32 m0, s83, 0x2000
	s_add_i32 s83, s84, s56
	global_load_lds_dwordx4 v[214:215], off
	v_lshl_add_u64 v[214:215], v[212:213], 0, s[24:25]
	s_mov_b32 m0, s83
	v_lshl_add_u64 v[212:213], v[212:213], 0, s[26:27]
	global_load_lds_dwordx4 v[214:215], off
	s_add_i32 m0, s83, 0x2000
	s_nop 0
	global_load_lds_dwordx4 v[212:213], off
	v_lshl_add_u64 v[212:213], s[50:51], 0, v[128:129]
	s_mov_b32 m0, s71
	s_nop 0
	global_load_lds_dwordx4 v[212:213], off
	v_lshl_add_u64 v[212:213], v[212:213], 0, s[10:11]
	s_mov_b32 m0, s72
	s_nop 0
	global_load_lds_dwordx4 v[212:213], off
	s_waitcnt vmcnt(8)
	s_waitcnt lgkmcnt(0)
	s_barrier
	s_setprio 1
	s_waitcnt lgkmcnt(0)
	v_mfma_f32_16x16x32_bf16 v[92:95], v[142:145], v[174:177], v[92:95]
	v_mfma_f32_16x16x32_bf16 v[92:95], v[146:149], v[178:181], v[92:95]
	v_mfma_f32_16x16x32_bf16 v[88:91], v[150:153], v[174:177], v[88:91]
	v_mfma_f32_16x16x32_bf16 v[88:91], v[154:157], v[178:181], v[88:91]
	v_mfma_f32_16x16x32_bf16 v[84:87], v[142:145], v[182:185], v[84:87]
	v_mfma_f32_16x16x32_bf16 v[84:87], v[146:149], v[192:195], v[84:87]
	v_mfma_f32_16x16x32_bf16 v[80:83], v[150:153], v[182:185], v[80:83]
	v_mfma_f32_16x16x32_bf16 v[80:83], v[154:157], v[192:195], v[80:83]
	v_mfma_f32_16x16x32_bf16 v[76:79], v[142:145], v[196:199], v[76:79]
	v_mfma_f32_16x16x32_bf16 v[76:79], v[146:149], v[200:203], v[76:79]
	v_mfma_f32_16x16x32_bf16 v[72:75], v[150:153], v[196:199], v[72:75]
	v_mfma_f32_16x16x32_bf16 v[72:75], v[154:157], v[200:203], v[72:75]
	v_mfma_f32_16x16x32_bf16 v[68:71], v[142:145], v[204:207], v[68:71]
	v_mfma_f32_16x16x32_bf16 v[68:71], v[146:149], v[208:211], v[68:71]
	v_mfma_f32_16x16x32_bf16 v[64:67], v[150:153], v[204:207], v[64:67]
	v_mfma_f32_16x16x32_bf16 v[64:67], v[154:157], v[208:211], v[64:67]
	s_setprio 0
	s_setprio 1
	v_mfma_f32_16x16x32_bf16 v[28:31], v[158:161], v[174:177], v[28:31]
	v_mfma_f32_16x16x32_bf16 v[28:31], v[162:165], v[178:181], v[28:31]
	v_mfma_f32_16x16x32_bf16 v[24:27], v[166:169], v[174:177], v[24:27]
	v_mfma_f32_16x16x32_bf16 v[24:27], v[170:173], v[178:181], v[24:27]
	v_mfma_f32_16x16x32_bf16 v[20:23], v[158:161], v[182:185], v[20:23]
	v_mfma_f32_16x16x32_bf16 v[20:23], v[162:165], v[192:195], v[20:23]
	v_mfma_f32_16x16x32_bf16 v[16:19], v[166:169], v[182:185], v[16:19]
	v_mfma_f32_16x16x32_bf16 v[16:19], v[170:173], v[192:195], v[16:19]
	v_mfma_f32_16x16x32_bf16 v[12:15], v[158:161], v[196:199], v[12:15]
	v_mfma_f32_16x16x32_bf16 v[12:15], v[162:165], v[200:203], v[12:15]
	v_mfma_f32_16x16x32_bf16 v[8:11], v[166:169], v[196:199], v[8:11]
	v_mfma_f32_16x16x32_bf16 v[8:11], v[170:173], v[200:203], v[8:11]
	v_mfma_f32_16x16x32_bf16 v[4:7], v[158:161], v[204:207], v[4:7]
	v_mfma_f32_16x16x32_bf16 v[4:7], v[162:165], v[208:211], v[4:7]
	v_mfma_f32_16x16x32_bf16 v[0:3], v[166:169], v[204:207], v[0:3]
	v_mfma_f32_16x16x32_bf16 v[0:3], v[170:173], v[208:211], v[0:3]
	s_setprio 0
	s_barrier
	s_add_i32 s82, s82, 2
	s_add_u32 s80, s80, 0x100
	s_addc_u32 s81, s81, 0
	s_add_u32 s48, s48, 0x10000
	s_addc_u32 s49, s49, 0
	s_cmpk_gt_u32 s82, 0xfd
	s_cbranch_scc0 .LBB0_1281
	s_lshl_b32 s37, s46, 8
	v_lshrrev_b32_e32 v132, 1, v191
	s_or_b32 s37, s37, s74
	v_and_b32_e32 v141, 56, v132
	s_ashr_i32 s43, s42, 31
	v_add_u32_e32 v140, s37, v141
	s_lshr_b32 s37, s43, 28
	s_lshl_b32 s35, s42, 8
	s_add_i32 s37, s42, s37
	s_ashr_i32 s47, s46, 31
	s_add_i32 s35, s35, s73
	s_ashr_i32 s37, s37, 4
	s_lshl_b64 s[42:43], s[42:43], 12
	s_lshl_b64 s[44:45], s[46:47], 8
	v_and_b32_e32 v150, 15, v191
	s_add_u32 s42, s42, s44
	s_addc_u32 s43, s43, s45
	v_or_b32_e32 v132, s73, v150
	v_lshl_add_u64 v[148:149], s[42:43], 0, v[132:133]
	s_mul_hi_i32 s43, s37, 0x18000
	s_mul_i32 s37, s37, 0x18000
	v_add_u32_e32 v132, s74, v141
	v_ashrrev_i32_e32 v141, 31, v140
	v_readlane_b32 s76, v245, 10
	s_add_u32 s42, s69, s37
	v_lshlrev_b64 v[220:221], 9, v[148:149]
	v_or_b32_e32 v154, s35, v150
	v_lshlrev_b64 v[140:141], 2, v[140:141]
	v_readlane_b32 s78, v245, 12
	v_readlane_b32 s79, v245, 13
	v_readlane_b32 s80, v245, 14
	v_readlane_b32 s81, v245, 15
	s_addc_u32 s43, s70, s43
	v_lshl_or_b32 v220, v132, 1, v220
	v_ashrrev_i32_e32 v155, 31, v154
	v_lshl_add_u64 v[142:143], s[78:79], 0, v[140:141]
	v_lshl_add_u64 v[144:145], s[80:81], 0, v[140:141]
	v_lshl_add_u64 v[146:147], s[42:43], 0, v[140:141]
	v_lshl_add_u64 v[148:149], s[16:17], 0, v[220:221]
	v_lshl_add_u64 v[140:141], v[154:155], 3, s[18:19]
	global_load_dwordx4 v[164:167], v[142:143], off offset:16
	global_load_dwordx4 v[168:171], v[142:143], off
	global_load_dwordx4 v[182:185], v[144:145], off offset:16
	global_load_dwordx4 v[192:195], v[144:145], off
	global_load_dwordx4 v[196:199], v[146:147], off offset:16
	global_load_dwordx4 v[200:203], v[146:147], off
	global_load_dwordx4 v[204:207], v[148:149], off nt
	global_load_dwordx2 v[222:223], v[140:141], off
	v_or_b32_e32 v152, 16, v154
	v_add_co_u32_e32 v150, vcc, s66, v148
	v_ashrrev_i32_e32 v153, 31, v152
	s_nop 0
	v_addc_co_u32_e32 v151, vcc, 0, v149, vcc
	v_lshl_add_u64 v[152:153], v[152:153], 3, s[18:19]
	global_load_dwordx4 v[208:211], v[150:151], off nt
	global_load_dwordx2 v[224:225], v[152:153], off
	v_add_co_u32_e32 v158, vcc, s67, v148
	v_or_b32_e32 v156, 32, v154
	s_nop 0
	v_addc_co_u32_e32 v159, vcc, 0, v149, vcc
	v_or_b32_e32 v154, 48, v154
	v_ashrrev_i32_e32 v157, 31, v156
	global_load_dwordx4 v[212:215], v[158:159], off nt
	v_ashrrev_i32_e32 v155, 31, v154
	v_lshl_add_u64 v[160:161], v[156:157], 3, s[18:19]
	v_add_co_u32_e32 v156, vcc, s68, v148
	v_lshl_add_u64 v[154:155], v[154:155], 3, s[18:19]
	s_nop 0
	v_addc_co_u32_e32 v157, vcc, 0, v149, vcc
	global_load_dwordx2 v[226:227], v[160:161], off
	global_load_dwordx4 v[216:219], v[156:157], off nt
	global_load_dwordx2 v[228:229], v[154:155], off
	v_readlane_b32 s42, v245, 61
	v_readlane_b32 s43, v245, 62
	s_mov_b32 s46, s34
	s_mov_b64 s[48:49], s[40:41]
	s_mov_b64 s[44:45], s[38:39]
	v_readlane_b32 s77, v245, 11
	v_readlane_b32 s82, v245, 16
	v_readlane_b32 s83, v245, 17
	v_readlane_b32 s84, v245, 18
	v_readlane_b32 s85, v245, 19
	v_readlane_b32 s86, v245, 20
	v_readlane_b32 s87, v245, 21
	v_readlane_b32 s88, v245, 22
	v_readlane_b32 s89, v245, 23
	v_readlane_b32 s90, v245, 24
	v_readlane_b32 s91, v245, 25
	s_waitcnt vmcnt(0)
; __device__ __forceinline__ u32x4 pack8f(f32x4 lo, f32x4 hi) { u32x4 w; w.x = cvtpk(lo[0], lo[1]); w.y = cvtpk(lo[2], lo[3]); w.z = cvtpk(hi[0], hi[1]); w.w = cvtpk(hi[2], hi[3]); return w; }
;     __device__ __forceinline__ void operator()(const Acc& acc, const Unit& u, int wr, int wc, int fr, int fq) const {
;     ...
;                 for (int m = 0; m < 4; ++m) { const int row = rowb + hf * 128 + m * 16; yv[m] = *(const u32x4*)(y1 + yb + (size_t)(hf * 128 + m * 16) * 256 + bj * 128); st[m] = *(const f32x2*)(stats + (size_t)row * 2); }
; #pragma unroll
;                 for (int m = 0; m < 4; ++m) { const int row = rowb + hf * 128 + m * 16;
;                     f32x4 lo, hi; unpack8(yv[m], lo, hi); const float r = st[m][1], mr = st[m][0] * r;
;                     lo = (lo * r - mr) * G[0] + Bc[0] + gm[0] * acc[hf][bj][m][0]; hi = (hi * r - mr) * G[1] + Bc[1] + gm[1] * acc[hf][bj][m][1];
;                     *(u32x4*)(y2 + yb + (size_t)(hf * 128 + m * 16) * 256 + bj * 128) = pack8f(lo, hi); }
;                 asm volatile("" ::: "memory");
	v_pk_mul_f32 v[162:163], v[166:167], s[28:29] op_sel_hi:[1,0]
	v_pk_mul_f32 v[166:167], v[184:185], s[28:29] op_sel_hi:[1,0]
	v_pk_mul_f32 v[178:179], v[194:195], s[28:29] op_sel_hi:[1,0]
	v_pk_mul_f32 v[180:181], v[192:193], s[28:29] op_sel_hi:[1,0]
	v_pk_add_f32 v[184:185], v[200:201], 1.0 op_sel_hi:[1,0]
	v_lshlrev_b32_e32 v192, 16, v204
	v_and_b32_e32 v193, 0xffff0000, v204
	v_lshlrev_b32_e32 v194, 16, v205
	v_and_b32_e32 v195, 0xffff0000, v205
	v_pk_mul_f32 v[200:201], v[222:223], v[222:223] op_sel:[0,1] op_sel_hi:[1,0]
	v_pk_mul_f32 v[174:175], v[170:171], s[28:29] op_sel_hi:[1,0]
	v_pk_mul_f32 v[176:177], v[168:169], s[28:29] op_sel_hi:[1,0]
	v_pk_fma_f32 v[192:193], v[222:223], v[192:193], v[200:201] op_sel:[1,0,0] op_sel_hi:[1,1,0] neg_lo:[0,0,1] neg_hi:[0,0,1]
	v_pk_fma_f32 v[194:195], v[222:223], v[194:195], v[200:201] op_sel:[1,0,0] op_sel_hi:[1,1,0] neg_lo:[0,0,1] neg_hi:[0,0,1]
	v_pk_mul_f32 v[172:173], v[182:183], s[28:29] op_sel_hi:[1,0]
	v_pk_add_f32 v[182:183], v[202:203], 1.0 op_sel_hi:[1,0]
	v_pk_add_f32 v[168:169], v[198:199], 1.0 op_sel_hi:[1,0]
	v_pk_add_f32 v[170:171], v[196:197], 1.0 op_sel_hi:[1,0]
	v_lshlrev_b32_e32 v196, 16, v206
	v_and_b32_e32 v197, 0xffff0000, v206
	v_lshlrev_b32_e32 v198, 16, v207
	v_and_b32_e32 v199, 0xffff0000, v207
	v_pk_fma_f32 v[194:195], v[174:175], v[194:195], v[178:179]
	v_pk_fma_f32 v[192:193], v[176:177], v[192:193], v[180:181]
	v_pk_mul_f32 v[164:165], v[164:165], s[28:29] op_sel_hi:[1,0]
	v_pk_fma_f32 v[126:127], v[126:127], v[182:183], v[194:195]
	v_pk_fma_f32 v[124:125], v[124:125], v[184:185], v[192:193]
	v_pk_fma_f32 v[192:193], v[222:223], v[196:197], v[200:201] op_sel:[1,0,0] op_sel_hi:[1,1,0] neg_lo:[0,0,1] neg_hi:[0,0,1]
	v_pk_fma_f32 v[194:195], v[222:223], v[198:199], v[200:201] op_sel:[1,0,0] op_sel_hi:[1,1,0] neg_lo:[0,0,1] neg_hi:[0,0,1]
	v_pk_fma_f32 v[192:193], v[164:165], v[192:193], v[172:173]
	v_pk_fma_f32 v[194:195], v[162:163], v[194:195], v[166:167]
	v_pk_fma_f32 v[120:121], v[120:121], v[170:171], v[192:193]
	v_pk_fma_f32 v[194:195], v[122:123], v[168:169], v[194:195]
	v_cvt_pk_bf16_f32 v122, v124, v125
	v_cvt_pk_bf16_f32 v123, v126, v127
	v_cvt_pk_bf16_f32 v124, v120, v121
	v_cvt_pk_bf16_f32 v125, v194, v195
	v_lshl_add_u64 v[120:121], s[42:43], 0, v[220:221]
	global_store_dwordx4 v[120:121], v[122:125], off
	v_pk_mul_f32 v[194:195], v[224:225], v[224:225] op_sel:[0,1] op_sel_hi:[1,0]
	v_lshlrev_b32_e32 v126, 16, v210
	v_lshlrev_b32_e32 v124, 16, v209
	v_and_b32_e32 v125, 0xffff0000, v209
	v_lshlrev_b32_e32 v122, 16, v208
	v_and_b32_e32 v123, 0xffff0000, v208
	v_pk_fma_f32 v[124:125], v[224:225], v[124:125], v[194:195] op_sel:[1,0,0] op_sel_hi:[1,1,0] neg_lo:[0,0,1] neg_hi:[0,0,1]
	v_and_b32_e32 v127, 0xffff0000, v210
	v_pk_fma_f32 v[122:123], v[224:225], v[122:123], v[194:195] op_sel:[1,0,0] op_sel_hi:[1,1,0] neg_lo:[0,0,1] neg_hi:[0,0,1]
	v_pk_fma_f32 v[124:125], v[174:175], v[124:125], v[178:179]
	v_lshlrev_b32_e32 v192, 16, v211
	v_and_b32_e32 v193, 0xffff0000, v211
	v_pk_fma_f32 v[122:123], v[176:177], v[122:123], v[180:181]
	v_pk_fma_f32 v[118:119], v[118:119], v[182:183], v[124:125]
	v_pk_fma_f32 v[124:125], v[224:225], v[126:127], v[194:195] op_sel:[1,0,0] op_sel_hi:[1,1,0] neg_lo:[0,0,1] neg_hi:[0,0,1]
	v_pk_fma_f32 v[116:117], v[116:117], v[184:185], v[122:123]
	v_pk_fma_f32 v[122:123], v[224:225], v[192:193], v[194:195] op_sel:[1,0,0] op_sel_hi:[1,1,0] neg_lo:[0,0,1] neg_hi:[0,0,1]
	v_pk_fma_f32 v[124:125], v[164:165], v[124:125], v[172:173]
	v_pk_fma_f32 v[122:123], v[162:163], v[122:123], v[166:167]
	v_pk_fma_f32 v[112:113], v[112:113], v[170:171], v[124:125]
	v_pk_fma_f32 v[122:123], v[114:115], v[168:169], v[122:123]
	v_cvt_pk_bf16_f32 v114, v116, v117
	v_cvt_pk_bf16_f32 v116, v112, v113
	v_add_co_u32_e32 v112, vcc, s66, v120
	v_cvt_pk_bf16_f32 v115, v118, v119
	v_cvt_pk_bf16_f32 v117, v122, v123
	v_addc_co_u32_e32 v113, vcc, 0, v121, vcc
	global_store_dwordx4 v[112:113], v[114:117], off
	v_pk_mul_f32 v[124:125], v[226:227], v[226:227] op_sel:[0,1] op_sel_hi:[1,0]
	v_lshlrev_b32_e32 v118, 16, v214
	v_lshlrev_b32_e32 v116, 16, v213
	v_and_b32_e32 v117, 0xffff0000, v213
	v_lshlrev_b32_e32 v114, 16, v212
	v_and_b32_e32 v115, 0xffff0000, v212
	v_pk_fma_f32 v[116:117], v[226:227], v[116:117], v[124:125] op_sel:[1,0,0] op_sel_hi:[1,1,0] neg_lo:[0,0,1] neg_hi:[0,0,1]
	v_and_b32_e32 v119, 0xffff0000, v214
	v_pk_fma_f32 v[114:115], v[226:227], v[114:115], v[124:125] op_sel:[1,0,0] op_sel_hi:[1,1,0] neg_lo:[0,0,1] neg_hi:[0,0,1]
	v_pk_fma_f32 v[116:117], v[174:175], v[116:117], v[178:179]
	v_lshlrev_b32_e32 v122, 16, v215
	v_and_b32_e32 v123, 0xffff0000, v215
	v_pk_fma_f32 v[114:115], v[176:177], v[114:115], v[180:181]
	v_pk_fma_f32 v[110:111], v[110:111], v[182:183], v[116:117]
	v_pk_fma_f32 v[116:117], v[226:227], v[118:119], v[124:125] op_sel:[1,0,0] op_sel_hi:[1,1,0] neg_lo:[0,0,1] neg_hi:[0,0,1]
	v_pk_fma_f32 v[108:109], v[108:109], v[184:185], v[114:115]
	v_pk_fma_f32 v[114:115], v[226:227], v[122:123], v[124:125] op_sel:[1,0,0] op_sel_hi:[1,1,0] neg_lo:[0,0,1] neg_hi:[0,0,1]
	v_pk_fma_f32 v[116:117], v[164:165], v[116:117], v[172:173]
	v_pk_fma_f32 v[114:115], v[162:163], v[114:115], v[166:167]
	v_pk_fma_f32 v[104:105], v[104:105], v[170:171], v[116:117]
	v_pk_fma_f32 v[114:115], v[106:107], v[168:169], v[114:115]
	v_cvt_pk_bf16_f32 v106, v108, v109
	v_cvt_pk_bf16_f32 v108, v104, v105
	v_add_co_u32_e32 v104, vcc, s67, v120
	v_cvt_pk_bf16_f32 v107, v110, v111
	v_cvt_pk_bf16_f32 v109, v114, v115
	v_addc_co_u32_e32 v105, vcc, 0, v121, vcc
	global_store_dwordx4 v[104:105], v[106:109], off
	v_pk_mul_f32 v[116:117], v[228:229], v[228:229] op_sel:[0,1] op_sel_hi:[1,0]
; __device__ __forceinline__ u32x4 pack8f(f32x4 lo, f32x4 hi) { u32x4 w; w.x = cvtpk(lo[0], lo[1]); w.y = cvtpk(lo[2], lo[3]); w.z = cvtpk(hi[0], hi[1]); w.w = cvtpk(hi[2], hi[3]); return w; }
;     __device__ __forceinline__ void operator()(const Acc& acc, const Unit& u, int wr, int wc, int fr, int fq) const {
;     ...
;                 for (int m = 0; m < 4; ++m) { const int row = rowb + hf * 128 + m * 16; yv[m] = *(const u32x4*)(y1 + yb + (size_t)(hf * 128 + m * 16) * 256 + bj * 128); st[m] = *(const f32x2*)(stats + (size_t)row * 2); }
; #pragma unroll
;                 for (int m = 0; m < 4; ++m) { const int row = rowb + hf * 128 + m * 16;
;                     f32x4 lo, hi; unpack8(yv[m], lo, hi); const float r = st[m][1], mr = st[m][0] * r;
;                     lo = (lo * r - mr) * G[0] + Bc[0] + gm[0] * acc[hf][bj][m][0]; hi = (hi * r - mr) * G[1] + Bc[1] + gm[1] * acc[hf][bj][m][1];
;                     *(u32x4*)(y2 + yb + (size_t)(hf * 128 + m * 16) * 256 + bj * 128) = pack8f(lo, hi); }
;                 asm volatile("" ::: "memory");
	v_lshlrev_b32_e32 v110, 16, v218
	v_lshlrev_b32_e32 v108, 16, v217
	v_and_b32_e32 v109, 0xffff0000, v217
	v_lshlrev_b32_e32 v106, 16, v216
	v_and_b32_e32 v107, 0xffff0000, v216
	v_pk_fma_f32 v[108:109], v[228:229], v[108:109], v[116:117] op_sel:[1,0,0] op_sel_hi:[1,1,0] neg_lo:[0,0,1] neg_hi:[0,0,1]
	v_and_b32_e32 v111, 0xffff0000, v218
	v_pk_fma_f32 v[106:107], v[228:229], v[106:107], v[116:117] op_sel:[1,0,0] op_sel_hi:[1,1,0] neg_lo:[0,0,1] neg_hi:[0,0,1]
	v_pk_fma_f32 v[108:109], v[174:175], v[108:109], v[178:179]
	v_lshlrev_b32_e32 v114, 16, v219
	v_and_b32_e32 v115, 0xffff0000, v219
	v_pk_fma_f32 v[106:107], v[176:177], v[106:107], v[180:181]
	v_pk_fma_f32 v[102:103], v[102:103], v[182:183], v[108:109]
	v_pk_fma_f32 v[108:109], v[228:229], v[110:111], v[116:117] op_sel:[1,0,0] op_sel_hi:[1,1,0] neg_lo:[0,0,1] neg_hi:[0,0,1]
	v_pk_fma_f32 v[100:101], v[100:101], v[184:185], v[106:107]
	v_pk_fma_f32 v[106:107], v[228:229], v[114:115], v[116:117] op_sel:[1,0,0] op_sel_hi:[1,1,0] neg_lo:[0,0,1] neg_hi:[0,0,1]
	v_pk_fma_f32 v[108:109], v[164:165], v[108:109], v[172:173]
	v_pk_fma_f32 v[106:107], v[162:163], v[106:107], v[166:167]
	v_pk_fma_f32 v[96:97], v[96:97], v[170:171], v[108:109]
	v_pk_fma_f32 v[106:107], v[98:99], v[168:169], v[106:107]
	v_cvt_pk_bf16_f32 v98, v100, v101
	v_cvt_pk_bf16_f32 v100, v96, v97
	v_add_co_u32_e32 v96, vcc, s68, v120
	v_cvt_pk_bf16_f32 v99, v102, v103
	v_cvt_pk_bf16_f32 v101, v106, v107
	v_addc_co_u32_e32 v97, vcc, 0, v121, vcc
	global_store_dwordx4 v[96:97], v[98:101], off
	s_mov_b32 s42, s36
	s_nop 0
	v_add_co_u32_e32 v98, vcc, s62, v148
	s_nop 1
	v_addc_co_u32_e32 v99, vcc, 0, v149, vcc
	global_load_dwordx4 v[108:111], v[98:99], off nt
	global_load_dwordx2 v[118:119], v[140:141], off offset:1024
	v_add_co_u32_e32 v100, vcc, s63, v148
	s_waitcnt vmcnt(1)
	v_lshlrev_b32_e32 v200, 16, v108
	v_addc_co_u32_e32 v101, vcc, 0, v149, vcc
	global_load_dwordx4 v[114:117], v[100:101], off nt
	global_load_dwordx2 v[126:127], v[140:141], off offset:1152
	v_add_co_u32_e32 v102, vcc, s64, v148
	v_and_b32_e32 v201, 0xffff0000, v108
	s_nop 0
	v_addc_co_u32_e32 v103, vcc, 0, v149, vcc
	global_load_dwordx4 v[122:125], v[102:103], off nt
	global_load_dwordx2 v[196:197], v[140:141], off offset:1280
	v_add_co_u32_e32 v106, vcc, s65, v148
	v_lshlrev_b32_e32 v108, 16, v109
	s_nop 0
	v_addc_co_u32_e32 v107, vcc, 0, v149, vcc
	global_load_dwordx4 v[192:195], v[106:107], off nt
	global_load_dwordx2 v[198:199], v[140:141], off offset:1408
	v_and_b32_e32 v109, 0xffff0000, v109
	s_waitcnt vmcnt(6)
	v_pk_mul_f32 v[204:205], v[118:119], v[118:119] op_sel:[0,1] op_sel_hi:[1,0]
	v_lshlrev_b32_e32 v202, 16, v110
	v_pk_fma_f32 v[108:109], v[118:119], v[108:109], v[204:205] op_sel:[1,0,0] op_sel_hi:[1,1,0] neg_lo:[0,0,1] neg_hi:[0,0,1]
	v_and_b32_e32 v203, 0xffff0000, v110
	v_lshlrev_b32_e32 v110, 16, v111
	v_and_b32_e32 v111, 0xffff0000, v111
	v_pk_fma_f32 v[108:109], v[174:175], v[108:109], v[178:179]
	v_pk_fma_f32 v[200:201], v[118:119], v[200:201], v[204:205] op_sel:[1,0,0] op_sel_hi:[1,1,0] neg_lo:[0,0,1] neg_hi:[0,0,1]
	v_pk_fma_f32 v[94:95], v[94:95], v[182:183], v[108:109]
	v_pk_fma_f32 v[108:109], v[118:119], v[110:111], v[204:205] op_sel:[1,0,0] op_sel_hi:[1,1,0] neg_lo:[0,0,1] neg_hi:[0,0,1]
	v_pk_fma_f32 v[110:111], v[118:119], v[202:203], v[204:205] op_sel:[1,0,0] op_sel_hi:[1,1,0] neg_lo:[0,0,1] neg_hi:[0,0,1]
	v_pk_fma_f32 v[200:201], v[176:177], v[200:201], v[180:181]
	v_pk_fma_f32 v[110:111], v[164:165], v[110:111], v[172:173]
	v_pk_fma_f32 v[92:93], v[92:93], v[184:185], v[200:201]
	v_pk_fma_f32 v[108:109], v[162:163], v[108:109], v[166:167]
	v_pk_fma_f32 v[88:89], v[88:89], v[170:171], v[110:111]
	v_pk_fma_f32 v[108:109], v[90:91], v[168:169], v[108:109]
	v_cvt_pk_bf16_f32 v90, v92, v93
	v_cvt_pk_bf16_f32 v92, v88, v89
	v_add_co_u32_e32 v88, vcc, s62, v120
	v_cvt_pk_bf16_f32 v91, v94, v95
	v_cvt_pk_bf16_f32 v93, v108, v109
	v_addc_co_u32_e32 v89, vcc, 0, v121, vcc
	global_store_dwordx4 v[88:89], v[90:93], off
	s_waitcnt vmcnt(6)
	v_lshlrev_b32_e32 v94, 16, v116
	v_lshlrev_b32_e32 v92, 16, v115
	v_and_b32_e32 v93, 0xffff0000, v115
	s_waitcnt vmcnt(5)
	v_pk_mul_f32 v[110:111], v[126:127], v[126:127] op_sel:[0,1] op_sel_hi:[1,0]
	v_lshlrev_b32_e32 v90, 16, v114
	v_and_b32_e32 v91, 0xffff0000, v114
	v_pk_fma_f32 v[92:93], v[126:127], v[92:93], v[110:111] op_sel:[1,0,0] op_sel_hi:[1,1,0] neg_lo:[0,0,1] neg_hi:[0,0,1]
	v_and_b32_e32 v95, 0xffff0000, v116
	v_pk_fma_f32 v[90:91], v[126:127], v[90:91], v[110:111] op_sel:[1,0,0] op_sel_hi:[1,1,0] neg_lo:[0,0,1] neg_hi:[0,0,1]
	v_pk_fma_f32 v[92:93], v[174:175], v[92:93], v[178:179]
	v_lshlrev_b32_e32 v108, 16, v117
	v_and_b32_e32 v109, 0xffff0000, v117
	v_pk_fma_f32 v[90:91], v[176:177], v[90:91], v[180:181]
	v_pk_fma_f32 v[86:87], v[86:87], v[182:183], v[92:93]
	v_pk_fma_f32 v[92:93], v[126:127], v[94:95], v[110:111] op_sel:[1,0,0] op_sel_hi:[1,1,0] neg_lo:[0,0,1] neg_hi:[0,0,1]
	v_pk_fma_f32 v[84:85], v[84:85], v[184:185], v[90:91]
	v_pk_fma_f32 v[90:91], v[126:127], v[108:109], v[110:111] op_sel:[1,0,0] op_sel_hi:[1,1,0] neg_lo:[0,0,1] neg_hi:[0,0,1]
	v_pk_fma_f32 v[92:93], v[164:165], v[92:93], v[172:173]
	v_pk_fma_f32 v[90:91], v[162:163], v[90:91], v[166:167]
	v_pk_fma_f32 v[80:81], v[80:81], v[170:171], v[92:93]
	v_pk_fma_f32 v[90:91], v[82:83], v[168:169], v[90:91]
	v_cvt_pk_bf16_f32 v82, v84, v85
	v_cvt_pk_bf16_f32 v84, v80, v81
	v_add_co_u32_e32 v80, vcc, s63, v120
	v_cvt_pk_bf16_f32 v83, v86, v87
	v_cvt_pk_bf16_f32 v85, v90, v91
	v_addc_co_u32_e32 v81, vcc, 0, v121, vcc
	global_store_dwordx4 v[80:81], v[82:85], off
	s_waitcnt vmcnt(4)
; __device__ __forceinline__ u32x4 pack8f(f32x4 lo, f32x4 hi) { u32x4 w; w.x = cvtpk(lo[0], lo[1]); w.y = cvtpk(lo[2], lo[3]); w.z = cvtpk(hi[0], hi[1]); w.w = cvtpk(hi[2], hi[3]); return w; }
;     __device__ __forceinline__ void operator()(const Acc& acc, const Unit& u, int wr, int wc, int fr, int fq) const {
;     ...
;         for (int bj = 0; bj < 2; ++bj) {
;             f32x4 gm[2], G[2], Bc[2];
; #pragma unroll
;             for (int n = 0; n < 2; ++n) { const int c = col0 + bj * 128 + n * 4; gm[n] = *(const f32x4*)(gate + (size_t)b * NADA + c) + 1.0f; G[n] = *(const f32x4*)(lg + c) * ALPHA; Bc[n] = *(const f32x4*)(lb + c) * ALPHA; }
; #pragma unroll
;             for (int hf = 0; hf < 2; ++hf) {
;                 u32x4 yv[4]; f32x2 st[4];
; #pragma unroll
;                 for (int m = 0; m < 4; ++m) { const int row = rowb + hf * 128 + m * 16; yv[m] = *(const u32x4*)(y1 + yb + (size_t)(hf * 128 + m * 16) * 256 + bj * 128); st[m] = *(const f32x2*)(stats + (size_t)row * 2); }
; #pragma unroll
;                 for (int m = 0; m < 4; ++m) { const int row = rowb + hf * 128 + m * 16;
;                     f32x4 lo, hi; unpack8(yv[m], lo, hi); const float r = st[m][1], mr = st[m][0] * r;
;                     lo = (lo * r - mr) * G[0] + Bc[0] + gm[0] * acc[hf][bj][m][0]; hi = (hi * r - mr) * G[1] + Bc[1] + gm[1] * acc[hf][bj][m][1];
;                     *(u32x4*)(y2 + yb + (size_t)(hf * 128 + m * 16) * 256 + bj * 128) = pack8f(lo, hi); }
;                 asm volatile("" ::: "memory");
	v_pk_mul_f32 v[92:93], v[196:197], v[196:197] op_sel:[0,1] op_sel_hi:[1,0]
	v_lshlrev_b32_e32 v86, 16, v124
	v_lshlrev_b32_e32 v84, 16, v123
	v_and_b32_e32 v85, 0xffff0000, v123
	v_lshlrev_b32_e32 v82, 16, v122
	v_and_b32_e32 v83, 0xffff0000, v122
	v_pk_fma_f32 v[84:85], v[196:197], v[84:85], v[92:93] op_sel:[1,0,0] op_sel_hi:[1,1,0] neg_lo:[0,0,1] neg_hi:[0,0,1]
	v_and_b32_e32 v87, 0xffff0000, v124
	v_pk_fma_f32 v[82:83], v[196:197], v[82:83], v[92:93] op_sel:[1,0,0] op_sel_hi:[1,1,0] neg_lo:[0,0,1] neg_hi:[0,0,1]
	v_pk_fma_f32 v[84:85], v[174:175], v[84:85], v[178:179]
	v_lshlrev_b32_e32 v90, 16, v125
	v_and_b32_e32 v91, 0xffff0000, v125
	v_pk_fma_f32 v[82:83], v[176:177], v[82:83], v[180:181]
	v_pk_fma_f32 v[78:79], v[78:79], v[182:183], v[84:85]
	v_pk_fma_f32 v[84:85], v[196:197], v[86:87], v[92:93] op_sel:[1,0,0] op_sel_hi:[1,1,0] neg_lo:[0,0,1] neg_hi:[0,0,1]
	v_pk_fma_f32 v[76:77], v[76:77], v[184:185], v[82:83]
	v_pk_fma_f32 v[82:83], v[196:197], v[90:91], v[92:93] op_sel:[1,0,0] op_sel_hi:[1,1,0] neg_lo:[0,0,1] neg_hi:[0,0,1]
	v_pk_fma_f32 v[84:85], v[164:165], v[84:85], v[172:173]
	v_pk_fma_f32 v[82:83], v[162:163], v[82:83], v[166:167]
	v_pk_fma_f32 v[72:73], v[72:73], v[170:171], v[84:85]
	v_pk_fma_f32 v[82:83], v[74:75], v[168:169], v[82:83]
	v_cvt_pk_bf16_f32 v74, v76, v77
	v_cvt_pk_bf16_f32 v76, v72, v73
	v_add_co_u32_e32 v72, vcc, s64, v120
	v_cvt_pk_bf16_f32 v75, v78, v79
	v_cvt_pk_bf16_f32 v77, v82, v83
	v_addc_co_u32_e32 v73, vcc, 0, v121, vcc
	global_store_dwordx4 v[72:73], v[74:77], off
	s_waitcnt vmcnt(3)
	v_pk_mul_f32 v[84:85], v[198:199], v[198:199] op_sel:[0,1] op_sel_hi:[1,0]
	v_lshlrev_b32_e32 v78, 16, v194
	v_lshlrev_b32_e32 v76, 16, v193
	v_and_b32_e32 v77, 0xffff0000, v193
	v_lshlrev_b32_e32 v74, 16, v192
	v_and_b32_e32 v75, 0xffff0000, v192
	v_pk_fma_f32 v[76:77], v[198:199], v[76:77], v[84:85] op_sel:[1,0,0] op_sel_hi:[1,1,0] neg_lo:[0,0,1] neg_hi:[0,0,1]
	v_and_b32_e32 v79, 0xffff0000, v194
	v_pk_fma_f32 v[74:75], v[198:199], v[74:75], v[84:85] op_sel:[1,0,0] op_sel_hi:[1,1,0] neg_lo:[0,0,1] neg_hi:[0,0,1]
	v_pk_fma_f32 v[76:77], v[174:175], v[76:77], v[178:179]
	v_lshlrev_b32_e32 v82, 16, v195
	v_and_b32_e32 v83, 0xffff0000, v195
	v_pk_fma_f32 v[74:75], v[176:177], v[74:75], v[180:181]
	v_pk_fma_f32 v[70:71], v[70:71], v[182:183], v[76:77]
	v_pk_fma_f32 v[76:77], v[198:199], v[78:79], v[84:85] op_sel:[1,0,0] op_sel_hi:[1,1,0] neg_lo:[0,0,1] neg_hi:[0,0,1]
	v_pk_fma_f32 v[68:69], v[68:69], v[184:185], v[74:75]
	v_pk_fma_f32 v[74:75], v[198:199], v[82:83], v[84:85] op_sel:[1,0,0] op_sel_hi:[1,1,0] neg_lo:[0,0,1] neg_hi:[0,0,1]
	v_pk_fma_f32 v[76:77], v[164:165], v[76:77], v[172:173]
	v_pk_fma_f32 v[74:75], v[162:163], v[74:75], v[166:167]
	v_pk_fma_f32 v[64:65], v[64:65], v[170:171], v[76:77]
	v_pk_fma_f32 v[74:75], v[66:67], v[168:169], v[74:75]
	v_cvt_pk_bf16_f32 v66, v68, v69
	v_cvt_pk_bf16_f32 v68, v64, v65
	v_add_co_u32_e32 v64, vcc, s65, v120
	v_cvt_pk_bf16_f32 v67, v70, v71
	v_cvt_pk_bf16_f32 v69, v74, v75
	v_addc_co_u32_e32 v65, vcc, 0, v121, vcc
	global_store_dwordx4 v[64:65], v[66:69], off
	global_load_dwordx4 v[66:69], v[146:147], off offset:512
	global_load_dwordx4 v[82:85], v[142:143], off offset:512
	global_load_dwordx4 v[108:111], v[144:145], off offset:512
	global_load_dwordx4 v[114:117], v[146:147], off offset:528
	global_load_dwordx4 v[122:125], v[142:143], off offset:528
	s_nop 0
	global_load_dwordx4 v[142:145], v[144:145], off offset:528
	s_nop 0
	global_load_dwordx4 v[146:149], v[148:149], off offset:256 nt
	s_nop 0
	global_load_dwordx2 v[118:119], v[140:141], off
	global_load_dwordx4 v[162:165], v[150:151], off offset:256 nt
	global_load_dwordx2 v[126:127], v[152:153], off
	s_nop 0
	global_load_dwordx4 v[150:153], v[158:159], off offset:256 nt
	s_nop 0
	global_load_dwordx2 v[158:159], v[160:161], off
	s_and_b64 vcc, exec, s[2:3]
	s_waitcnt vmcnt(11)
	v_pk_add_f32 v[74:75], v[68:69], 1.0 op_sel_hi:[1,0]
	v_pk_add_f32 v[76:77], v[66:67], 1.0 op_sel_hi:[1,0]
	s_waitcnt vmcnt(9)
	v_pk_mul_f32 v[92:93], v[110:111], s[28:29] op_sel_hi:[1,0]
	v_pk_mul_f32 v[94:95], v[108:109], s[28:29] op_sel_hi:[1,0]
	s_waitcnt vmcnt(8)
	v_pk_add_f32 v[68:69], v[114:115], 1.0 op_sel_hi:[1,0]
	global_load_dwordx4 v[108:111], v[156:157], off offset:256 nt
	global_load_dwordx2 v[114:115], v[154:155], off
	v_pk_mul_f32 v[90:91], v[82:83], s[28:29] op_sel_hi:[1,0]
	v_pk_add_f32 v[66:67], v[116:117], 1.0 op_sel_hi:[1,0]
	s_waitcnt vmcnt(8)
	v_pk_mul_f32 v[82:83], v[144:145], s[28:29] op_sel_hi:[1,0]
	s_waitcnt vmcnt(7)
	v_lshlrev_b32_e32 v116, 16, v146
	v_and_b32_e32 v117, 0xffff0000, v146
	s_waitcnt vmcnt(6)
	v_pk_mul_f32 v[144:145], v[118:119], v[118:119] op_sel:[0,1] op_sel_hi:[1,0]
	v_pk_mul_f32 v[86:87], v[84:85], s[28:29] op_sel_hi:[1,0]
	v_pk_fma_f32 v[116:117], v[118:119], v[116:117], v[144:145] op_sel:[1,0,0] op_sel_hi:[1,1,0] neg_lo:[0,0,1] neg_hi:[0,0,1]
	v_pk_mul_f32 v[70:71], v[124:125], s[28:29] op_sel_hi:[1,0]
	v_pk_mul_f32 v[78:79], v[122:123], s[28:29] op_sel_hi:[1,0]
	v_pk_mul_f32 v[84:85], v[142:143], s[28:29] op_sel_hi:[1,0]
	v_lshlrev_b32_e32 v122, 16, v147
	v_and_b32_e32 v123, 0xffff0000, v147
	v_lshlrev_b32_e32 v124, 16, v148
	v_and_b32_e32 v125, 0xffff0000, v148
	v_lshlrev_b32_e32 v142, 16, v149
	v_and_b32_e32 v143, 0xffff0000, v149
	v_pk_fma_f32 v[116:117], v[90:91], v[116:117], v[94:95]
	v_pk_fma_f32 v[122:123], v[118:119], v[122:123], v[144:145] op_sel:[1,0,0] op_sel_hi:[1,1,0] neg_lo:[0,0,1] neg_hi:[0,0,1]
	v_pk_fma_f32 v[60:61], v[60:61], v[76:77], v[116:117]
	v_pk_fma_f32 v[116:117], v[118:119], v[124:125], v[144:145] op_sel:[1,0,0] op_sel_hi:[1,1,0] neg_lo:[0,0,1] neg_hi:[0,0,1]
	v_pk_fma_f32 v[118:119], v[118:119], v[142:143], v[144:145] op_sel:[1,0,0] op_sel_hi:[1,1,0] neg_lo:[0,0,1] neg_hi:[0,0,1]
	v_pk_fma_f32 v[122:123], v[86:87], v[122:123], v[92:93]
	v_pk_fma_f32 v[118:119], v[70:71], v[118:119], v[82:83]
	v_pk_fma_f32 v[116:117], v[78:79], v[116:117], v[84:85]
	v_pk_fma_f32 v[62:63], v[62:63], v[74:75], v[122:123]
	v_pk_fma_f32 v[118:119], v[58:59], v[66:67], v[118:119]
	v_pk_fma_f32 v[58:59], v[56:57], v[68:69], v[116:117]
	v_cvt_pk_bf16_f32 v56, v60, v61
	v_cvt_pk_bf16_f32 v57, v62, v63
	v_cvt_pk_bf16_f32 v58, v58, v59
	v_cvt_pk_bf16_f32 v59, v118, v119
	global_store_dwordx4 v[120:121], v[56:59], off offset:256
	s_waitcnt vmcnt(5)
; __device__ __forceinline__ u32x4 pack8f(f32x4 lo, f32x4 hi) { u32x4 w; w.x = cvtpk(lo[0], lo[1]); w.y = cvtpk(lo[2], lo[3]); w.z = cvtpk(hi[0], hi[1]); w.w = cvtpk(hi[2], hi[3]); return w; }
;     __device__ __forceinline__ void operator()(const Acc& acc, const Unit& u, int wr, int wc, int fr, int fq) const {
;     ...
;             for (int hf = 0; hf < 2; ++hf) {
;                 u32x4 yv[4]; f32x2 st[4];
; #pragma unroll
;                 for (int m = 0; m < 4; ++m) { const int row = rowb + hf * 128 + m * 16; yv[m] = *(const u32x4*)(y1 + yb + (size_t)(hf * 128 + m * 16) * 256 + bj * 128); st[m] = *(const f32x2*)(stats + (size_t)row * 2); }
; #pragma unroll
;                 for (int m = 0; m < 4; ++m) { const int row = rowb + hf * 128 + m * 16;
;                     f32x4 lo, hi; unpack8(yv[m], lo, hi); const float r = st[m][1], mr = st[m][0] * r;
;                     lo = (lo * r - mr) * G[0] + Bc[0] + gm[0] * acc[hf][bj][m][0]; hi = (hi * r - mr) * G[1] + Bc[1] + gm[1] * acc[hf][bj][m][1];
;                     *(u32x4*)(y2 + yb + (size_t)(hf * 128 + m * 16) * 256 + bj * 128) = pack8f(lo, hi); }
;                 asm volatile("" ::: "memory");
	v_pk_mul_f32 v[116:117], v[126:127], v[126:127] op_sel:[0,1] op_sel_hi:[1,0]
	v_lshlrev_b32_e32 v60, 16, v164
	v_lshlrev_b32_e32 v56, 16, v162
	v_and_b32_e32 v57, 0xffff0000, v162
	v_lshlrev_b32_e32 v58, 16, v163
	v_and_b32_e32 v59, 0xffff0000, v163
	v_pk_fma_f32 v[58:59], v[126:127], v[58:59], v[116:117] op_sel:[1,0,0] op_sel_hi:[1,1,0] neg_lo:[0,0,1] neg_hi:[0,0,1]
	v_pk_fma_f32 v[56:57], v[126:127], v[56:57], v[116:117] op_sel:[1,0,0] op_sel_hi:[1,1,0] neg_lo:[0,0,1] neg_hi:[0,0,1]
	v_and_b32_e32 v61, 0xffff0000, v164
	v_lshlrev_b32_e32 v62, 16, v165
	v_and_b32_e32 v63, 0xffff0000, v165
	v_pk_fma_f32 v[56:57], v[90:91], v[56:57], v[94:95]
	v_pk_fma_f32 v[58:59], v[86:87], v[58:59], v[92:93]
	v_pk_fma_f32 v[52:53], v[52:53], v[76:77], v[56:57]
	v_pk_fma_f32 v[54:55], v[54:55], v[74:75], v[58:59]
	v_pk_fma_f32 v[56:57], v[126:127], v[62:63], v[116:117] op_sel:[1,0,0] op_sel_hi:[1,1,0] neg_lo:[0,0,1] neg_hi:[0,0,1]
	v_pk_fma_f32 v[58:59], v[126:127], v[60:61], v[116:117] op_sel:[1,0,0] op_sel_hi:[1,1,0] neg_lo:[0,0,1] neg_hi:[0,0,1]
	v_pk_fma_f32 v[56:57], v[70:71], v[56:57], v[82:83]
	v_pk_fma_f32 v[58:59], v[78:79], v[58:59], v[84:85]
	v_pk_fma_f32 v[56:57], v[50:51], v[66:67], v[56:57]
	v_pk_fma_f32 v[50:51], v[48:49], v[68:69], v[58:59]
	v_cvt_pk_bf16_f32 v48, v52, v53
	v_cvt_pk_bf16_f32 v49, v54, v55
	v_cvt_pk_bf16_f32 v50, v50, v51
	v_cvt_pk_bf16_f32 v51, v56, v57
	global_store_dwordx4 v[112:113], v[48:51], off offset:256
	s_waitcnt vmcnt(4)
	v_pk_mul_f32 v[56:57], v[158:159], v[158:159] op_sel:[0,1] op_sel_hi:[1,0]
	v_lshlrev_b32_e32 v52, 16, v152
	v_lshlrev_b32_e32 v48, 16, v150
	v_and_b32_e32 v49, 0xffff0000, v150
	v_lshlrev_b32_e32 v50, 16, v151
	v_and_b32_e32 v51, 0xffff0000, v151
	v_pk_fma_f32 v[50:51], v[158:159], v[50:51], v[56:57] op_sel:[1,0,0] op_sel_hi:[1,1,0] neg_lo:[0,0,1] neg_hi:[0,0,1]
	v_pk_fma_f32 v[48:49], v[158:159], v[48:49], v[56:57] op_sel:[1,0,0] op_sel_hi:[1,1,0] neg_lo:[0,0,1] neg_hi:[0,0,1]
	v_and_b32_e32 v53, 0xffff0000, v152
	v_lshlrev_b32_e32 v54, 16, v153
	v_and_b32_e32 v55, 0xffff0000, v153
	v_pk_fma_f32 v[48:49], v[90:91], v[48:49], v[94:95]
	v_pk_fma_f32 v[50:51], v[86:87], v[50:51], v[92:93]
	v_pk_fma_f32 v[44:45], v[44:45], v[76:77], v[48:49]
	v_pk_fma_f32 v[46:47], v[46:47], v[74:75], v[50:51]
	v_pk_fma_f32 v[48:49], v[158:159], v[54:55], v[56:57] op_sel:[1,0,0] op_sel_hi:[1,1,0] neg_lo:[0,0,1] neg_hi:[0,0,1]
	v_pk_fma_f32 v[50:51], v[158:159], v[52:53], v[56:57] op_sel:[1,0,0] op_sel_hi:[1,1,0] neg_lo:[0,0,1] neg_hi:[0,0,1]
	v_pk_fma_f32 v[48:49], v[70:71], v[48:49], v[82:83]
	v_pk_fma_f32 v[50:51], v[78:79], v[50:51], v[84:85]
	v_pk_fma_f32 v[48:49], v[42:43], v[66:67], v[48:49]
	v_pk_fma_f32 v[42:43], v[40:41], v[68:69], v[50:51]
	v_cvt_pk_bf16_f32 v40, v44, v45
	v_cvt_pk_bf16_f32 v41, v46, v47
	v_cvt_pk_bf16_f32 v42, v42, v43
	v_cvt_pk_bf16_f32 v43, v48, v49
	global_store_dwordx4 v[104:105], v[40:43], off offset:256
	s_waitcnt vmcnt(3)
	v_pk_mul_f32 v[48:49], v[114:115], v[114:115] op_sel:[0,1] op_sel_hi:[1,0]
	v_lshlrev_b32_e32 v44, 16, v110
	v_lshlrev_b32_e32 v40, 16, v108
	v_and_b32_e32 v41, 0xffff0000, v108
	v_lshlrev_b32_e32 v42, 16, v109
	v_and_b32_e32 v43, 0xffff0000, v109
	v_pk_fma_f32 v[42:43], v[114:115], v[42:43], v[48:49] op_sel:[1,0,0] op_sel_hi:[1,1,0] neg_lo:[0,0,1] neg_hi:[0,0,1]
	v_pk_fma_f32 v[40:41], v[114:115], v[40:41], v[48:49] op_sel:[1,0,0] op_sel_hi:[1,1,0] neg_lo:[0,0,1] neg_hi:[0,0,1]
	v_and_b32_e32 v45, 0xffff0000, v110
	v_lshlrev_b32_e32 v46, 16, v111
	v_and_b32_e32 v47, 0xffff0000, v111
	v_pk_fma_f32 v[40:41], v[90:91], v[40:41], v[94:95]
	v_pk_fma_f32 v[42:43], v[86:87], v[42:43], v[92:93]
	v_pk_fma_f32 v[36:37], v[36:37], v[76:77], v[40:41]
	v_pk_fma_f32 v[38:39], v[38:39], v[74:75], v[42:43]
	v_pk_fma_f32 v[40:41], v[114:115], v[46:47], v[48:49] op_sel:[1,0,0] op_sel_hi:[1,1,0] neg_lo:[0,0,1] neg_hi:[0,0,1]
	v_pk_fma_f32 v[42:43], v[114:115], v[44:45], v[48:49] op_sel:[1,0,0] op_sel_hi:[1,1,0] neg_lo:[0,0,1] neg_hi:[0,0,1]
	v_pk_fma_f32 v[40:41], v[70:71], v[40:41], v[82:83]
	v_pk_fma_f32 v[42:43], v[78:79], v[42:43], v[84:85]
	v_pk_fma_f32 v[40:41], v[34:35], v[66:67], v[40:41]
	v_pk_fma_f32 v[34:35], v[32:33], v[68:69], v[42:43]
	v_cvt_pk_bf16_f32 v32, v36, v37
	v_cvt_pk_bf16_f32 v33, v38, v39
	v_cvt_pk_bf16_f32 v34, v34, v35
	v_cvt_pk_bf16_f32 v35, v40, v41
	global_store_dwordx4 v[96:97], v[32:35], off offset:256
	global_load_dwordx4 v[32:35], v[98:99], off offset:256 nt
	global_load_dwordx2 v[48:49], v[140:141], off offset:1024
	global_load_dwordx4 v[36:39], v[100:101], off offset:256 nt
	global_load_dwordx2 v[50:51], v[140:141], off offset:1152
	global_load_dwordx4 v[40:43], v[102:103], off offset:256 nt
	global_load_dwordx2 v[52:53], v[140:141], off offset:1280
	global_load_dwordx4 v[44:47], v[106:107], off offset:256 nt
	global_load_dwordx2 v[54:55], v[140:141], off offset:1408
	s_waitcnt vmcnt(7)
	v_lshlrev_b32_e32 v56, 16, v32
	v_and_b32_e32 v57, 0xffff0000, v32
	v_lshlrev_b32_e32 v32, 16, v33
	v_and_b32_e32 v33, 0xffff0000, v33
	s_waitcnt vmcnt(6)
; __device__ __forceinline__ u32x4 pack8f(f32x4 lo, f32x4 hi) { u32x4 w; w.x = cvtpk(lo[0], lo[1]); w.y = cvtpk(lo[2], lo[3]); w.z = cvtpk(hi[0], hi[1]); w.w = cvtpk(hi[2], hi[3]); return w; }
;     __device__ __forceinline__ void operator()(const Acc& acc, const Unit& u, int wr, int wc, int fr, int fq) const {
;     ...
;                 for (int m = 0; m < 4; ++m) { const int row = rowb + hf * 128 + m * 16;
;                     f32x4 lo, hi; unpack8(yv[m], lo, hi); const float r = st[m][1], mr = st[m][0] * r;
;                     lo = (lo * r - mr) * G[0] + Bc[0] + gm[0] * acc[hf][bj][m][0]; hi = (hi * r - mr) * G[1] + Bc[1] + gm[1] * acc[hf][bj][m][1];
;                     *(u32x4*)(y2 + yb + (size_t)(hf * 128 + m * 16) * 256 + bj * 128) = pack8f(lo, hi); }
;                 asm volatile("" ::: "memory");
;             }
;             asm volatile("" ::: "memory");
;         }
;     }
	v_pk_mul_f32 v[60:61], v[48:49], v[48:49] op_sel:[0,1] op_sel_hi:[1,0]
	v_lshlrev_b32_e32 v58, 16, v34
	v_pk_fma_f32 v[32:33], v[48:49], v[32:33], v[60:61] op_sel:[1,0,0] op_sel_hi:[1,1,0] neg_lo:[0,0,1] neg_hi:[0,0,1]
	v_and_b32_e32 v59, 0xffff0000, v34
	v_lshlrev_b32_e32 v34, 16, v35
	v_and_b32_e32 v35, 0xffff0000, v35
	v_pk_fma_f32 v[32:33], v[86:87], v[32:33], v[92:93]
	v_pk_fma_f32 v[56:57], v[48:49], v[56:57], v[60:61] op_sel:[1,0,0] op_sel_hi:[1,1,0] neg_lo:[0,0,1] neg_hi:[0,0,1]
	v_pk_fma_f32 v[30:31], v[30:31], v[74:75], v[32:33]
	v_pk_fma_f32 v[32:33], v[48:49], v[34:35], v[60:61] op_sel:[1,0,0] op_sel_hi:[1,1,0] neg_lo:[0,0,1] neg_hi:[0,0,1]
	v_pk_fma_f32 v[34:35], v[48:49], v[58:59], v[60:61] op_sel:[1,0,0] op_sel_hi:[1,1,0] neg_lo:[0,0,1] neg_hi:[0,0,1]
	v_pk_fma_f32 v[56:57], v[90:91], v[56:57], v[94:95]
	v_pk_fma_f32 v[34:35], v[78:79], v[34:35], v[84:85]
	v_pk_fma_f32 v[32:33], v[70:71], v[32:33], v[82:83]
	v_pk_fma_f32 v[28:29], v[28:29], v[76:77], v[56:57]
	v_pk_fma_f32 v[32:33], v[26:27], v[66:67], v[32:33]
	v_pk_fma_f32 v[26:27], v[24:25], v[68:69], v[34:35]
	v_cvt_pk_bf16_f32 v24, v28, v29
	v_cvt_pk_bf16_f32 v25, v30, v31
	v_cvt_pk_bf16_f32 v26, v26, v27
	v_cvt_pk_bf16_f32 v27, v32, v33
	global_store_dwordx4 v[88:89], v[24:27], off offset:256
	s_waitcnt vmcnt(5)
	v_pk_mul_f32 v[32:33], v[50:51], v[50:51] op_sel:[0,1] op_sel_hi:[1,0]
	v_lshlrev_b32_e32 v28, 16, v38
	v_lshlrev_b32_e32 v24, 16, v36
	v_and_b32_e32 v25, 0xffff0000, v36
	v_lshlrev_b32_e32 v26, 16, v37
	v_and_b32_e32 v27, 0xffff0000, v37
	v_pk_fma_f32 v[26:27], v[50:51], v[26:27], v[32:33] op_sel:[1,0,0] op_sel_hi:[1,1,0] neg_lo:[0,0,1] neg_hi:[0,0,1]
	v_pk_fma_f32 v[24:25], v[50:51], v[24:25], v[32:33] op_sel:[1,0,0] op_sel_hi:[1,1,0] neg_lo:[0,0,1] neg_hi:[0,0,1]
	v_and_b32_e32 v29, 0xffff0000, v38
	v_lshlrev_b32_e32 v30, 16, v39
	v_and_b32_e32 v31, 0xffff0000, v39
	v_pk_fma_f32 v[24:25], v[90:91], v[24:25], v[94:95]
	v_pk_fma_f32 v[26:27], v[86:87], v[26:27], v[92:93]
	v_pk_fma_f32 v[20:21], v[20:21], v[76:77], v[24:25]
	v_pk_fma_f32 v[22:23], v[22:23], v[74:75], v[26:27]
	v_pk_fma_f32 v[24:25], v[50:51], v[30:31], v[32:33] op_sel:[1,0,0] op_sel_hi:[1,1,0] neg_lo:[0,0,1] neg_hi:[0,0,1]
	v_pk_fma_f32 v[26:27], v[50:51], v[28:29], v[32:33] op_sel:[1,0,0] op_sel_hi:[1,1,0] neg_lo:[0,0,1] neg_hi:[0,0,1]
	v_pk_fma_f32 v[24:25], v[70:71], v[24:25], v[82:83]
	v_pk_fma_f32 v[26:27], v[78:79], v[26:27], v[84:85]
	v_pk_fma_f32 v[24:25], v[18:19], v[66:67], v[24:25]
	v_pk_fma_f32 v[18:19], v[16:17], v[68:69], v[26:27]
	v_cvt_pk_bf16_f32 v16, v20, v21
	v_cvt_pk_bf16_f32 v17, v22, v23
	v_cvt_pk_bf16_f32 v18, v18, v19
	v_cvt_pk_bf16_f32 v19, v24, v25
	global_store_dwordx4 v[80:81], v[16:19], off offset:256
	s_waitcnt vmcnt(4)
	v_pk_mul_f32 v[24:25], v[52:53], v[52:53] op_sel:[0,1] op_sel_hi:[1,0]
	v_lshlrev_b32_e32 v20, 16, v42
	v_lshlrev_b32_e32 v16, 16, v40
	v_and_b32_e32 v17, 0xffff0000, v40
	v_lshlrev_b32_e32 v18, 16, v41
	v_and_b32_e32 v19, 0xffff0000, v41
	v_pk_fma_f32 v[18:19], v[52:53], v[18:19], v[24:25] op_sel:[1,0,0] op_sel_hi:[1,1,0] neg_lo:[0,0,1] neg_hi:[0,0,1]
	v_pk_fma_f32 v[16:17], v[52:53], v[16:17], v[24:25] op_sel:[1,0,0] op_sel_hi:[1,1,0] neg_lo:[0,0,1] neg_hi:[0,0,1]
	v_and_b32_e32 v21, 0xffff0000, v42
	v_lshlrev_b32_e32 v22, 16, v43
	v_and_b32_e32 v23, 0xffff0000, v43
	v_pk_fma_f32 v[16:17], v[90:91], v[16:17], v[94:95]
	v_pk_fma_f32 v[18:19], v[86:87], v[18:19], v[92:93]
	v_pk_fma_f32 v[12:13], v[12:13], v[76:77], v[16:17]
	v_pk_fma_f32 v[14:15], v[14:15], v[74:75], v[18:19]
	v_pk_fma_f32 v[16:17], v[52:53], v[22:23], v[24:25] op_sel:[1,0,0] op_sel_hi:[1,1,0] neg_lo:[0,0,1] neg_hi:[0,0,1]
	v_pk_fma_f32 v[18:19], v[52:53], v[20:21], v[24:25] op_sel:[1,0,0] op_sel_hi:[1,1,0] neg_lo:[0,0,1] neg_hi:[0,0,1]
	v_pk_fma_f32 v[16:17], v[70:71], v[16:17], v[82:83]
	v_pk_fma_f32 v[18:19], v[78:79], v[18:19], v[84:85]
	v_pk_fma_f32 v[16:17], v[10:11], v[66:67], v[16:17]
	v_pk_fma_f32 v[10:11], v[8:9], v[68:69], v[18:19]
	v_cvt_pk_bf16_f32 v8, v12, v13
	v_cvt_pk_bf16_f32 v9, v14, v15
	v_cvt_pk_bf16_f32 v10, v10, v11
	v_cvt_pk_bf16_f32 v11, v16, v17
	global_store_dwordx4 v[72:73], v[8:11], off offset:256
	s_waitcnt vmcnt(3)
	v_pk_mul_f32 v[16:17], v[54:55], v[54:55] op_sel:[0,1] op_sel_hi:[1,0]
	v_lshlrev_b32_e32 v12, 16, v46
	v_lshlrev_b32_e32 v8, 16, v44
	v_and_b32_e32 v9, 0xffff0000, v44
	v_lshlrev_b32_e32 v10, 16, v45
	v_and_b32_e32 v11, 0xffff0000, v45
	v_pk_fma_f32 v[10:11], v[54:55], v[10:11], v[16:17] op_sel:[1,0,0] op_sel_hi:[1,1,0] neg_lo:[0,0,1] neg_hi:[0,0,1]
	v_pk_fma_f32 v[8:9], v[54:55], v[8:9], v[16:17] op_sel:[1,0,0] op_sel_hi:[1,1,0] neg_lo:[0,0,1] neg_hi:[0,0,1]
	v_and_b32_e32 v13, 0xffff0000, v46
	v_lshlrev_b32_e32 v14, 16, v47
	v_and_b32_e32 v15, 0xffff0000, v47
	v_pk_fma_f32 v[8:9], v[90:91], v[8:9], v[94:95]
	v_pk_fma_f32 v[10:11], v[86:87], v[10:11], v[92:93]
	v_pk_fma_f32 v[4:5], v[4:5], v[76:77], v[8:9]
	v_pk_fma_f32 v[6:7], v[6:7], v[74:75], v[10:11]
	v_pk_fma_f32 v[8:9], v[54:55], v[14:15], v[16:17] op_sel:[1,0,0] op_sel_hi:[1,1,0] neg_lo:[0,0,1] neg_hi:[0,0,1]
	v_pk_fma_f32 v[10:11], v[54:55], v[12:13], v[16:17] op_sel:[1,0,0] op_sel_hi:[1,1,0] neg_lo:[0,0,1] neg_hi:[0,0,1]
	v_pk_fma_f32 v[8:9], v[70:71], v[8:9], v[82:83]
	v_pk_fma_f32 v[10:11], v[78:79], v[10:11], v[84:85]
	v_pk_fma_f32 v[8:9], v[2:3], v[66:67], v[8:9]
	v_pk_fma_f32 v[2:3], v[0:1], v[68:69], v[10:11]
	v_cvt_pk_bf16_f32 v0, v4, v5
	v_cvt_pk_bf16_f32 v1, v6, v7
	v_cvt_pk_bf16_f32 v2, v2, v3
	v_cvt_pk_bf16_f32 v3, v8, v9
	global_store_dwordx4 v[64:65], v[0:3], off offset:256
	s_cbranch_vccz .LBB0_1274
	s_waitcnt vmcnt(0)
	s_cmpk_gt_u32 s29, 0xff
	s_cbranch_scc1 .LBB0_1285
	s_barrier

; __device__ __forceinline__ u32x4 pack8f(f32x4 lo, f32x4 hi) { u32x4 w; w.x = cvtpk(lo[0], lo[1]); w.y = cvtpk(lo[2], lo[3]); w.z = cvtpk(hi[0], hi[1]); w.w = cvtpk(hi[2], hi[3]); return w; }
; template <bool LN1>
; __device__ __forceinline__ void ln_phase(Frame& F, const bf16_t* Yin, const float* ga, const float* be, const float* modf, float* stats, bf16_t* ob16, float* of32) {
;     ...
;             for (int k = 0; k < 8; ++k) {
;                 float s = 0.f, q = 0.f;
; #pragma unroll
;                 for (int ww = 0; ww < 8; ++ww) { const f32x2 p = rd[k * 8 + ww]; s += p[0]; q += p[1]; }
;                 const float mean = s * (1.0f / D), var = fmaxf(q * (1.0f / D) - mean * mean, 0.f), rstd = 1.0f / sqrtf(var + 1e-5f);
;                 const size_t ro = (size_t)(r0 + k) * D + c0;
;                 if (LN1) { if (w == 0 && lane == 0) *(f32x2*)(stats + (size_t)(r0 + k) * 2) = (f32x2){mean, rstd};
;                     const int row = r0 + k; const size_t bo = ((((size_t)(row >> 8) * (D / 64)) + (c0 >> 6)) * 256 + (row & 255)) * 64 + (c0 & 63);
;                     *(u32x4*)(ob16 + bo) = pg8::pack8f((v[k][0] - mean) * rstd * ca[0] + cb[0], (v[k][1] - mean) * rstd * ca[1] + cb[1]); }
;                 else { *(f32x4*)(of32 + ro) = (v[k][0] - mean) * rstd * ca[0] + cb[0]; *(f32x4*)(of32 + ro + 4) = (v[k][1] - mean) * rstd * ca[1] + cb[1]; }
;             }
;         }
;         __syncthreads();
.LBB0_1342:
	s_or_b64 exec, exec, s[2:3]
	s_waitcnt lgkmcnt(0)
	s_barrier
	ds_read_b128 v[156:159], v49 offset:512
	ds_read_b128 v[160:163], v49 offset:528
	ds_read_b128 v[164:167], v49 offset:544
	ds_read_b128 v[168:171], v49 offset:560
	v_lshl_add_u64 v[58:59], v[58:59], 0, s[8:9]
	s_waitcnt lgkmcnt(3)
	v_pk_add_f32 v[156:157], v[156:157], 0 op_sel_hi:[1,0]
	s_nop 0
	v_pk_add_f32 v[156:157], v[156:157], v[158:159]
	s_waitcnt lgkmcnt(2)
	v_pk_add_f32 v[156:157], v[156:157], v[160:161]
	s_nop 0
	v_pk_add_f32 v[156:157], v[156:157], v[162:163]
	s_waitcnt lgkmcnt(1)
	v_pk_add_f32 v[156:157], v[156:157], v[164:165]
	s_nop 0
	v_pk_add_f32 v[156:157], v[156:157], v[166:167]
	s_waitcnt lgkmcnt(0)
	v_pk_add_f32 v[156:157], v[156:157], v[168:169]
	s_nop 0
	v_pk_add_f32 v[156:157], v[156:157], v[170:171]
	s_nop 0
	v_pk_mul_f32 v[160:161], v[156:157], s[10:11] op_sel_hi:[1,0]
	s_nop 0
	v_fma_f32 v17, -v160, v160, v161
	v_max_f32_e32 v17, 0, v17
	v_add_f32_e32 v17, 0x3727c5ac, v17
	v_mul_f32_e32 v19, 0x4f800000, v17
	v_cmp_gt_f32_e32 vcc, s5, v17
	v_sub_f32_e32 v153, v154, v160
	v_sub_f32_e32 v152, v152, v160
	v_cndmask_b32_e32 v17, v17, v19, vcc
	v_sqrt_f32_e32 v19, v17
	v_sub_f32_e32 v149, v150, v160
	v_sub_f32_e32 v148, v148, v160
	v_sub_f32_e32 v167, v146, v160
	v_add_u32_e32 v21, -1, v19
	v_fma_f32 v23, -v21, v19, v17
	v_cmp_ge_f32_e64 s[2:3], 0, v23
	v_add_u32_e32 v23, 1, v19
	v_sub_f32_e32 v166, v144, v160
	v_cndmask_b32_e64 v21, v19, v21, s[2:3]
	v_fma_f32 v19, -v23, v19, v17
	v_cmp_lt_f32_e64 s[2:3], 0, v19
	ds_read_b128 v[144:147], v49 offset:576
	v_sub_f32_e32 v117, v134, v160
	v_cndmask_b32_e64 v19, v21, v23, s[2:3]
	v_mul_f32_e32 v21, 0x37800000, v19
	v_cndmask_b32_e32 v19, v19, v21, vcc
	v_cmp_class_f32_e32 vcc, v17, v196
	s_waitcnt lgkmcnt(0)
	v_pk_add_f32 v[134:135], v[144:145], 0 op_sel_hi:[1,0]
	v_sub_f32_e32 v116, v116, v160
	v_cndmask_b32_e32 v17, v19, v17, vcc
	v_div_scale_f32 v19, s[2:3], v17, v17, 1.0
	v_rcp_f32_e32 v21, v19
	s_or_b32 s2, s4, 56
	s_ashr_i32 s3, s2, 31
	s_lshl_b64 s[2:3], s[2:3], 14
	v_fma_f32 v23, -v19, v21, 1.0
	v_fmac_f32_e32 v21, v23, v21
	v_div_scale_f32 v23, vcc, 1.0, v17, 1.0
	v_mul_f32_e32 v25, v23, v21
	v_fma_f32 v27, -v19, v25, v23
	v_fmac_f32_e32 v25, v27, v21
	v_fma_f32 v19, -v19, v25, v23
	v_div_fmas_f32 v19, v19, v21, v25
	v_div_fixup_f32 v162, v19, v17, 1.0
	v_pk_mul_f32 v[148:149], v[148:149], v[162:163] op_sel_hi:[1,0]
	v_pk_mul_f32 v[150:151], v[152:153], v[162:163] op_sel_hi:[1,0]
	v_pk_fma_f32 v[148:149], v[8:9], v[148:149], v[12:13]
	v_pk_fma_f32 v[150:151], v[10:11], v[150:151], v[14:15]
	v_lshl_add_u64 v[164:165], v[56:57], 0, s[2:3]
	global_store_dwordx4 v[164:165], v[148:151], off nt
	ds_read_b128 v[148:151], v49 offset:592
	ds_read_b128 v[152:155], v49 offset:608
	ds_read_b128 v[156:159], v49 offset:624
	v_pk_add_f32 v[134:135], v[134:135], v[146:147]
	v_pk_mul_f32 v[116:117], v[116:117], v[162:163] op_sel_hi:[1,0]
	s_waitcnt lgkmcnt(2)
	v_pk_add_f32 v[134:135], v[134:135], v[148:149]
	v_pk_fma_f32 v[144:145], v[0:1], v[116:117], v[4:5]
	v_pk_add_f32 v[134:135], v[134:135], v[150:151]
	s_waitcnt lgkmcnt(1)
	v_pk_add_f32 v[134:135], v[134:135], v[152:153]
	s_nop 0
	v_pk_add_f32 v[134:135], v[134:135], v[154:155]
	s_waitcnt lgkmcnt(0)
	v_pk_add_f32 v[134:135], v[134:135], v[156:157]
	s_nop 0
	v_pk_add_f32 v[134:135], v[134:135], v[158:159]
	s_nop 0
	v_pk_mul_f32 v[148:149], v[134:135], s[10:11] op_sel_hi:[1,0]
	v_pk_mul_f32 v[134:135], v[166:167], v[162:163] op_sel_hi:[1,0]
	v_fma_f32 v17, -v148, v148, v149
	v_max_f32_e32 v17, 0, v17
	v_add_f32_e32 v17, 0x3727c5ac, v17
	v_mul_f32_e32 v19, 0x4f800000, v17
	v_cmp_gt_f32_e32 vcc, s5, v17
	v_pk_fma_f32 v[146:147], v[2:3], v[134:135], v[6:7]
	v_sub_f32_e32 v135, v142, v148
	v_cndmask_b32_e32 v17, v17, v19, vcc
	v_sqrt_f32_e32 v19, v17
	v_sub_f32_e32 v134, v140, v148
	v_sub_f32_e32 v137, v138, v148
	v_sub_f32_e32 v136, v136, v148
	v_add_u32_e32 v21, -1, v19
	v_fma_f32 v23, -v21, v19, v17
	v_cmp_ge_f32_e64 s[2:3], 0, v23
	v_add_u32_e32 v23, 1, v19
	v_sub_f32_e32 v151, v132, v148
	v_cndmask_b32_e64 v21, v19, v21, s[2:3]
	v_fma_f32 v19, -v23, v19, v17
	v_cmp_lt_f32_e64 s[2:3], 0, v19
	v_sub_f32_e32 v150, v130, v148
	ds_read_b128 v[130:133], v49 offset:640
	v_cndmask_b32_e64 v19, v21, v23, s[2:3]
	v_mul_f32_e32 v21, 0x37800000, v19
	v_cndmask_b32_e32 v19, v19, v21, vcc
	v_cmp_class_f32_e32 vcc, v17, v196
	global_store_dwordx4 v[164:165], v[144:147], off offset:16 nt
	v_sub_f32_e32 v101, v120, v148
	v_cndmask_b32_e32 v17, v19, v17, vcc
	v_div_scale_f32 v19, s[2:3], v17, v17, 1.0
	v_rcp_f32_e32 v21, v19
	s_or_b32 s2, s4, 57
	s_ashr_i32 s3, s2, 31
	s_lshl_b64 s[2:3], s[2:3], 14
	v_fma_f32 v23, -v19, v21, 1.0
	v_fmac_f32_e32 v21, v23, v21
	v_div_scale_f32 v23, vcc, 1.0, v17, 1.0
	v_mul_f32_e32 v25, v23, v21
	v_fma_f32 v27, -v19, v25, v23
	v_fmac_f32_e32 v25, v27, v21
	v_fma_f32 v19, -v19, v25, v23
	v_div_fmas_f32 v19, v19, v21, v25
	v_div_fixup_f32 v116, v19, v17, 1.0
	v_pk_mul_f32 v[138:139], v[136:137], v[116:117] op_sel_hi:[1,0]
	v_pk_mul_f32 v[134:135], v[134:135], v[116:117] op_sel_hi:[1,0]
	v_lshl_add_u64 v[146:147], v[56:57], 0, s[2:3]
	v_pk_fma_f32 v[136:137], v[10:11], v[134:135], v[14:15]
	v_pk_fma_f32 v[134:135], v[8:9], v[138:139], v[12:13]
	global_store_dwordx4 v[146:147], v[134:137], off nt
	ds_read_b128 v[134:137], v49 offset:656
	ds_read_b128 v[138:141], v49 offset:672
	ds_read_b128 v[142:145], v49 offset:688
	s_waitcnt lgkmcnt(3)
	v_pk_add_f32 v[120:121], v[130:131], 0 op_sel_hi:[1,0]
	v_sub_f32_e32 v100, v100, v148
	v_pk_add_f32 v[120:121], v[120:121], v[132:133]
	v_pk_mul_f32 v[100:101], v[100:101], v[116:117] op_sel_hi:[1,0]
	s_waitcnt lgkmcnt(2)
; __device__ __forceinline__ u32x4 pack8f(f32x4 lo, f32x4 hi) { u32x4 w; w.x = cvtpk(lo[0], lo[1]); w.y = cvtpk(lo[2], lo[3]); w.z = cvtpk(hi[0], hi[1]); w.w = cvtpk(hi[2], hi[3]); return w; }
; template <bool LN1>
; __device__ __forceinline__ void ln_phase(Frame& F, const bf16_t* Yin, const float* ga, const float* be, const float* modf, float* stats, bf16_t* ob16, float* of32) {
;     ...
;             for (int k = 0; k < 8; ++k) {
;                 float s = 0.f, q = 0.f;
; #pragma unroll
;                 for (int ww = 0; ww < 8; ++ww) { const f32x2 p = rd[k * 8 + ww]; s += p[0]; q += p[1]; }
;                 const float mean = s * (1.0f / D), var = fmaxf(q * (1.0f / D) - mean * mean, 0.f), rstd = 1.0f / sqrtf(var + 1e-5f);
;                 const size_t ro = (size_t)(r0 + k) * D + c0;
;                 if (LN1) { if (w == 0 && lane == 0) *(f32x2*)(stats + (size_t)(r0 + k) * 2) = (f32x2){mean, rstd};
;                     const int row = r0 + k; const size_t bo = ((((size_t)(row >> 8) * (D / 64)) + (c0 >> 6)) * 256 + (row & 255)) * 64 + (c0 & 63);
;                     *(u32x4*)(ob16 + bo) = pg8::pack8f((v[k][0] - mean) * rstd * ca[0] + cb[0], (v[k][1] - mean) * rstd * ca[1] + cb[1]); }
;                 else { *(f32x4*)(of32 + ro) = (v[k][0] - mean) * rstd * ca[0] + cb[0]; *(f32x4*)(of32 + ro + 4) = (v[k][1] - mean) * rstd * ca[1] + cb[1]; }
;             }
;         }
;         __syncthreads();
	v_pk_add_f32 v[120:121], v[120:121], v[134:135]
	v_pk_mul_f32 v[116:117], v[150:151], v[116:117] op_sel_hi:[1,0]
	v_pk_add_f32 v[120:121], v[120:121], v[136:137]
	v_pk_fma_f32 v[132:133], v[2:3], v[116:117], v[6:7]
	s_waitcnt lgkmcnt(1)
	v_pk_add_f32 v[120:121], v[120:121], v[138:139]
	v_pk_fma_f32 v[130:131], v[0:1], v[100:101], v[4:5]
	v_pk_add_f32 v[120:121], v[120:121], v[140:141]
	global_store_dwordx4 v[146:147], v[130:133], off offset:16 nt
	s_waitcnt lgkmcnt(0)
	v_pk_add_f32 v[120:121], v[120:121], v[142:143]
	s_nop 0
	v_pk_add_f32 v[120:121], v[120:121], v[144:145]
	s_nop 0
	v_pk_mul_f32 v[134:135], v[120:121], s[10:11] op_sel_hi:[1,0]
	s_nop 0
	v_fma_f32 v17, -v134, v134, v135
	v_max_f32_e32 v17, 0, v17
	v_add_f32_e32 v17, 0x3727c5ac, v17
	v_mul_f32_e32 v19, 0x4f800000, v17
	v_cmp_gt_f32_e32 vcc, s5, v17
	v_sub_f32_e32 v117, v128, v134
	v_sub_f32_e32 v116, v126, v134
	v_cndmask_b32_e32 v17, v17, v19, vcc
	v_sqrt_f32_e32 v19, v17
	v_sub_f32_e32 v121, v124, v134
	v_sub_f32_e32 v120, v122, v134
	v_sub_f32_e32 v132, v114, v134
	v_add_u32_e32 v21, -1, v19
	v_fma_f32 v23, -v21, v19, v17
	v_cmp_ge_f32_e64 s[2:3], 0, v23
	v_add_u32_e32 v23, 1, v19
	v_sub_f32_e32 v133, v118, v134
	v_cndmask_b32_e64 v21, v19, v21, s[2:3]
	v_fma_f32 v19, -v23, v19, v17
	v_cmp_lt_f32_e64 s[2:3], 0, v19
	v_sub_f32_e32 v85, v104, v134
	v_sub_f32_e32 v84, v84, v134
	v_cndmask_b32_e64 v19, v21, v23, s[2:3]
	v_mul_f32_e32 v21, 0x37800000, v19
	v_cndmask_b32_e32 v19, v19, v21, vcc
	v_cmp_class_f32_e32 vcc, v17, v196
	s_nop 1
	v_cndmask_b32_e32 v17, v19, v17, vcc
	v_div_scale_f32 v19, s[2:3], v17, v17, 1.0
	v_rcp_f32_e32 v21, v19
	s_or_b32 s2, s4, 58
	s_ashr_i32 s3, s2, 31
	s_lshl_b64 s[2:3], s[2:3], 14
	v_fma_f32 v23, -v19, v21, 1.0
	v_fmac_f32_e32 v21, v23, v21
	v_div_scale_f32 v23, vcc, 1.0, v17, 1.0
	v_mul_f32_e32 v25, v23, v21
	v_fma_f32 v27, -v19, v25, v23
	v_fmac_f32_e32 v25, v27, v21
	v_fma_f32 v19, -v19, v25, v23
	v_div_fmas_f32 v19, v19, v21, v25
	v_div_fixup_f32 v100, v19, v17, 1.0
	v_pk_mul_f32 v[116:117], v[116:117], v[100:101] op_sel_hi:[1,0]
	v_pk_mul_f32 v[120:121], v[120:121], v[100:101] op_sel_hi:[1,0]
	v_pk_fma_f32 v[122:123], v[10:11], v[116:117], v[14:15]
	ds_read_b128 v[114:117], v49 offset:704
	v_pk_fma_f32 v[120:121], v[8:9], v[120:121], v[12:13]
	v_lshl_add_u64 v[130:131], v[56:57], 0, s[2:3]
	global_store_dwordx4 v[130:131], v[120:123], off nt
	ds_read_b128 v[118:121], v49 offset:720
	ds_read_b128 v[122:125], v49 offset:736
	ds_read_b128 v[126:129], v49 offset:752
	s_waitcnt lgkmcnt(3)
	v_pk_add_f32 v[104:105], v[114:115], 0 op_sel_hi:[1,0]
	v_pk_mul_f32 v[84:85], v[84:85], v[100:101] op_sel_hi:[1,0]
	v_pk_add_f32 v[104:105], v[104:105], v[116:117]
	v_pk_mul_f32 v[100:101], v[132:133], v[100:101] op_sel_hi:[1,0]
	s_waitcnt lgkmcnt(2)
	v_pk_add_f32 v[104:105], v[104:105], v[118:119]
	v_pk_fma_f32 v[116:117], v[2:3], v[100:101], v[6:7]
	v_pk_add_f32 v[104:105], v[104:105], v[120:121]
	v_pk_fma_f32 v[114:115], v[0:1], v[84:85], v[4:5]
	s_waitcnt lgkmcnt(1)
	v_pk_add_f32 v[104:105], v[104:105], v[122:123]
	global_store_dwordx4 v[130:131], v[114:117], off offset:16 nt
	v_pk_add_f32 v[104:105], v[104:105], v[124:125]
	s_waitcnt lgkmcnt(0)
	v_pk_add_f32 v[104:105], v[104:105], v[126:127]
	s_nop 0
	v_pk_add_f32 v[104:105], v[104:105], v[128:129]
	s_nop 0
	v_pk_mul_f32 v[118:119], v[104:105], s[10:11] op_sel_hi:[1,0]
	s_nop 0
	v_fma_f32 v17, -v118, v118, v119
	v_max_f32_e32 v17, 0, v17
	v_add_f32_e32 v17, 0x3727c5ac, v17
	v_mul_f32_e32 v19, 0x4f800000, v17
	v_cmp_gt_f32_e32 vcc, s5, v17
	v_sub_f32_e32 v101, v112, v118
	v_sub_f32_e32 v100, v110, v118
	v_cndmask_b32_e32 v17, v17, v19, vcc
	v_sqrt_f32_e32 v19, v17
	v_sub_f32_e32 v105, v108, v118
	v_sub_f32_e32 v104, v106, v118
	v_sub_f32_e32 v116, v98, v118
	v_add_u32_e32 v21, -1, v19
	v_fma_f32 v23, -v21, v19, v17
	v_cmp_ge_f32_e64 s[2:3], 0, v23
	v_add_u32_e32 v23, 1, v19
	v_sub_f32_e32 v117, v102, v118
	v_cndmask_b32_e64 v21, v19, v21, s[2:3]
	v_fma_f32 v19, -v23, v19, v17
	v_cmp_lt_f32_e64 s[2:3], 0, v19
	v_sub_f32_e32 v69, v88, v118
	v_sub_f32_e32 v68, v68, v118
	v_cndmask_b32_e64 v19, v21, v23, s[2:3]
	v_mul_f32_e32 v21, 0x37800000, v19
	v_cndmask_b32_e32 v19, v19, v21, vcc
	v_cmp_class_f32_e32 vcc, v17, v196
	s_nop 1
	v_cndmask_b32_e32 v17, v19, v17, vcc
	v_div_scale_f32 v19, s[2:3], v17, v17, 1.0
	v_rcp_f32_e32 v21, v19
	s_or_b32 s2, s4, 59
	s_ashr_i32 s3, s2, 31
	s_lshl_b64 s[2:3], s[2:3], 14
	v_fma_f32 v23, -v19, v21, 1.0
	v_fmac_f32_e32 v21, v23, v21
	v_div_scale_f32 v23, vcc, 1.0, v17, 1.0
	v_mul_f32_e32 v25, v23, v21
	v_fma_f32 v27, -v19, v25, v23
	v_fmac_f32_e32 v25, v27, v21
	v_fma_f32 v19, -v19, v25, v23
	v_div_fmas_f32 v19, v19, v21, v25
	v_div_fixup_f32 v84, v19, v17, 1.0
	v_pk_mul_f32 v[100:101], v[100:101], v[84:85] op_sel_hi:[1,0]
	v_pk_mul_f32 v[104:105], v[104:105], v[84:85] op_sel_hi:[1,0]
	v_pk_fma_f32 v[106:107], v[10:11], v[100:101], v[14:15]
	ds_read_b128 v[98:101], v49 offset:768
	v_pk_fma_f32 v[104:105], v[8:9], v[104:105], v[12:13]
	v_lshl_add_u64 v[114:115], v[56:57], 0, s[2:3]
	global_store_dwordx4 v[114:115], v[104:107], off nt
	ds_read_b128 v[102:105], v49 offset:784
	ds_read_b128 v[106:109], v49 offset:800
	ds_read_b128 v[110:113], v49 offset:816
	s_waitcnt lgkmcnt(3)
	v_pk_add_f32 v[88:89], v[98:99], 0 op_sel_hi:[1,0]
	v_pk_mul_f32 v[68:69], v[68:69], v[84:85] op_sel_hi:[1,0]
	v_pk_add_f32 v[88:89], v[88:89], v[100:101]
	v_pk_mul_f32 v[84:85], v[116:117], v[84:85] op_sel_hi:[1,0]
	s_waitcnt lgkmcnt(2)
	v_pk_add_f32 v[88:89], v[88:89], v[102:103]
	v_pk_fma_f32 v[100:101], v[2:3], v[84:85], v[6:7]
	v_pk_add_f32 v[88:89], v[88:89], v[104:105]
	v_pk_fma_f32 v[98:99], v[0:1], v[68:69], v[4:5]
	s_waitcnt lgkmcnt(1)
; __device__ __forceinline__ u32x4 pack8f(f32x4 lo, f32x4 hi) { u32x4 w; w.x = cvtpk(lo[0], lo[1]); w.y = cvtpk(lo[2], lo[3]); w.z = cvtpk(hi[0], hi[1]); w.w = cvtpk(hi[2], hi[3]); return w; }
; template <bool LN1>
; __device__ __forceinline__ void ln_phase(Frame& F, const bf16_t* Yin, const float* ga, const float* be, const float* modf, float* stats, bf16_t* ob16, float* of32) {
;     ...
;             for (int k = 0; k < 8; ++k) {
;                 float s = 0.f, q = 0.f;
; #pragma unroll
;                 for (int ww = 0; ww < 8; ++ww) { const f32x2 p = rd[k * 8 + ww]; s += p[0]; q += p[1]; }
;                 const float mean = s * (1.0f / D), var = fmaxf(q * (1.0f / D) - mean * mean, 0.f), rstd = 1.0f / sqrtf(var + 1e-5f);
;                 const size_t ro = (size_t)(r0 + k) * D + c0;
;                 if (LN1) { if (w == 0 && lane == 0) *(f32x2*)(stats + (size_t)(r0 + k) * 2) = (f32x2){mean, rstd};
;                     const int row = r0 + k; const size_t bo = ((((size_t)(row >> 8) * (D / 64)) + (c0 >> 6)) * 256 + (row & 255)) * 64 + (c0 & 63);
;                     *(u32x4*)(ob16 + bo) = pg8::pack8f((v[k][0] - mean) * rstd * ca[0] + cb[0], (v[k][1] - mean) * rstd * ca[1] + cb[1]); }
;                 else { *(f32x4*)(of32 + ro) = (v[k][0] - mean) * rstd * ca[0] + cb[0]; *(f32x4*)(of32 + ro + 4) = (v[k][1] - mean) * rstd * ca[1] + cb[1]; }
;             }
;         }
;         __syncthreads();
	v_pk_add_f32 v[88:89], v[88:89], v[106:107]
	global_store_dwordx4 v[114:115], v[98:101], off offset:16 nt
	v_pk_add_f32 v[88:89], v[88:89], v[108:109]
	s_waitcnt lgkmcnt(0)
	v_pk_add_f32 v[88:89], v[88:89], v[110:111]
	s_nop 0
	v_pk_add_f32 v[88:89], v[88:89], v[112:113]
	s_nop 0
	v_pk_mul_f32 v[102:103], v[88:89], s[10:11] op_sel_hi:[1,0]
	s_nop 0
	v_fma_f32 v17, -v102, v102, v103
	v_max_f32_e32 v17, 0, v17
	v_add_f32_e32 v17, 0x3727c5ac, v17
	v_mul_f32_e32 v19, 0x4f800000, v17
	v_cmp_gt_f32_e32 vcc, s5, v17
	v_sub_f32_e32 v85, v96, v102
	v_sub_f32_e32 v84, v94, v102
	v_cndmask_b32_e32 v17, v17, v19, vcc
	v_sqrt_f32_e32 v19, v17
	v_sub_f32_e32 v89, v92, v102
	v_sub_f32_e32 v88, v90, v102
	v_sub_f32_e32 v100, v82, v102
	v_add_u32_e32 v21, -1, v19
	v_fma_f32 v23, -v21, v19, v17
	v_cmp_ge_f32_e64 s[2:3], 0, v23
	v_add_u32_e32 v23, 1, v19
	v_sub_f32_e32 v101, v86, v102
	v_cndmask_b32_e64 v21, v19, v21, s[2:3]
	v_fma_f32 v19, -v23, v19, v17
	v_cmp_lt_f32_e64 s[2:3], 0, v19
	v_sub_f32_e32 v41, v72, v102
	v_sub_f32_e32 v40, v40, v102
	v_cndmask_b32_e64 v19, v21, v23, s[2:3]
	v_mul_f32_e32 v21, 0x37800000, v19
	v_cndmask_b32_e32 v19, v19, v21, vcc
	v_cmp_class_f32_e32 vcc, v17, v196
	s_nop 1
	v_cndmask_b32_e32 v17, v19, v17, vcc
	v_div_scale_f32 v19, s[2:3], v17, v17, 1.0
	v_rcp_f32_e32 v21, v19
	s_or_b32 s2, s4, 60
	s_ashr_i32 s3, s2, 31
	s_lshl_b64 s[2:3], s[2:3], 14
	v_fma_f32 v23, -v19, v21, 1.0
	v_fmac_f32_e32 v21, v23, v21
	v_div_scale_f32 v23, vcc, 1.0, v17, 1.0
	v_mul_f32_e32 v25, v23, v21
	v_fma_f32 v27, -v19, v25, v23
	v_fmac_f32_e32 v25, v27, v21
	v_fma_f32 v19, -v19, v25, v23
	v_div_fmas_f32 v19, v19, v21, v25
	v_div_fixup_f32 v68, v19, v17, 1.0
	v_pk_mul_f32 v[84:85], v[84:85], v[68:69] op_sel_hi:[1,0]
	v_pk_mul_f32 v[88:89], v[88:89], v[68:69] op_sel_hi:[1,0]
	v_pk_fma_f32 v[90:91], v[10:11], v[84:85], v[14:15]
	ds_read_b128 v[82:85], v49 offset:832
	v_pk_fma_f32 v[88:89], v[8:9], v[88:89], v[12:13]
	v_lshl_add_u64 v[98:99], v[56:57], 0, s[2:3]
	global_store_dwordx4 v[98:99], v[88:91], off nt
	ds_read_b128 v[86:89], v49 offset:848
	ds_read_b128 v[90:93], v49 offset:864
	ds_read_b128 v[94:97], v49 offset:880
	s_waitcnt lgkmcnt(3)
	v_pk_add_f32 v[72:73], v[82:83], 0 op_sel_hi:[1,0]
	v_pk_mul_f32 v[40:41], v[40:41], v[68:69] op_sel_hi:[1,0]
	v_pk_add_f32 v[72:73], v[72:73], v[84:85]
	v_pk_mul_f32 v[68:69], v[100:101], v[68:69] op_sel_hi:[1,0]
	s_waitcnt lgkmcnt(2)
	v_pk_add_f32 v[72:73], v[72:73], v[86:87]
	v_pk_fma_f32 v[84:85], v[2:3], v[68:69], v[6:7]
	v_pk_add_f32 v[72:73], v[72:73], v[88:89]
	v_pk_fma_f32 v[82:83], v[0:1], v[40:41], v[4:5]
	s_waitcnt lgkmcnt(1)
	v_pk_add_f32 v[72:73], v[72:73], v[90:91]
	global_store_dwordx4 v[98:99], v[82:85], off offset:16 nt
	v_pk_add_f32 v[72:73], v[72:73], v[92:93]
	s_waitcnt lgkmcnt(0)
	v_pk_add_f32 v[72:73], v[72:73], v[94:95]
	s_nop 0
	v_pk_add_f32 v[72:73], v[72:73], v[96:97]
	s_nop 0
	v_pk_mul_f32 v[86:87], v[72:73], s[10:11] op_sel_hi:[1,0]
	s_nop 0
	v_fma_f32 v17, -v86, v86, v87
	v_max_f32_e32 v17, 0, v17
	v_add_f32_e32 v17, 0x3727c5ac, v17
	v_mul_f32_e32 v19, 0x4f800000, v17
	v_cmp_gt_f32_e32 vcc, s5, v17
	v_sub_f32_e32 v69, v80, v86
	v_sub_f32_e32 v68, v78, v86
	v_cndmask_b32_e32 v17, v17, v19, vcc
	v_sqrt_f32_e32 v19, v17
	v_sub_f32_e32 v73, v76, v86
	v_sub_f32_e32 v72, v74, v86
	v_sub_f32_e32 v84, v66, v86
	v_add_u32_e32 v21, -1, v19
	v_fma_f32 v23, -v21, v19, v17
	v_cmp_ge_f32_e64 s[2:3], 0, v23
	v_add_u32_e32 v23, 1, v19
	v_sub_f32_e32 v85, v70, v86
	v_cndmask_b32_e64 v21, v19, v21, s[2:3]
	v_fma_f32 v19, -v23, v19, v17
	v_cmp_lt_f32_e64 s[2:3], 0, v19
	v_sub_f32_e32 v24, v24, v86
	s_nop 0
	v_cndmask_b32_e64 v19, v21, v23, s[2:3]
	v_mul_f32_e32 v21, 0x37800000, v19
	v_cndmask_b32_e32 v19, v19, v21, vcc
	v_cmp_class_f32_e32 vcc, v17, v196
	s_nop 1
	v_cndmask_b32_e32 v17, v19, v17, vcc
	v_div_scale_f32 v19, s[2:3], v17, v17, 1.0
	v_rcp_f32_e32 v21, v19
	s_or_b32 s2, s4, 61
	s_ashr_i32 s3, s2, 31
	s_lshl_b64 s[2:3], s[2:3], 14
	v_fma_f32 v23, -v19, v21, 1.0
	v_fmac_f32_e32 v21, v23, v21
	v_div_scale_f32 v23, vcc, 1.0, v17, 1.0
	v_mul_f32_e32 v25, v23, v21
	v_fma_f32 v27, -v19, v25, v23
	v_fmac_f32_e32 v25, v27, v21
	v_fma_f32 v19, -v19, v25, v23
	v_div_fmas_f32 v19, v19, v21, v25
	v_div_fixup_f32 v40, v19, v17, 1.0
	v_pk_mul_f32 v[68:69], v[68:69], v[40:41] op_sel_hi:[1,0]
	v_pk_mul_f32 v[72:73], v[72:73], v[40:41] op_sel_hi:[1,0]
	v_pk_fma_f32 v[74:75], v[10:11], v[68:69], v[14:15]
	ds_read_b128 v[66:69], v49 offset:896
	v_pk_fma_f32 v[72:73], v[8:9], v[72:73], v[12:13]
	v_lshl_add_u64 v[82:83], v[56:57], 0, s[2:3]
	global_store_dwordx4 v[82:83], v[72:75], off nt
	ds_read_b128 v[70:73], v49 offset:912
	ds_read_b128 v[74:77], v49 offset:928
	ds_read_b128 v[78:81], v49 offset:944
	v_sub_f32_e32 v25, v44, v86
	s_waitcnt lgkmcnt(3)
	v_pk_add_f32 v[44:45], v[66:67], 0 op_sel_hi:[1,0]
	v_pk_mul_f32 v[24:25], v[24:25], v[40:41] op_sel_hi:[1,0]
	v_pk_add_f32 v[44:45], v[44:45], v[68:69]
	v_pk_fma_f32 v[66:67], v[0:1], v[24:25], v[4:5]
	s_waitcnt lgkmcnt(2)
; __device__ __forceinline__ u32x4 pack8f(f32x4 lo, f32x4 hi) { u32x4 w; w.x = cvtpk(lo[0], lo[1]); w.y = cvtpk(lo[2], lo[3]); w.z = cvtpk(hi[0], hi[1]); w.w = cvtpk(hi[2], hi[3]); return w; }
; template <bool LN1>
; __device__ __forceinline__ void ln_phase(Frame& F, const bf16_t* Yin, const float* ga, const float* be, const float* modf, float* stats, bf16_t* ob16, float* of32) {
;     ...
;             for (int k = 0; k < 8; ++k) {
;                 float s = 0.f, q = 0.f;
; #pragma unroll
;                 for (int ww = 0; ww < 8; ++ww) { const f32x2 p = rd[k * 8 + ww]; s += p[0]; q += p[1]; }
;                 const float mean = s * (1.0f / D), var = fmaxf(q * (1.0f / D) - mean * mean, 0.f), rstd = 1.0f / sqrtf(var + 1e-5f);
;                 const size_t ro = (size_t)(r0 + k) * D + c0;
;                 if (LN1) { if (w == 0 && lane == 0) *(f32x2*)(stats + (size_t)(r0 + k) * 2) = (f32x2){mean, rstd};
;                     const int row = r0 + k; const size_t bo = ((((size_t)(row >> 8) * (D / 64)) + (c0 >> 6)) * 256 + (row & 255)) * 64 + (c0 & 63);
;                     *(u32x4*)(ob16 + bo) = pg8::pack8f((v[k][0] - mean) * rstd * ca[0] + cb[0], (v[k][1] - mean) * rstd * ca[1] + cb[1]); }
;                 else { *(f32x4*)(of32 + ro) = (v[k][0] - mean) * rstd * ca[0] + cb[0]; *(f32x4*)(of32 + ro + 4) = (v[k][1] - mean) * rstd * ca[1] + cb[1]; }
;             }
;         }
;         __syncthreads();
;     }
; }
	v_pk_add_f32 v[44:45], v[44:45], v[70:71]
	v_pk_mul_f32 v[40:41], v[84:85], v[40:41] op_sel_hi:[1,0]
	v_pk_add_f32 v[44:45], v[44:45], v[72:73]
	v_pk_fma_f32 v[68:69], v[2:3], v[40:41], v[6:7]
	s_waitcnt lgkmcnt(1)
	v_pk_add_f32 v[44:45], v[44:45], v[74:75]
	global_store_dwordx4 v[82:83], v[66:69], off offset:16 nt
	v_pk_add_f32 v[44:45], v[44:45], v[76:77]
	s_waitcnt lgkmcnt(0)
	v_pk_add_f32 v[44:45], v[44:45], v[78:79]
	s_nop 0
	v_pk_add_f32 v[44:45], v[44:45], v[80:81]
	s_nop 0
	v_pk_mul_f32 v[70:71], v[44:45], s[10:11] op_sel_hi:[1,0]
	s_nop 0
	v_fma_f32 v17, -v70, v70, v71
	v_max_f32_e32 v17, 0, v17
	v_add_f32_e32 v17, 0x3727c5ac, v17
	v_mul_f32_e32 v19, 0x4f800000, v17
	v_cmp_gt_f32_e32 vcc, s5, v17
	v_sub_f32_e32 v41, v64, v70
	v_sub_f32_e32 v40, v62, v70
	v_cndmask_b32_e32 v17, v17, v19, vcc
	v_sqrt_f32_e32 v19, v17
	v_sub_f32_e32 v45, v60, v70
	v_sub_f32_e32 v44, v46, v70
	v_sub_f32_e32 v20, v20, v70
	v_add_u32_e32 v21, -1, v19
	v_fma_f32 v23, -v21, v19, v17
	v_cmp_ge_f32_e64 s[2:3], 0, v23
	v_add_u32_e32 v23, 1, v19
	s_nop 0
	v_cndmask_b32_e64 v21, v19, v21, s[2:3]
	v_fma_f32 v19, -v23, v19, v17
	v_cmp_lt_f32_e64 s[2:3], 0, v19
	s_nop 1
	v_cndmask_b32_e64 v19, v21, v23, s[2:3]
	v_mul_f32_e32 v21, 0x37800000, v19
	v_cndmask_b32_e32 v19, v19, v21, vcc
	v_cmp_class_f32_e32 vcc, v17, v196
	s_nop 1
	v_cndmask_b32_e32 v17, v19, v17, vcc
	v_div_scale_f32 v19, s[2:3], v17, v17, 1.0
	v_rcp_f32_e32 v21, v19
	s_or_b32 s2, s4, 62
	s_ashr_i32 s3, s2, 31
	s_lshl_b64 s[2:3], s[2:3], 14
	v_fma_f32 v23, -v19, v21, 1.0
	v_fmac_f32_e32 v21, v23, v21
	v_div_scale_f32 v23, vcc, 1.0, v17, 1.0
	v_mul_f32_e32 v24, v23, v21
	v_fma_f32 v25, -v19, v24, v23
	v_fmac_f32_e32 v24, v25, v21
	v_fma_f32 v19, -v19, v24, v23
	v_div_fmas_f32 v19, v19, v21, v24
	v_div_fixup_f32 v24, v19, v17, 1.0
	v_pk_mul_f32 v[44:45], v[44:45], v[24:25] op_sel_hi:[1,0]
	v_pk_mul_f32 v[40:41], v[40:41], v[24:25] op_sel_hi:[1,0]
	v_pk_fma_f32 v[44:45], v[8:9], v[44:45], v[12:13]
	v_pk_fma_f32 v[46:47], v[10:11], v[40:41], v[14:15]
	v_lshl_add_u64 v[68:69], v[56:57], 0, s[2:3]
	global_store_dwordx4 v[68:69], v[44:47], off nt
	v_sub_f32_e32 v21, v28, v70
	v_pk_mul_f32 v[20:21], v[20:21], v[24:25] op_sel_hi:[1,0]
	v_sub_f32_e32 v46, v38, v70
	ds_read_b128 v[38:41], v49 offset:960
	v_sub_f32_e32 v47, v42, v70
	ds_read_b128 v[42:45], v49 offset:976
	ds_read_b128 v[60:63], v49 offset:992
	ds_read_b128 v[64:67], v49 offset:1008
	v_pk_mul_f32 v[24:25], v[46:47], v[24:25] op_sel_hi:[1,0]
	s_waitcnt lgkmcnt(3)
	v_pk_add_f32 v[28:29], v[38:39], 0 op_sel_hi:[1,0]
	s_nop 0
	v_pk_add_f32 v[28:29], v[28:29], v[40:41]
	v_pk_fma_f32 v[38:39], v[0:1], v[20:21], v[4:5]
	s_waitcnt lgkmcnt(2)
	v_pk_add_f32 v[28:29], v[28:29], v[42:43]
	v_pk_fma_f32 v[40:41], v[2:3], v[24:25], v[6:7]
	v_pk_add_f32 v[28:29], v[28:29], v[44:45]
	global_store_dwordx4 v[68:69], v[38:41], off offset:16 nt
	s_waitcnt lgkmcnt(1)
	v_pk_add_f32 v[28:29], v[28:29], v[60:61]
	s_nop 0
	v_pk_add_f32 v[28:29], v[28:29], v[62:63]
	s_waitcnt lgkmcnt(0)
	v_pk_add_f32 v[28:29], v[28:29], v[64:65]
	s_nop 0
	v_pk_add_f32 v[28:29], v[28:29], v[66:67]
	s_nop 0
	v_pk_mul_f32 v[28:29], v[28:29], s[10:11] op_sel_hi:[1,0]
	s_nop 0
	v_fma_f32 v17, -v28, v28, v29
	v_max_f32_e32 v17, 0, v17
	v_add_f32_e32 v17, 0x3727c5ac, v17
	v_mul_f32_e32 v19, 0x4f800000, v17
	v_cmp_gt_f32_e32 vcc, s5, v17
	v_sub_f32_e32 v25, v36, v28
	v_sub_f32_e32 v31, v32, v28
	v_cndmask_b32_e32 v17, v17, v19, vcc
	v_sqrt_f32_e32 v19, v17
	v_sub_f32_e32 v30, v30, v28
	v_add_u32_e32 v23, -1, v19
	v_fma_f32 v27, -v23, v19, v17
	v_cmp_ge_f32_e64 s[2:3], 0, v27
	v_add_u32_e32 v27, 1, v19
	s_nop 0
	v_cndmask_b32_e64 v23, v19, v23, s[2:3]
	v_fma_f32 v19, -v27, v19, v17
	v_cmp_lt_f32_e64 s[2:3], 0, v19
	s_nop 1
	v_cndmask_b32_e64 v19, v23, v27, s[2:3]
	v_mul_f32_e32 v23, 0x37800000, v19
	v_cndmask_b32_e32 v19, v19, v23, vcc
	v_cmp_class_f32_e32 vcc, v17, v196
	s_nop 1
	v_cndmask_b32_e32 v17, v19, v17, vcc
	v_div_scale_f32 v19, s[2:3], v17, v17, 1.0
	v_rcp_f32_e32 v23, v19
	s_or_b32 s2, s4, 63
	s_ashr_i32 s3, s2, 31
	s_lshl_b64 s[2:3], s[2:3], 14
	v_fma_f32 v20, -v19, v23, 1.0
	v_fmac_f32_e32 v23, v20, v23
	v_div_scale_f32 v20, vcc, 1.0, v17, 1.0
	v_mul_f32_e32 v21, v20, v23
	v_fma_f32 v24, -v19, v21, v20
	v_fmac_f32_e32 v21, v24, v23
	v_fma_f32 v19, -v19, v21, v20
	v_div_fmas_f32 v19, v19, v23, v21
	v_div_fixup_f32 v20, v19, v17, 1.0
	v_sub_f32_e32 v24, v34, v28
	v_pk_mul_f32 v[30:31], v[30:31], v[20:21] op_sel_hi:[1,0]
	v_pk_mul_f32 v[24:25], v[24:25], v[20:21] op_sel_hi:[1,0]
	v_pk_fma_f32 v[8:9], v[8:9], v[30:31], v[12:13]
	v_pk_fma_f32 v[10:11], v[10:11], v[24:25], v[14:15]
	v_lshl_add_u64 v[12:13], v[56:57], 0, s[2:3]
	global_store_dwordx4 v[12:13], v[8:11], off nt
	s_add_i32 s4, s4, s6
	s_cmpk_gt_i32 s4, 0x3fff
	v_sub_f32_e32 v9, v26, v28
	v_sub_f32_e32 v8, v22, v28
	v_sub_f32_e32 v11, v18, v28
	v_sub_f32_e32 v10, v16, v28
	v_pk_mul_f32 v[10:11], v[10:11], v[20:21] op_sel_hi:[1,0]
	v_pk_mul_f32 v[8:9], v[8:9], v[20:21] op_sel_hi:[1,0]
	v_pk_fma_f32 v[0:1], v[0:1], v[10:11], v[4:5]
	v_pk_fma_f32 v[2:3], v[2:3], v[8:9], v[6:7]
	global_store_dwordx4 v[12:13], v[0:3], off offset:16 nt
	s_barrier
	s_cbranch_scc1 .LBB0_1377

; __device__ __forceinline__ u32x4 pack8f(f32x4 lo, f32x4 hi) { u32x4 w; w.x = cvtpk(lo[0], lo[1]); w.y = cvtpk(lo[2], lo[3]); w.z = cvtpk(hi[0], hi[1]); w.w = cvtpk(hi[2], hi[3]); return w; }
; __device__ __forceinline__ size_t ytile(int row, int col) { return ((((size_t)(row >> 8) * 16) + (col >> 8)) * 256 + (row & 255)) * 256 + (col & 255); }
; template <bool LN1>
; __device__ __forceinline__ void ln_phase(Frame& F, const bf16_t* Yin, const float* ga, const float* be, const float* modf, float* stats, bf16_t* ob16, float* of32) {
;     ...
;             if (bt < 7) {
; #pragma unroll
;                 for (int k = 0; k < 8; ++k) nx[k] = *(const u32x4*)(Yin + ytile(r0 + 8 + k, c0));
;             }
;             __syncthreads();
; #pragma unroll
;             for (int k = 0; k < 8; ++k) {
;                 float s = 0.f, q = 0.f;
; #pragma unroll
;                 for (int ww = 0; ww < 8; ++ww) { const f32x2 p = rd[k * 8 + ww]; s += p[0]; q += p[1]; }
;                 const float mean = s * (1.0f / D), var = fmaxf(q * (1.0f / D) - mean * mean, 0.f), rstd = 1.0f / sqrtf(var + 1e-5f);
;                 const size_t ro = (size_t)(r0 + k) * D + c0;
;                 if (LN1) { if (w == 0 && lane == 0) *(f32x2*)(stats + (size_t)(r0 + k) * 2) = (f32x2){mean, rstd};
;                     const int row = r0 + k; const size_t bo = ((((size_t)(row >> 8) * (D / 64)) + (c0 >> 6)) * 256 + (row & 255)) * 64 + (c0 & 63);
;                     *(u32x4*)(ob16 + bo) = pg8::pack8f((v[k][0] - mean) * rstd * ca[0] + cb[0], (v[k][1] - mean) * rstd * ca[1] + cb[1]); }
;                 else { *(f32x4*)(of32 + ro) = (v[k][0] - mean) * rstd * ca[0] + cb[0]; *(f32x4*)(of32 + ro + 4) = (v[k][1] - mean) * rstd * ca[1] + cb[1]; }
.LBB0_1344:
	s_or_b64 exec, exec, s[2:3]
	s_add_i32 s16, s4, s15
	s_add_i32 s18, s16, 8
	s_ashr_i32 s2, s18, 8
	s_ashr_i32 s3, s2, 31
	s_lshl_b64 s[2:3], s[2:3], 12
	v_lshl_add_u64 v[16:17], s[2:3], 0, v[48:49]
	s_and_b32 s2, s18, 0xf8
	s_waitcnt lgkmcnt(1)
	v_or_b32_e32 v18, s2, v16
	s_waitcnt lgkmcnt(0)
	v_mov_b32_e32 v19, v17
	v_lshlrev_b64 v[18:19], 9, v[18:19]
	v_or3_b32 v20, s2, 1, v16
	v_mov_b32_e32 v21, v17
	v_lshl_add_u64 v[18:19], v[54:55], 0, v[18:19]
	v_lshlrev_b64 v[20:21], 9, v[20:21]
	v_lshl_add_u64 v[20:21], v[54:55], 0, v[20:21]
	global_load_dwordx4 v[44:47], v[18:19], off
	global_load_dwordx4 v[40:43], v[20:21], off
	v_or3_b32 v18, s2, 2, v16
	v_mov_b32_e32 v19, v17
	v_lshlrev_b64 v[18:19], 9, v[18:19]
	v_or3_b32 v20, s2, 3, v16
	v_mov_b32_e32 v21, v17
	v_lshl_add_u64 v[18:19], v[54:55], 0, v[18:19]
	v_lshlrev_b64 v[20:21], 9, v[20:21]
	v_lshl_add_u64 v[20:21], v[54:55], 0, v[20:21]
	global_load_dwordx4 v[36:39], v[18:19], off
	global_load_dwordx4 v[32:35], v[20:21], off
	v_or3_b32 v18, s2, 4, v16
	v_mov_b32_e32 v19, v17
	v_lshlrev_b64 v[18:19], 9, v[18:19]
	v_or3_b32 v20, s2, 5, v16
	v_mov_b32_e32 v21, v17
	v_lshl_add_u64 v[18:19], v[54:55], 0, v[18:19]
	v_lshlrev_b64 v[20:21], 9, v[20:21]
	v_lshl_add_u64 v[20:21], v[54:55], 0, v[20:21]
	global_load_dwordx4 v[28:31], v[18:19], off
	global_load_dwordx4 v[24:27], v[20:21], off
	v_or3_b32 v18, s2, 6, v16
	v_mov_b32_e32 v19, v17
	v_or3_b32 v16, s2, 7, v16
	v_lshlrev_b64 v[18:19], 9, v[18:19]
	v_lshlrev_b64 v[16:17], 9, v[16:17]
	v_lshl_add_u64 v[18:19], v[54:55], 0, v[18:19]
	v_lshl_add_u64 v[16:17], v[54:55], 0, v[16:17]
	v_mov_b32_e32 v63, s17
	global_load_dwordx4 v[20:23], v[18:19], off
	s_nop 0
	global_load_dwordx4 v[16:19], v[16:17], off
	s_barrier
	ds_read_b128 v[198:201], v63
	ds_read_b128 v[202:205], v63 offset:16
	ds_read_b128 v[206:209], v63 offset:32
	ds_read_b128 v[210:213], v63 offset:48
	s_add_i32 s15, s15, 8
	s_waitcnt lgkmcnt(3)
	v_pk_add_f32 v[198:199], v[198:199], 0 op_sel_hi:[1,0]
	s_add_i32 s7, s7, 64
	v_pk_add_f32 v[198:199], v[198:199], v[200:201]
	s_waitcnt lgkmcnt(2)
	v_pk_add_f32 v[198:199], v[198:199], v[202:203]
	s_nop 0
	v_pk_add_f32 v[198:199], v[198:199], v[204:205]
	s_waitcnt lgkmcnt(1)
	v_pk_add_f32 v[198:199], v[198:199], v[206:207]
	s_nop 0
	v_pk_add_f32 v[198:199], v[198:199], v[208:209]
	s_waitcnt lgkmcnt(0)
	v_pk_add_f32 v[198:199], v[198:199], v[210:211]
	s_nop 0
	v_pk_add_f32 v[198:199], v[198:199], v[212:213]
	s_nop 0
	v_pk_mul_f32 v[202:203], v[198:199], s[10:11] op_sel_hi:[1,0]
	s_nop 0
	v_fma_f32 v65, -v202, v202, v203
	v_max_f32_e32 v65, 0, v65
	v_add_f32_e32 v65, 0x3727c5ac, v65
	v_mul_f32_e32 v67, 0x4f800000, v65
	v_cmp_gt_f32_e32 vcc, s5, v65
	v_sub_f32_e32 v187, v188, v202
	v_sub_f32_e32 v186, v186, v202
	v_cndmask_b32_e32 v65, v65, v67, vcc
	v_sqrt_f32_e32 v67, v65
	v_sub_f32_e32 v183, v184, v202
	v_sub_f32_e32 v182, v182, v202
	v_sub_f32_e32 v207, v180, v202
	v_add_u32_e32 v69, -1, v67
	v_fma_f32 v71, -v69, v67, v65
	v_cmp_ge_f32_e64 s[2:3], 0, v71
	v_add_u32_e32 v71, 1, v67
	v_sub_f32_e32 v206, v178, v202
	v_cndmask_b32_e64 v69, v67, v69, s[2:3]
	v_fma_f32 v67, -v71, v67, v65
	v_cmp_lt_f32_e64 s[2:3], 0, v67
	ds_read_b128 v[178:181], v63 offset:64
	v_sub_f32_e32 v149, v168, v202
	v_cndmask_b32_e64 v67, v69, v71, s[2:3]
	v_mul_f32_e32 v69, 0x37800000, v67
	v_cndmask_b32_e32 v67, v67, v69, vcc
	v_cmp_class_f32_e32 vcc, v65, v196
	s_waitcnt lgkmcnt(0)
	v_pk_add_f32 v[168:169], v[178:179], 0 op_sel_hi:[1,0]
	v_sub_f32_e32 v148, v148, v202
	v_cndmask_b32_e32 v65, v67, v65, vcc
	v_div_scale_f32 v67, s[2:3], v65, v65, 1.0
	v_rcp_f32_e32 v69, v67
	v_pk_add_f32 v[168:169], v[168:169], v[180:181]
	v_fma_f32 v71, -v67, v69, 1.0
	v_fmac_f32_e32 v69, v71, v69
	v_div_scale_f32 v71, vcc, 1.0, v65, 1.0
	v_mul_f32_e32 v73, v71, v69
	v_fma_f32 v75, -v67, v73, v71
	v_fmac_f32_e32 v73, v75, v69
	v_fma_f32 v67, -v67, v73, v71
	v_div_fmas_f32 v67, v67, v69, v73
	v_div_fixup_f32 v204, v67, v65, 1.0
	v_pk_mul_f32 v[182:183], v[182:183], v[204:205] op_sel_hi:[1,0]
	v_pk_mul_f32 v[184:185], v[186:187], v[204:205] op_sel_hi:[1,0]
	v_pk_fma_f32 v[182:183], v[8:9], v[182:183], v[12:13]
	v_pk_fma_f32 v[184:185], v[10:11], v[184:185], v[14:15]
	global_store_dwordx4 v[60:61], v[182:185], off offset:-16 nt
	ds_read_b128 v[182:185], v63 offset:80
	ds_read_b128 v[186:189], v63 offset:96
	ds_read_b128 v[198:201], v63 offset:112
	v_pk_mul_f32 v[148:149], v[148:149], v[204:205] op_sel_hi:[1,0]
	s_waitcnt lgkmcnt(2)
	v_pk_add_f32 v[168:169], v[168:169], v[182:183]
	s_nop 0
	v_pk_add_f32 v[168:169], v[168:169], v[184:185]
	v_pk_fma_f32 v[178:179], v[0:1], v[148:149], v[4:5]
	s_waitcnt lgkmcnt(1)
	v_pk_add_f32 v[168:169], v[168:169], v[186:187]
	s_nop 0
	v_pk_add_f32 v[168:169], v[168:169], v[188:189]
	s_waitcnt lgkmcnt(0)
; __device__ __forceinline__ u32x4 pack8f(f32x4 lo, f32x4 hi) { u32x4 w; w.x = cvtpk(lo[0], lo[1]); w.y = cvtpk(lo[2], lo[3]); w.z = cvtpk(hi[0], hi[1]); w.w = cvtpk(hi[2], hi[3]); return w; }
; template <bool LN1>
; __device__ __forceinline__ void ln_phase(Frame& F, const bf16_t* Yin, const float* ga, const float* be, const float* modf, float* stats, bf16_t* ob16, float* of32) {
;     ...
;             for (int k = 0; k < 8; ++k) {
;                 float s = 0.f, q = 0.f;
; #pragma unroll
;                 for (int ww = 0; ww < 8; ++ww) { const f32x2 p = rd[k * 8 + ww]; s += p[0]; q += p[1]; }
;                 const float mean = s * (1.0f / D), var = fmaxf(q * (1.0f / D) - mean * mean, 0.f), rstd = 1.0f / sqrtf(var + 1e-5f);
;                 const size_t ro = (size_t)(r0 + k) * D + c0;
;                 if (LN1) { if (w == 0 && lane == 0) *(f32x2*)(stats + (size_t)(r0 + k) * 2) = (f32x2){mean, rstd};
;                     const int row = r0 + k; const size_t bo = ((((size_t)(row >> 8) * (D / 64)) + (c0 >> 6)) * 256 + (row & 255)) * 64 + (c0 & 63);
;                     *(u32x4*)(ob16 + bo) = pg8::pack8f((v[k][0] - mean) * rstd * ca[0] + cb[0], (v[k][1] - mean) * rstd * ca[1] + cb[1]); }
;                 else { *(f32x4*)(of32 + ro) = (v[k][0] - mean) * rstd * ca[0] + cb[0]; *(f32x4*)(of32 + ro + 4) = (v[k][1] - mean) * rstd * ca[1] + cb[1]; }
;             }
;         }
	v_pk_add_f32 v[168:169], v[168:169], v[198:199]
	s_nop 0
	v_pk_add_f32 v[168:169], v[168:169], v[200:201]
	s_nop 0
	v_pk_mul_f32 v[182:183], v[168:169], s[10:11] op_sel_hi:[1,0]
	v_pk_mul_f32 v[168:169], v[206:207], v[204:205] op_sel_hi:[1,0]
	v_fma_f32 v65, -v182, v182, v183
	v_max_f32_e32 v65, 0, v65
	v_add_f32_e32 v65, 0x3727c5ac, v65
	v_mul_f32_e32 v67, 0x4f800000, v65
	v_cmp_gt_f32_e32 vcc, s5, v65
	v_pk_fma_f32 v[180:181], v[2:3], v[168:169], v[6:7]
	v_sub_f32_e32 v169, v176, v182
	v_cndmask_b32_e32 v65, v65, v67, vcc
	v_sqrt_f32_e32 v67, v65
	v_sub_f32_e32 v168, v174, v182
	v_sub_f32_e32 v171, v172, v182
	v_sub_f32_e32 v170, v170, v182
	v_add_u32_e32 v69, -1, v67
	v_fma_f32 v71, -v69, v67, v65
	v_cmp_ge_f32_e64 s[2:3], 0, v71
	v_add_u32_e32 v71, 1, v67
	v_sub_f32_e32 v185, v166, v182
	v_cndmask_b32_e64 v69, v67, v69, s[2:3]
	v_fma_f32 v67, -v71, v67, v65
	v_cmp_lt_f32_e64 s[2:3], 0, v67
	v_sub_f32_e32 v184, v164, v182
	ds_read_b128 v[164:167], v63 offset:128
	v_cndmask_b32_e64 v67, v69, v71, s[2:3]
	v_mul_f32_e32 v69, 0x37800000, v67
	v_cndmask_b32_e32 v67, v67, v69, vcc
	v_cmp_class_f32_e32 vcc, v65, v196
	global_store_dwordx4 v[60:61], v[178:181], off nt
	v_sub_f32_e32 v135, v154, v182
	v_cndmask_b32_e32 v65, v67, v65, vcc
	v_div_scale_f32 v67, s[2:3], v65, v65, 1.0
	v_rcp_f32_e32 v69, v67
	s_add_i32 s2, s16, 1
	s_ashr_i32 s3, s2, 31
	s_lshl_b64 s[2:3], s[2:3], 14
	v_fma_f32 v71, -v67, v69, 1.0
	v_fmac_f32_e32 v69, v71, v69
	v_div_scale_f32 v71, vcc, 1.0, v65, 1.0
	v_mul_f32_e32 v73, v71, v69
	v_fma_f32 v75, -v67, v73, v71
	v_fmac_f32_e32 v73, v75, v69
	v_fma_f32 v67, -v67, v73, v71
	v_div_fmas_f32 v67, v67, v69, v73
	v_div_fixup_f32 v148, v67, v65, 1.0
	v_pk_mul_f32 v[172:173], v[170:171], v[148:149] op_sel_hi:[1,0]
	v_pk_mul_f32 v[168:169], v[168:169], v[148:149] op_sel_hi:[1,0]
	v_lshl_add_u64 v[180:181], v[56:57], 0, s[2:3]
	v_pk_fma_f32 v[170:171], v[10:11], v[168:169], v[14:15]
	v_pk_fma_f32 v[168:169], v[8:9], v[172:173], v[12:13]
	global_store_dwordx4 v[180:181], v[168:171], off nt
	ds_read_b128 v[168:171], v63 offset:144
	ds_read_b128 v[172:175], v63 offset:160
	ds_read_b128 v[176:179], v63 offset:176
	s_waitcnt lgkmcnt(3)
	v_pk_add_f32 v[154:155], v[164:165], 0 op_sel_hi:[1,0]
	v_sub_f32_e32 v134, v134, v182
	v_pk_add_f32 v[154:155], v[154:155], v[166:167]
	v_pk_mul_f32 v[134:135], v[134:135], v[148:149] op_sel_hi:[1,0]
	s_waitcnt lgkmcnt(2)
	v_pk_add_f32 v[154:155], v[154:155], v[168:169]
	v_pk_mul_f32 v[148:149], v[184:185], v[148:149] op_sel_hi:[1,0]
	v_pk_add_f32 v[154:155], v[154:155], v[170:171]
	v_pk_fma_f32 v[166:167], v[2:3], v[148:149], v[6:7]
	s_waitcnt lgkmcnt(1)
	v_pk_add_f32 v[154:155], v[154:155], v[172:173]
	v_pk_fma_f32 v[164:165], v[0:1], v[134:135], v[4:5]
	v_pk_add_f32 v[154:155], v[154:155], v[174:175]
	global_store_dwordx4 v[180:181], v[164:167], off offset:16 nt
	s_waitcnt lgkmcnt(0)
	v_pk_add_f32 v[154:155], v[154:155], v[176:177]
	v_lshl_add_u64 v[60:61], v[60:61], 0, s[12:13]
	v_pk_add_f32 v[154:155], v[154:155], v[178:179]
	s_nop 0
	v_pk_mul_f32 v[168:169], v[154:155], s[10:11] op_sel_hi:[1,0]
	s_nop 0
	v_fma_f32 v65, -v168, v168, v169
	v_max_f32_e32 v65, 0, v65
	v_add_f32_e32 v65, 0x3727c5ac, v65
	v_mul_f32_e32 v67, 0x4f800000, v65
	v_cmp_gt_f32_e32 vcc, s5, v65
	v_sub_f32_e32 v149, v162, v168
	v_sub_f32_e32 v148, v160, v168
	v_cndmask_b32_e32 v65, v65, v67, vcc
	v_sqrt_f32_e32 v67, v65
	v_sub_f32_e32 v155, v158, v168
	v_sub_f32_e32 v154, v156, v168
	v_sub_f32_e32 v166, v150, v168
	v_add_u32_e32 v69, -1, v67
	v_fma_f32 v71, -v69, v67, v65
	v_cmp_ge_f32_e64 s[2:3], 0, v71
	v_add_u32_e32 v71, 1, v67
	v_sub_f32_e32 v167, v152, v168
	v_cndmask_b32_e64 v69, v67, v69, s[2:3]
	v_fma_f32 v67, -v71, v67, v65
	v_cmp_lt_f32_e64 s[2:3], 0, v67
	v_sub_f32_e32 v119, v138, v168
	v_sub_f32_e32 v118, v118, v168
	v_cndmask_b32_e64 v67, v69, v71, s[2:3]
	v_mul_f32_e32 v69, 0x37800000, v67
	v_cndmask_b32_e32 v67, v67, v69, vcc
	v_cmp_class_f32_e32 vcc, v65, v196
	s_nop 1
	v_cndmask_b32_e32 v65, v67, v65, vcc
	v_div_scale_f32 v67, s[2:3], v65, v65, 1.0
	v_rcp_f32_e32 v69, v67
	s_add_i32 s2, s16, 2
	s_ashr_i32 s3, s2, 31
	s_lshl_b64 s[2:3], s[2:3], 14
	v_fma_f32 v71, -v67, v69, 1.0
	v_fmac_f32_e32 v69, v71, v69
	v_div_scale_f32 v71, vcc, 1.0, v65, 1.0
	v_mul_f32_e32 v73, v71, v69
	v_fma_f32 v75, -v67, v73, v71
	v_fmac_f32_e32 v73, v75, v69
	v_fma_f32 v67, -v67, v73, v71
	v_div_fmas_f32 v67, v67, v69, v73
	v_div_fixup_f32 v134, v67, v65, 1.0
	v_pk_mul_f32 v[148:149], v[148:149], v[134:135] op_sel_hi:[1,0]
	v_pk_mul_f32 v[154:155], v[154:155], v[134:135] op_sel_hi:[1,0]
	v_pk_fma_f32 v[156:157], v[10:11], v[148:149], v[14:15]
	ds_read_b128 v[148:151], v63 offset:192
	v_pk_fma_f32 v[154:155], v[8:9], v[154:155], v[12:13]
	v_lshl_add_u64 v[164:165], v[56:57], 0, s[2:3]
	global_store_dwordx4 v[164:165], v[154:157], off nt
	ds_read_b128 v[152:155], v63 offset:208
	ds_read_b128 v[156:159], v63 offset:224
	ds_read_b128 v[160:163], v63 offset:240
	s_waitcnt lgkmcnt(3)
	v_pk_add_f32 v[138:139], v[148:149], 0 op_sel_hi:[1,0]
	v_pk_mul_f32 v[118:119], v[118:119], v[134:135] op_sel_hi:[1,0]
	v_pk_add_f32 v[138:139], v[138:139], v[150:151]
	v_pk_mul_f32 v[134:135], v[166:167], v[134:135] op_sel_hi:[1,0]
	s_waitcnt lgkmcnt(2)
	v_pk_add_f32 v[138:139], v[138:139], v[152:153]
	v_pk_fma_f32 v[150:151], v[2:3], v[134:135], v[6:7]
	v_pk_add_f32 v[138:139], v[138:139], v[154:155]
	v_pk_fma_f32 v[148:149], v[0:1], v[118:119], v[4:5]
	s_waitcnt lgkmcnt(1)
	v_pk_add_f32 v[138:139], v[138:139], v[156:157]
	global_store_dwordx4 v[164:165], v[148:151], off offset:16 nt
	v_pk_add_f32 v[138:139], v[138:139], v[158:159]
	s_waitcnt lgkmcnt(0)
; __device__ __forceinline__ u32x4 pack8f(f32x4 lo, f32x4 hi) { u32x4 w; w.x = cvtpk(lo[0], lo[1]); w.y = cvtpk(lo[2], lo[3]); w.z = cvtpk(hi[0], hi[1]); w.w = cvtpk(hi[2], hi[3]); return w; }
; template <bool LN1>
; __device__ __forceinline__ void ln_phase(Frame& F, const bf16_t* Yin, const float* ga, const float* be, const float* modf, float* stats, bf16_t* ob16, float* of32) {
;     ...
;             for (int k = 0; k < 8; ++k) {
;                 float s = 0.f, q = 0.f;
; #pragma unroll
;                 for (int ww = 0; ww < 8; ++ww) { const f32x2 p = rd[k * 8 + ww]; s += p[0]; q += p[1]; }
;                 const float mean = s * (1.0f / D), var = fmaxf(q * (1.0f / D) - mean * mean, 0.f), rstd = 1.0f / sqrtf(var + 1e-5f);
;                 const size_t ro = (size_t)(r0 + k) * D + c0;
;                 if (LN1) { if (w == 0 && lane == 0) *(f32x2*)(stats + (size_t)(r0 + k) * 2) = (f32x2){mean, rstd};
;                     const int row = r0 + k; const size_t bo = ((((size_t)(row >> 8) * (D / 64)) + (c0 >> 6)) * 256 + (row & 255)) * 64 + (c0 & 63);
;                     *(u32x4*)(ob16 + bo) = pg8::pack8f((v[k][0] - mean) * rstd * ca[0] + cb[0], (v[k][1] - mean) * rstd * ca[1] + cb[1]); }
;                 else { *(f32x4*)(of32 + ro) = (v[k][0] - mean) * rstd * ca[0] + cb[0]; *(f32x4*)(of32 + ro + 4) = (v[k][1] - mean) * rstd * ca[1] + cb[1]; }
;             }
;         }
	v_pk_add_f32 v[138:139], v[138:139], v[160:161]
	s_nop 0
	v_pk_add_f32 v[138:139], v[138:139], v[162:163]
	s_nop 0
	v_pk_mul_f32 v[152:153], v[138:139], s[10:11] op_sel_hi:[1,0]
	s_nop 0
	v_fma_f32 v65, -v152, v152, v153
	v_max_f32_e32 v65, 0, v65
	v_add_f32_e32 v65, 0x3727c5ac, v65
	v_mul_f32_e32 v67, 0x4f800000, v65
	v_cmp_gt_f32_e32 vcc, s5, v65
	v_sub_f32_e32 v135, v146, v152
	v_sub_f32_e32 v134, v144, v152
	v_cndmask_b32_e32 v65, v65, v67, vcc
	v_sqrt_f32_e32 v67, v65
	v_sub_f32_e32 v139, v142, v152
	v_sub_f32_e32 v138, v140, v152
	v_sub_f32_e32 v150, v132, v152
	v_add_u32_e32 v69, -1, v67
	v_fma_f32 v71, -v69, v67, v65
	v_cmp_ge_f32_e64 s[2:3], 0, v71
	v_add_u32_e32 v71, 1, v67
	v_sub_f32_e32 v151, v136, v152
	v_cndmask_b32_e64 v69, v67, v69, s[2:3]
	v_fma_f32 v67, -v71, v67, v65
	v_cmp_lt_f32_e64 s[2:3], 0, v67
	v_sub_f32_e32 v103, v122, v152
	v_sub_f32_e32 v102, v102, v152
	v_cndmask_b32_e64 v67, v69, v71, s[2:3]
	v_mul_f32_e32 v69, 0x37800000, v67
	v_cndmask_b32_e32 v67, v67, v69, vcc
	v_cmp_class_f32_e32 vcc, v65, v196
	s_nop 1
	v_cndmask_b32_e32 v65, v67, v65, vcc
	v_div_scale_f32 v67, s[2:3], v65, v65, 1.0
	v_rcp_f32_e32 v69, v67
	s_add_i32 s2, s16, 3
	s_ashr_i32 s3, s2, 31
	s_lshl_b64 s[2:3], s[2:3], 14
	v_fma_f32 v71, -v67, v69, 1.0
	v_fmac_f32_e32 v69, v71, v69
	v_div_scale_f32 v71, vcc, 1.0, v65, 1.0
	v_mul_f32_e32 v73, v71, v69
	v_fma_f32 v75, -v67, v73, v71
	v_fmac_f32_e32 v73, v75, v69
	v_fma_f32 v67, -v67, v73, v71
	v_div_fmas_f32 v67, v67, v69, v73
	v_div_fixup_f32 v118, v67, v65, 1.0
	v_pk_mul_f32 v[134:135], v[134:135], v[118:119] op_sel_hi:[1,0]
	v_pk_mul_f32 v[138:139], v[138:139], v[118:119] op_sel_hi:[1,0]
	v_pk_fma_f32 v[140:141], v[10:11], v[134:135], v[14:15]
	ds_read_b128 v[132:135], v63 offset:256
	v_pk_fma_f32 v[138:139], v[8:9], v[138:139], v[12:13]
	v_lshl_add_u64 v[148:149], v[56:57], 0, s[2:3]
	global_store_dwordx4 v[148:149], v[138:141], off nt
	ds_read_b128 v[136:139], v63 offset:272
	ds_read_b128 v[140:143], v63 offset:288
	ds_read_b128 v[144:147], v63 offset:304
	s_waitcnt lgkmcnt(3)
	v_pk_add_f32 v[122:123], v[132:133], 0 op_sel_hi:[1,0]
	v_pk_mul_f32 v[102:103], v[102:103], v[118:119] op_sel_hi:[1,0]
	v_pk_add_f32 v[122:123], v[122:123], v[134:135]
	v_pk_mul_f32 v[118:119], v[150:151], v[118:119] op_sel_hi:[1,0]
	s_waitcnt lgkmcnt(2)
	v_pk_add_f32 v[122:123], v[122:123], v[136:137]
	v_pk_fma_f32 v[134:135], v[2:3], v[118:119], v[6:7]
	v_pk_add_f32 v[122:123], v[122:123], v[138:139]
	v_pk_fma_f32 v[132:133], v[0:1], v[102:103], v[4:5]
	s_waitcnt lgkmcnt(1)
	v_pk_add_f32 v[122:123], v[122:123], v[140:141]
	global_store_dwordx4 v[148:149], v[132:135], off offset:16 nt
	v_pk_add_f32 v[122:123], v[122:123], v[142:143]
	s_waitcnt lgkmcnt(0)
	v_pk_add_f32 v[122:123], v[122:123], v[144:145]
	s_nop 0
	v_pk_add_f32 v[122:123], v[122:123], v[146:147]
	s_nop 0
	v_pk_mul_f32 v[136:137], v[122:123], s[10:11] op_sel_hi:[1,0]
	s_nop 0
	v_fma_f32 v65, -v136, v136, v137
	v_max_f32_e32 v65, 0, v65
	v_add_f32_e32 v65, 0x3727c5ac, v65
	v_mul_f32_e32 v67, 0x4f800000, v65
	v_cmp_gt_f32_e32 vcc, s5, v65
	v_sub_f32_e32 v119, v130, v136
	v_sub_f32_e32 v118, v128, v136
	v_cndmask_b32_e32 v65, v65, v67, vcc
	v_sqrt_f32_e32 v67, v65
	v_sub_f32_e32 v123, v126, v136
	v_sub_f32_e32 v122, v124, v136
	v_sub_f32_e32 v134, v116, v136
	v_add_u32_e32 v69, -1, v67
	v_fma_f32 v71, -v69, v67, v65
	v_cmp_ge_f32_e64 s[2:3], 0, v71
	v_add_u32_e32 v71, 1, v67
	v_sub_f32_e32 v135, v120, v136
	v_cndmask_b32_e64 v69, v67, v69, s[2:3]
	v_fma_f32 v67, -v71, v67, v65
	v_cmp_lt_f32_e64 s[2:3], 0, v67
	v_sub_f32_e32 v87, v106, v136
	v_sub_f32_e32 v86, v86, v136
	v_cndmask_b32_e64 v67, v69, v71, s[2:3]
	v_mul_f32_e32 v69, 0x37800000, v67
	v_cndmask_b32_e32 v67, v67, v69, vcc
	v_cmp_class_f32_e32 vcc, v65, v196
	s_nop 1
	v_cndmask_b32_e32 v65, v67, v65, vcc
	v_div_scale_f32 v67, s[2:3], v65, v65, 1.0
	v_rcp_f32_e32 v69, v67
	s_add_i32 s2, s16, 4
	s_ashr_i32 s3, s2, 31
	s_lshl_b64 s[2:3], s[2:3], 14
	v_fma_f32 v71, -v67, v69, 1.0
	v_fmac_f32_e32 v69, v71, v69
	v_div_scale_f32 v71, vcc, 1.0, v65, 1.0
	v_mul_f32_e32 v73, v71, v69
	v_fma_f32 v75, -v67, v73, v71
	v_fmac_f32_e32 v73, v75, v69
	v_fma_f32 v67, -v67, v73, v71
	v_div_fmas_f32 v67, v67, v69, v73
	v_div_fixup_f32 v102, v67, v65, 1.0
	v_pk_mul_f32 v[118:119], v[118:119], v[102:103] op_sel_hi:[1,0]
	v_pk_mul_f32 v[122:123], v[122:123], v[102:103] op_sel_hi:[1,0]
	v_pk_fma_f32 v[124:125], v[10:11], v[118:119], v[14:15]
	ds_read_b128 v[116:119], v63 offset:320
	v_pk_fma_f32 v[122:123], v[8:9], v[122:123], v[12:13]
	v_lshl_add_u64 v[132:133], v[56:57], 0, s[2:3]
	global_store_dwordx4 v[132:133], v[122:125], off nt
	ds_read_b128 v[120:123], v63 offset:336
	ds_read_b128 v[124:127], v63 offset:352
	ds_read_b128 v[128:131], v63 offset:368
	s_waitcnt lgkmcnt(3)
	v_pk_add_f32 v[106:107], v[116:117], 0 op_sel_hi:[1,0]
	v_pk_mul_f32 v[86:87], v[86:87], v[102:103] op_sel_hi:[1,0]
	v_pk_add_f32 v[106:107], v[106:107], v[118:119]
	v_pk_mul_f32 v[102:103], v[134:135], v[102:103] op_sel_hi:[1,0]
	s_waitcnt lgkmcnt(2)
	v_pk_add_f32 v[106:107], v[106:107], v[120:121]
	v_pk_fma_f32 v[118:119], v[2:3], v[102:103], v[6:7]
	v_pk_add_f32 v[106:107], v[106:107], v[122:123]
	v_pk_fma_f32 v[116:117], v[0:1], v[86:87], v[4:5]
	s_waitcnt lgkmcnt(1)
	v_pk_add_f32 v[106:107], v[106:107], v[124:125]
	global_store_dwordx4 v[132:133], v[116:119], off offset:16 nt
	v_pk_add_f32 v[106:107], v[106:107], v[126:127]
	s_waitcnt lgkmcnt(0)
; __device__ __forceinline__ u32x4 pack8f(f32x4 lo, f32x4 hi) { u32x4 w; w.x = cvtpk(lo[0], lo[1]); w.y = cvtpk(lo[2], lo[3]); w.z = cvtpk(hi[0], hi[1]); w.w = cvtpk(hi[2], hi[3]); return w; }
; template <bool LN1>
; __device__ __forceinline__ void ln_phase(Frame& F, const bf16_t* Yin, const float* ga, const float* be, const float* modf, float* stats, bf16_t* ob16, float* of32) {
;     ...
;             for (int k = 0; k < 8; ++k) {
;                 float s = 0.f, q = 0.f;
; #pragma unroll
;                 for (int ww = 0; ww < 8; ++ww) { const f32x2 p = rd[k * 8 + ww]; s += p[0]; q += p[1]; }
;                 const float mean = s * (1.0f / D), var = fmaxf(q * (1.0f / D) - mean * mean, 0.f), rstd = 1.0f / sqrtf(var + 1e-5f);
;                 const size_t ro = (size_t)(r0 + k) * D + c0;
;                 if (LN1) { if (w == 0 && lane == 0) *(f32x2*)(stats + (size_t)(r0 + k) * 2) = (f32x2){mean, rstd};
;                     const int row = r0 + k; const size_t bo = ((((size_t)(row >> 8) * (D / 64)) + (c0 >> 6)) * 256 + (row & 255)) * 64 + (c0 & 63);
;                     *(u32x4*)(ob16 + bo) = pg8::pack8f((v[k][0] - mean) * rstd * ca[0] + cb[0], (v[k][1] - mean) * rstd * ca[1] + cb[1]); }
;                 else { *(f32x4*)(of32 + ro) = (v[k][0] - mean) * rstd * ca[0] + cb[0]; *(f32x4*)(of32 + ro + 4) = (v[k][1] - mean) * rstd * ca[1] + cb[1]; }
;             }
;         }
	v_pk_add_f32 v[106:107], v[106:107], v[128:129]
	s_nop 0
	v_pk_add_f32 v[106:107], v[106:107], v[130:131]
	s_nop 0
	v_pk_mul_f32 v[120:121], v[106:107], s[10:11] op_sel_hi:[1,0]
	s_nop 0
	v_fma_f32 v65, -v120, v120, v121
	v_max_f32_e32 v65, 0, v65
	v_add_f32_e32 v65, 0x3727c5ac, v65
	v_mul_f32_e32 v67, 0x4f800000, v65
	v_cmp_gt_f32_e32 vcc, s5, v65
	v_sub_f32_e32 v103, v114, v120
	v_sub_f32_e32 v102, v112, v120
	v_cndmask_b32_e32 v65, v65, v67, vcc
	v_sqrt_f32_e32 v67, v65
	v_sub_f32_e32 v107, v110, v120
	v_sub_f32_e32 v106, v108, v120
	v_sub_f32_e32 v118, v100, v120
	v_add_u32_e32 v69, -1, v67
	v_fma_f32 v71, -v69, v67, v65
	v_cmp_ge_f32_e64 s[2:3], 0, v71
	v_add_u32_e32 v71, 1, v67
	v_sub_f32_e32 v119, v104, v120
	v_cndmask_b32_e64 v69, v67, v69, s[2:3]
	v_fma_f32 v67, -v71, v67, v65
	v_cmp_lt_f32_e64 s[2:3], 0, v67
	v_sub_f32_e32 v70, v70, v120
	s_nop 0
	v_cndmask_b32_e64 v67, v69, v71, s[2:3]
	v_mul_f32_e32 v69, 0x37800000, v67
	v_cndmask_b32_e32 v67, v67, v69, vcc
	v_cmp_class_f32_e32 vcc, v65, v196
	s_nop 1
	v_cndmask_b32_e32 v65, v67, v65, vcc
	v_div_scale_f32 v67, s[2:3], v65, v65, 1.0
	v_rcp_f32_e32 v69, v67
	s_add_i32 s2, s16, 5
	s_ashr_i32 s3, s2, 31
	s_lshl_b64 s[2:3], s[2:3], 14
	v_fma_f32 v71, -v67, v69, 1.0
	v_fmac_f32_e32 v69, v71, v69
	v_div_scale_f32 v71, vcc, 1.0, v65, 1.0
	v_mul_f32_e32 v73, v71, v69
	v_fma_f32 v75, -v67, v73, v71
	v_fmac_f32_e32 v73, v75, v69
	v_fma_f32 v67, -v67, v73, v71
	v_div_fmas_f32 v67, v67, v69, v73
	v_div_fixup_f32 v86, v67, v65, 1.0
	v_pk_mul_f32 v[102:103], v[102:103], v[86:87] op_sel_hi:[1,0]
	v_pk_mul_f32 v[106:107], v[106:107], v[86:87] op_sel_hi:[1,0]
	v_pk_fma_f32 v[108:109], v[10:11], v[102:103], v[14:15]
	ds_read_b128 v[100:103], v63 offset:384
	v_pk_fma_f32 v[106:107], v[8:9], v[106:107], v[12:13]
	v_lshl_add_u64 v[116:117], v[56:57], 0, s[2:3]
	global_store_dwordx4 v[116:117], v[106:109], off nt
	ds_read_b128 v[104:107], v63 offset:400
	ds_read_b128 v[108:111], v63 offset:416
	ds_read_b128 v[112:115], v63 offset:432
	v_sub_f32_e32 v71, v90, v120
	s_waitcnt lgkmcnt(3)
	v_pk_add_f32 v[90:91], v[100:101], 0 op_sel_hi:[1,0]
	v_pk_mul_f32 v[70:71], v[70:71], v[86:87] op_sel_hi:[1,0]
	v_pk_add_f32 v[90:91], v[90:91], v[102:103]
	v_pk_fma_f32 v[100:101], v[0:1], v[70:71], v[4:5]
	s_waitcnt lgkmcnt(2)
	v_pk_add_f32 v[90:91], v[90:91], v[104:105]
	v_pk_mul_f32 v[86:87], v[118:119], v[86:87] op_sel_hi:[1,0]
	v_pk_add_f32 v[90:91], v[90:91], v[106:107]
	v_pk_fma_f32 v[102:103], v[2:3], v[86:87], v[6:7]
	s_waitcnt lgkmcnt(1)
	v_pk_add_f32 v[90:91], v[90:91], v[108:109]
	global_store_dwordx4 v[116:117], v[100:103], off offset:16 nt
	v_pk_add_f32 v[90:91], v[90:91], v[110:111]
	s_waitcnt lgkmcnt(0)
	v_pk_add_f32 v[90:91], v[90:91], v[112:113]
	s_nop 0
	v_pk_add_f32 v[90:91], v[90:91], v[114:115]
	s_nop 0
	v_pk_mul_f32 v[104:105], v[90:91], s[10:11] op_sel_hi:[1,0]
	s_nop 0
	v_fma_f32 v65, -v104, v104, v105
	v_max_f32_e32 v65, 0, v65
	v_add_f32_e32 v65, 0x3727c5ac, v65
	v_mul_f32_e32 v67, 0x4f800000, v65
	v_cmp_gt_f32_e32 vcc, s5, v65
	v_sub_f32_e32 v87, v98, v104
	v_sub_f32_e32 v86, v96, v104
	v_cndmask_b32_e32 v65, v65, v67, vcc
	v_sqrt_f32_e32 v67, v65
	v_sub_f32_e32 v91, v94, v104
	v_sub_f32_e32 v90, v92, v104
	v_sub_f32_e32 v102, v84, v104
	v_add_u32_e32 v69, -1, v67
	v_fma_f32 v73, -v69, v67, v65
	v_cmp_ge_f32_e64 s[2:3], 0, v73
	v_add_u32_e32 v73, 1, v67
	v_sub_f32_e32 v103, v88, v104
	v_cndmask_b32_e64 v69, v67, v69, s[2:3]
	v_fma_f32 v67, -v73, v67, v65
	v_cmp_lt_f32_e64 s[2:3], 0, v67
	v_sub_f32_e32 v75, v74, v104
	v_sub_f32_e32 v74, v62, v104
	v_cndmask_b32_e64 v67, v69, v73, s[2:3]
	v_mul_f32_e32 v69, 0x37800000, v67
	v_cndmask_b32_e32 v67, v67, v69, vcc
	v_cmp_class_f32_e32 vcc, v65, v196
	s_nop 1
	v_cndmask_b32_e32 v65, v67, v65, vcc
	v_div_scale_f32 v67, s[2:3], v65, v65, 1.0
	v_rcp_f32_e32 v69, v67
	s_add_i32 s2, s16, 6
	s_ashr_i32 s3, s2, 31
	s_lshl_b64 s[2:3], s[2:3], 14
	v_fma_f32 v70, -v67, v69, 1.0
	v_fmac_f32_e32 v69, v70, v69
	v_div_scale_f32 v70, vcc, 1.0, v65, 1.0
	v_mul_f32_e32 v71, v70, v69
	v_fma_f32 v73, -v67, v71, v70
	v_fmac_f32_e32 v71, v73, v69
	v_fma_f32 v67, -v67, v71, v70
	v_div_fmas_f32 v67, v67, v69, v71
	v_div_fixup_f32 v70, v67, v65, 1.0
	v_pk_mul_f32 v[86:87], v[86:87], v[70:71] op_sel_hi:[1,0]
	v_pk_mul_f32 v[90:91], v[90:91], v[70:71] op_sel_hi:[1,0]
	v_pk_fma_f32 v[92:93], v[10:11], v[86:87], v[14:15]
	ds_read_b128 v[84:87], v63 offset:448
	v_pk_fma_f32 v[90:91], v[8:9], v[90:91], v[12:13]
	v_lshl_add_u64 v[100:101], v[56:57], 0, s[2:3]
	global_store_dwordx4 v[100:101], v[90:93], off nt
	ds_read_b128 v[88:91], v63 offset:464
	ds_read_b128 v[92:95], v63 offset:480
	ds_read_b128 v[96:99], v63 offset:496
	s_waitcnt lgkmcnt(3)
; __device__ __forceinline__ u32x4 pack8f(f32x4 lo, f32x4 hi) { u32x4 w; w.x = cvtpk(lo[0], lo[1]); w.y = cvtpk(lo[2], lo[3]); w.z = cvtpk(hi[0], hi[1]); w.w = cvtpk(hi[2], hi[3]); return w; }
; template <bool LN1>
; __device__ __forceinline__ void ln_phase(Frame& F, const bf16_t* Yin, const float* ga, const float* be, const float* modf, float* stats, bf16_t* ob16, float* of32) {
;     ...
;             for (int k = 0; k < 8; ++k) {
;                 float s = 0.f, q = 0.f;
; #pragma unroll
;                 for (int ww = 0; ww < 8; ++ww) { const f32x2 p = rd[k * 8 + ww]; s += p[0]; q += p[1]; }
;                 const float mean = s * (1.0f / D), var = fmaxf(q * (1.0f / D) - mean * mean, 0.f), rstd = 1.0f / sqrtf(var + 1e-5f);
;                 const size_t ro = (size_t)(r0 + k) * D + c0;
;                 if (LN1) { if (w == 0 && lane == 0) *(f32x2*)(stats + (size_t)(r0 + k) * 2) = (f32x2){mean, rstd};
;                     const int row = r0 + k; const size_t bo = ((((size_t)(row >> 8) * (D / 64)) + (c0 >> 6)) * 256 + (row & 255)) * 64 + (c0 & 63);
;                     *(u32x4*)(ob16 + bo) = pg8::pack8f((v[k][0] - mean) * rstd * ca[0] + cb[0], (v[k][1] - mean) * rstd * ca[1] + cb[1]); }
;                 else { *(f32x4*)(of32 + ro) = (v[k][0] - mean) * rstd * ca[0] + cb[0]; *(f32x4*)(of32 + ro + 4) = (v[k][1] - mean) * rstd * ca[1] + cb[1]; }
;             }
;         }
	v_pk_add_f32 v[84:85], v[84:85], 0 op_sel_hi:[1,0]
	s_nop 0
	v_pk_add_f32 v[84:85], v[84:85], v[86:87]
	s_waitcnt lgkmcnt(2)
	v_pk_add_f32 v[84:85], v[84:85], v[88:89]
	s_nop 0
	v_pk_add_f32 v[84:85], v[84:85], v[90:91]
	s_waitcnt lgkmcnt(1)
	v_pk_add_f32 v[84:85], v[84:85], v[92:93]
	s_nop 0
	v_pk_add_f32 v[84:85], v[84:85], v[94:95]
	s_waitcnt lgkmcnt(0)
	v_pk_add_f32 v[84:85], v[84:85], v[96:97]
	s_nop 0
	v_pk_add_f32 v[84:85], v[84:85], v[98:99]
	s_nop 0
	v_pk_mul_f32 v[88:89], v[84:85], s[10:11] op_sel_hi:[1,0]
	s_nop 0
	v_fma_f32 v63, -v88, v88, v89
	v_max_f32_e32 v63, 0, v63
	v_add_f32_e32 v63, 0x3727c5ac, v63
	v_mul_f32_e32 v65, 0x4f800000, v63
	v_cmp_gt_f32_e32 vcc, s5, v63
	v_sub_f32_e32 v68, v68, v88
	v_sub_f32_e32 v64, v64, v88
	v_cndmask_b32_e32 v65, v63, v65, vcc
	v_sqrt_f32_e32 v67, v65
	v_pk_mul_f32 v[62:63], v[74:75], v[70:71] op_sel_hi:[1,0]
	v_pk_mul_f32 v[70:71], v[102:103], v[70:71] op_sel_hi:[1,0]
	v_pk_fma_f32 v[84:85], v[0:1], v[62:63], v[4:5]
	v_add_u32_e32 v69, -1, v67
	v_fma_f32 v73, -v69, v67, v65
	v_cmp_ge_f32_e64 s[2:3], 0, v73
	v_add_u32_e32 v73, 1, v67
	v_pk_fma_f32 v[86:87], v[2:3], v[70:71], v[6:7]
	v_cndmask_b32_e64 v69, v67, v69, s[2:3]
	v_fma_f32 v67, -v73, v67, v65
	v_cmp_lt_f32_e64 s[2:3], 0, v67
	v_sub_f32_e32 v71, v82, v88
	v_sub_f32_e32 v75, v78, v88
	v_cndmask_b32_e64 v67, v69, v73, s[2:3]
	v_mul_f32_e32 v69, 0x37800000, v67
	v_cndmask_b32_e32 v67, v67, v69, vcc
	v_cmp_class_f32_e32 vcc, v65, v196
	v_sub_f32_e32 v74, v76, v88
	global_store_dwordx4 v[100:101], v[84:87], off offset:16 nt
	v_cndmask_b32_e32 v65, v67, v65, vcc
	v_div_scale_f32 v67, s[2:3], v65, v65, 1.0
	v_rcp_f32_e32 v69, v67
	s_add_i32 s2, s16, 7
	s_ashr_i32 s3, s2, 31
	s_lshl_b64 s[2:3], s[2:3], 14
	v_fma_f32 v62, -v67, v69, 1.0
	v_fmac_f32_e32 v69, v62, v69
	v_div_scale_f32 v62, vcc, 1.0, v65, 1.0
	v_mul_f32_e32 v63, v62, v69
	v_fma_f32 v70, -v67, v63, v62
	v_fmac_f32_e32 v63, v70, v69
	v_fma_f32 v62, -v67, v63, v62
	v_div_fmas_f32 v62, v62, v69, v63
	v_div_fixup_f32 v62, v62, v65, 1.0
	v_sub_f32_e32 v70, v80, v88
	v_sub_f32_e32 v69, v72, v88
	v_sub_f32_e32 v65, v66, v88
	v_pk_mul_f32 v[74:75], v[74:75], v[62:63] op_sel_hi:[1,0]
	v_pk_mul_f32 v[70:71], v[70:71], v[62:63] op_sel_hi:[1,0]
	v_pk_mul_f32 v[66:67], v[64:65], v[62:63] op_sel_hi:[1,0]
	v_pk_mul_f32 v[62:63], v[68:69], v[62:63] op_sel_hi:[1,0]
	v_pk_fma_f32 v[76:77], v[10:11], v[70:71], v[14:15]
	v_pk_fma_f32 v[74:75], v[8:9], v[74:75], v[12:13]
	v_lshl_add_u64 v[70:71], v[56:57], 0, s[2:3]
	v_pk_fma_f32 v[64:65], v[2:3], v[62:63], v[6:7]
	v_pk_fma_f32 v[62:63], v[0:1], v[66:67], v[4:5]
	s_cmp_eq_u32 s15, 56
	global_store_dwordx4 v[70:71], v[74:77], off nt
	global_store_dwordx4 v[70:71], v[62:65], off offset:16 nt
	s_cbranch_scc1 .LBB0_1361
